# adds: gates stored 16B per lane (both column halves adjacent) and merge gate loads remapped; skip redundant first-iteration DMA waits after an epilogue
# speedup vs baseline: 1.0199x; 1.0036x over previous
; __device__ __forceinline__ int fresh_tid() { int t = threadIdx.x; asm volatile("" : "+v"(t)); return t; }
; #define PG8_STAGE(bufoff, gbase, voff) do { _Pragma("unroll") for (int _i = 0; _i < 2; ++_i) \
;         __builtin_amdgcn_global_load_lds((const unsigned*)((const char*)(gbase) + (voff)[_i]), (LAS unsigned*)(lds + (bufoff) + ldsw + _i * 8192), 16, 0, 0); } while (0)
; #define PG8_WAIT_V(n) asm volatile("s_waitcnt vmcnt(" #n ")" ::: "memory")
; template <class Epi, class Sched, int NSEG, int KK, int LDA, int LDB>
; __device__ __forceinline__ void gemm_phase(LAS unsigned char* lds, const Gemm g, const Sched& S, const Epi& E) {
;     const int tid = fresh_tid(), wid = __builtin_amdgcn_readfirstlane(tid >> 6), lane = tid & 63, wr = wid >> 2, wc = wid & 3, fr = lane & 15, fq = lane >> 4;
;     constexpr int nt = KK / BK;
;     unsigned voffA[2], voffB[2];
; #pragma unroll
;     for (int i = 0; i < 2; ++i) { int R, C; stage_rc(tid * 16 + i * 8192, R, C); const int Rb = Epi::PERM ? ((R & ~31) + perm32(R & 31)) : R;
;         voffA[i] = (unsigned)(R * LDA + C) * 2u; voffB[i] = (unsigned)(Rb * LDB + C) * 2u; }
;     constexpr size_t kstep = (size_t)(BK * 2);
;     constexpr size_t hstepA = (size_t)HALF * LDA * 2, hstepB = (size_t)HALF * LDB * 2;
;     constexpr size_t tstepA = 2 * hstepA, tstepB = 2 * hstepB;
;     const unsigned ldsw = (unsigned)wid * 1024u;
;     const int aoff = lds_byte(wr * 64 + fr, fq * 8), boff = lds_byte(wc * 32 + fr, fq * 8);
;     ...
;     Unit cur, nxt; int ui = 0;
;     if (!S.next(0, cur)) return;
;     f32x4 acc[2][2][4][2];
; #pragma unroll
;     for (int a = 0; a < 2; ++a)
; #pragma unroll
;         for (int b = 0; b < 2; ++b)
; #pragma unroll
;             for (int m = 0; m < 4; ++m)
; #pragma unroll
;                 for (int n = 0; n < 2; ++n) acc[a][b][m][n] = (f32x4){0.f, 0.f, 0.f, 0.f};
;     bf16x8 At[4][2], B0[2][2], B1[2][2];
;     const char* cA = PG8_APTR(cur); const char* cB = PG8_BPTR(cur);
;     PG8_STAGE(PG8_SB(0, 0), cB, voffB); PG8_STAGE(PG8_SB(0, 1), cB + hstepB, voffB); PG8_STAGE(PG8_SA(0, 0), cA, voffA); PG8_STAGE(PG8_SA(0, 1), cA + hstepA, voffA);
;     if (wr == 1) PG8_BAR;
;     PG8_WAIT_V(2); PG8_BAR;
;     PG8_STAGE(PG8_SB(1, 0), cB + kstep, voffB); PG8_STAGE(PG8_SA(1, 0), cA + kstep, voffA); PG8_STAGE(PG8_SB(1, 1), cB + hstepB + kstep, voffB);
;     PG8_WAIT_V(6); PG8_BAR;
.LBB0_379:
	s_mov_b32 s101, 0
	s_mul_i32 s8, s94, 0x2480000
	s_add_u32 s8, s88, s8
	v_writelane_b32 v254, s8, 22
	s_addc_u32 s8, s89, 0
	v_writelane_b32 v254, s8, 23
	v_readlane_b32 s8, v253, 40
	v_mov_b32_e32 v2, v246
	v_readlane_b32 s9, v253, 41
	s_andn2_b64 vcc, exec, s[8:9]
	v_readfirstlane_b32 s24, v2
	s_cbranch_vccnz .LBB0_427
	v_lshlrev_b32_e32 v5, 4, v2
	v_add_u32_e32 v3, 0x2000, v5
	v_ashrrev_i32_e32 v0, 31, v3
	v_lshrrev_b32_e32 v0, 22, v0
	v_add_u32_e32 v0, v3, v0
	v_ashrrev_i32_e32 v0, 10, v0
	v_mul_i32_i24_e32 v4, 0x400, v0
	v_sub_u32_e32 v3, v3, v4
	v_lshrrev_b32_e32 v4, 4, v3
	v_bitop3_b32 v4, v4, v3, 32 bitop3:0x6c
	v_ashrrev_i32_e32 v3, 31, v4
	v_lshrrev_b32_e32 v3, 26, v3
	v_add_u32_e32 v6, v4, v3
	v_lshlrev_b32_e32 v7, 3, v0
	v_ashrrev_i32_e32 v3, 6, v6
	v_and_b32_e32 v7, -16, v7
	v_add_u32_e32 v7, v3, v7
	v_and_b32_e32 v8, 3, v3
	s_mov_b32 s8, 0x1fffe0
	v_lshrrev_b32_e32 v9, 2, v7
	v_lshlrev_b32_e32 v10, 1, v7
	v_and_b32_e32 v6, 0xc0, v6
	v_and_or_b32 v8, v7, s8, v8
	v_and_b32_e32 v9, 4, v9
	v_and_b32_e32 v10, 24, v10
	v_sub_u32_e32 v4, v4, v6
	v_or3_b32 v8, v8, v9, v10
	v_lshlrev_b32_e32 v9, 5, v0
	v_ashrrev_i16_sdwa v4, v248, sext(v4) dst_sel:DWORD dst_unused:UNUSED_PAD src0_sel:DWORD src1_sel:BYTE_0
	v_and_b32_e32 v9, 32, v9
	v_bfe_i32 v4, v4, 0, 16
	v_add_lshl_u32 v6, v9, v4, 1
	v_lshl_add_u32 v142, v8, 11, v6
	v_lshl_add_u32 v144, v7, 11, v6
	v_bfe_i32 v6, v2, 27, 1
	v_lshrrev_b32_e32 v6, 22, v6
	v_add_u32_e32 v6, v5, v6
	v_and_b32_e32 v6, 0xfffffc00, v6
	v_sub_u32_e32 v5, v5, v6
	v_lshrrev_b32_e32 v6, 4, v5
	v_bitop3_b32 v7, v6, v5, 32 bitop3:0x6c
	v_ashrrev_i32_e32 v6, 31, v2
	v_lshrrev_b32_e32 v6, 26, v6
	v_ashrrev_i32_e32 v5, 31, v5
	v_add_u32_e32 v6, v2, v6
	v_lshrrev_b32_e32 v5, 26, v5
	v_ashrrev_i32_e32 v6, 6, v6
	v_add_u32_e32 v5, v7, v5
	v_lshlrev_b32_e32 v8, 3, v6
	v_ashrrev_i32_e32 v5, 6, v5
	v_and_b32_e32 v8, -16, v8
	v_add_u32_e32 v8, v5, v8
	v_and_b32_e32 v9, 3, v5
	v_lshrrev_b32_e32 v10, 2, v8
	v_lshlrev_b32_e32 v11, 1, v8
	v_and_or_b32 v9, v8, s8, v9
	v_and_b32_e32 v10, 4, v10
	v_and_b32_e32 v11, 24, v11
	v_or3_b32 v9, v9, v10, v11
	v_mul_i32_i24_e32 v11, 64, v5
	s_ashr_i32 s25, s24, 6
	v_sub_u32_e32 v7, v7, v11
	s_ashr_i32 s12, s24, 8
	s_lshl_b32 s13, s25, 10
	v_lshlrev_b32_e32 v10, 5, v6
	v_ashrrev_i16_sdwa v7, v248, sext(v7) dst_sel:DWORD dst_unused:UNUSED_PAD src0_sel:DWORD src1_sel:BYTE_0
	v_readlane_b32 s8, v255, 36
	v_readlane_b32 s10, v254, 22
	v_and_b32_e32 v10, 32, v10
	v_bfe_i32 v7, v7, 0, 16
	v_readlane_b32 s9, v255, 37
	s_add_u32 s10, s10, s8
	v_readlane_b32 s8, v254, 23
	v_add_lshl_u32 v10, v10, v7, 1
	s_addc_u32 s11, s8, s9
	s_add_i32 s22, s13, 0
	v_lshl_add_u32 v146, v9, 11, v10
	s_add_i32 m0, s22, 0x10000
	v_lshl_add_u32 v148, v8, 11, v10
	global_load_lds_dwordx4 v146, s[10:11]
	s_add_i32 m0, s22, 0x12000
	s_add_u32 s8, s10, 0x40000
	global_load_lds_dwordx4 v142, s[10:11]
	s_addc_u32 s9, s11, 0
	s_add_i32 m0, s22, 0x14000
	s_add_i32 s23, s22, 0x2000
	global_load_lds_dwordx4 v146, s[8:9]
	s_add_i32 m0, s22, 0x16000
	s_add_i32 s26, s22, 0x4000
	global_load_lds_dwordx4 v142, s[8:9]
	v_readlane_b32 s8, v255, 40
	s_mov_b32 m0, s22
	v_readlane_b32 s9, v255, 41
	s_add_i32 s33, s22, 0x6000
	s_cmp_eq_u32 s12, 1
	s_nop 2
	global_load_lds_dwordx4 v148, s[8:9]
	s_mov_b32 m0, s23
	s_nop 0
	global_load_lds_dwordx4 v144, s[8:9]
	v_readlane_b32 s8, v255, 42
	s_mov_b32 m0, s26
	v_readlane_b32 s9, v255, 43
	s_nop 4
	global_load_lds_dwordx4 v148, s[8:9]
	s_mov_b32 m0, s33
	s_nop 0
	global_load_lds_dwordx4 v144, s[8:9]
	s_cselect_b64 s[8:9], -1, 0
	s_cmp_lg_u32 s12, 1
	s_cbranch_scc1 .LBB0_382
	s_barrier

; #define PG8_STAGE(bufoff, gbase, voff) do { _Pragma("unroll") for (int _i = 0; _i < 2; ++_i) \
;         __builtin_amdgcn_global_load_lds((const unsigned*)((const char*)(gbase) + (voff)[_i]), (LAS unsigned*)(lds + (bufoff) + ldsw + _i * 8192), 16, 0, 0); } while (0)
; #define PG8_LDA(dst, b, h) do { _Pragma("unroll") for (int m = 0; m < 4; ++m) _Pragma("unroll") for (int k = 0; k < 2; ++k) dst[m][k] = *(const LAS bf16x8*)(lds + PG8_SA(b, h) + aoff + m * 2048 + k * 1024); } while (0)
; #define PG8_LDB(dst, b, h) do { _Pragma("unroll") for (int n = 0; n < 2; ++n) _Pragma("unroll") for (int k = 0; k < 2; ++k) dst[n][k] = *(const LAS bf16x8*)(lds + PG8_SB(b, h) + boff + n * 2048 + k * 1024); } while (0)
; #define PG8_MMA(ai, bj, At, Bt) do { __builtin_amdgcn_s_setprio(1); _Pragma("unroll") for (int m = 0; m < 4; ++m) _Pragma("unroll") for (int n = 0; n < 2; ++n) _Pragma("unroll") for (int k = 0; k < 2; ++k) \
;         acc[ai][bj][m][n] = __builtin_amdgcn_mfma_f32_16x16x32_bf16(Bt[n][k], At[m][k], acc[ai][bj][m][n], 0, 0, 0); __builtin_amdgcn_s_setprio(0); } while (0)
; #define PG8_WAIT_V(n) asm volatile("s_waitcnt vmcnt(" #n ")" ::: "memory")
; #define PG8_WAIT_L(n) asm volatile("s_waitcnt lgkmcnt(" #n ")" ::: "memory")
; #define PG8_BAR __builtin_amdgcn_s_barrier()
; #define PG8_SCHED __builtin_amdgcn_sched_barrier(0)
; template <class Epi, class Sched, int NSEG, int KK, int LDA, int LDB>
; __device__ __forceinline__ void gemm_phase(LAS unsigned char* lds, const Gemm g, const Sched& S, const Epi& E) {
;     ...
;         for (int t = 0; t < nt; t += 2) {
;             const bool last = (t == nt - 2);
;             const char* a1 = cA + (size_t)(t + 1) * kstep;
;             const char* a2 = last ? nA : cA + (size_t)(t + 2) * kstep; const char* b2 = last ? nB : cB + (size_t)(t + 2) * kstep;
;             const char* a3 = a2 + kstep; const char* b3 = b2 + kstep;
;             PG8_LDB(B0, 0, 0); PG8_LDB(B1, 0, 1); PG8_SCHED; PG8_LDA(At, 0, 0); PG8_STAGE(PG8_SA(1, 1), a1 + hstepA, voffA);
;             PG8_WAIT_V(8); PG8_WAIT_L(0); PG8_BAR; PG8_MMA(0, 0, At, B0); PG8_MMA(0, 1, At, B1); PG8_BAR; PG8_SCHED;
;             PG8_LDA(At, 0, 1); PG8_STAGE(PG8_SB(0, 0), b2, voffB); PG8_STAGE(PG8_SB(0, 1), b2 + hstepB, voffB); PG8_STAGE(PG8_SA(0, 0), a2, voffA);
;             PG8_WAIT_V(8); PG8_WAIT_L(0); PG8_BAR; PG8_MMA(1, 0, At, B0); PG8_MMA(1, 1, At, B1); PG8_BAR; PG8_SCHED;
.LBB0_388:
	s_add_u32 s10, s40, 0xfffc0080
	s_addc_u32 s11, s41, -1
	s_add_i32 s63, 0, 0x10000
	s_cmp_eq_u32 s62, 12
	s_cselect_b32 s51, s45, s11
	s_cselect_b32 s50, s58, s10
	v_add_u32_e32 v0, s63, v156
	s_cselect_b32 s11, s43, s61
	s_cselect_b32 s10, s59, s60
	s_add_i32 s77, 0, 0x14000
	ds_read_b128 v[130:133], v0
	ds_read_b128 v[134:137], v0 offset:1024
	ds_read_b128 v[138:141], v0 offset:2048
	ds_read_b128 v[158:161], v0 offset:3072
	v_add_u32_e32 v0, s77, v156
	ds_read_b128 v[162:165], v0
	ds_read_b128 v[176:179], v0 offset:1024
	ds_read_b128 v[180:183], v0 offset:2048
	ds_read_b128 v[184:187], v0 offset:3072
	v_lshl_add_u64 v[154:155], s[40:41], 0, v[150:151]
	s_add_i32 m0, s22, 0xc000
	ds_read_b128 v[188:191], v157
	ds_read_b128 v[192:195], v157 offset:1024
	ds_read_b128 v[196:199], v157 offset:2048
	ds_read_b128 v[200:203], v157 offset:3072
	ds_read_b128 v[204:207], v157 offset:4096
	ds_read_b128 v[208:211], v157 offset:5120
	ds_read_b128 v[212:215], v157 offset:6144
	ds_read_b128 v[216:219], v157 offset:7168
	global_load_lds_dwordx4 v[154:155], off
	v_lshl_add_u64 v[154:155], s[40:41], 0, v[152:153]
	s_add_i32 m0, s22, 0xe000
	s_nop 0
	global_load_lds_dwordx4 v[154:155], off
	s_cmp_lg_u32 s101, 0
	s_cbranch_scc1 .Lskw_0_1
	s_waitcnt vmcnt(8)
.Lskw_0_1:
	s_waitcnt lgkmcnt(0)
	s_barrier
	s_setprio 1
	s_waitcnt lgkmcnt(0)
	v_mfma_f32_16x16x32_bf16 v[126:129], v[130:133], v[188:191], v[126:129]
	v_mfma_f32_16x16x32_bf16 v[122:125], v[138:141], v[188:191], v[122:125]
	v_mfma_f32_16x16x32_bf16 v[110:113], v[130:133], v[196:199], v[110:113]
	v_mfma_f32_16x16x32_bf16 v[106:109], v[138:141], v[196:199], v[106:109]
	v_mfma_f32_16x16x32_bf16 v[94:97], v[130:133], v[204:207], v[94:97]
	v_mfma_f32_16x16x32_bf16 v[90:93], v[138:141], v[204:207], v[90:93]
	v_mfma_f32_16x16x32_bf16 v[78:81], v[130:133], v[212:215], v[78:81]
	v_mfma_f32_16x16x32_bf16 v[74:77], v[138:141], v[212:215], v[74:77]
	v_mfma_f32_16x16x32_bf16 v[126:129], v[134:137], v[192:195], v[126:129]
	v_mfma_f32_16x16x32_bf16 v[122:125], v[158:161], v[192:195], v[122:125]
	v_mfma_f32_16x16x32_bf16 v[110:113], v[134:137], v[200:203], v[110:113]
	v_mfma_f32_16x16x32_bf16 v[106:109], v[158:161], v[200:203], v[106:109]
	v_mfma_f32_16x16x32_bf16 v[94:97], v[134:137], v[208:211], v[94:97]
	v_mfma_f32_16x16x32_bf16 v[90:93], v[158:161], v[208:211], v[90:93]
	v_mfma_f32_16x16x32_bf16 v[78:81], v[134:137], v[216:219], v[78:81]
	v_mfma_f32_16x16x32_bf16 v[74:77], v[158:161], v[216:219], v[74:77]
	s_setprio 0
	s_setprio 1
	v_mfma_f32_16x16x32_bf16 v[118:121], v[162:165], v[188:191], v[118:121]
	v_mfma_f32_16x16x32_bf16 v[114:117], v[180:183], v[188:191], v[114:117]
	v_mfma_f32_16x16x32_bf16 v[102:105], v[162:165], v[196:199], v[102:105]
	v_mfma_f32_16x16x32_bf16 v[98:101], v[180:183], v[196:199], v[98:101]
	v_mfma_f32_16x16x32_bf16 v[86:89], v[162:165], v[204:207], v[86:89]
	v_mfma_f32_16x16x32_bf16 v[82:85], v[180:183], v[204:207], v[82:85]
	v_mfma_f32_16x16x32_bf16 v[70:73], v[162:165], v[212:215], v[70:73]
	v_mfma_f32_16x16x32_bf16 v[66:69], v[180:183], v[212:215], v[66:69]
	v_mfma_f32_16x16x32_bf16 v[118:121], v[176:179], v[192:195], v[118:121]
	v_mfma_f32_16x16x32_bf16 v[114:117], v[184:187], v[192:195], v[114:117]
	v_mfma_f32_16x16x32_bf16 v[102:105], v[176:179], v[200:203], v[102:105]
	v_mfma_f32_16x16x32_bf16 v[98:101], v[184:187], v[200:203], v[98:101]
	v_mfma_f32_16x16x32_bf16 v[86:89], v[176:179], v[208:211], v[86:89]
	v_mfma_f32_16x16x32_bf16 v[82:85], v[184:187], v[208:211], v[82:85]
	v_mfma_f32_16x16x32_bf16 v[70:73], v[176:179], v[216:219], v[70:73]
	v_mfma_f32_16x16x32_bf16 v[66:69], v[184:187], v[216:219], v[66:69]
	s_setprio 0
	s_barrier
	s_add_i32 s63, s63, s13
	v_lshl_add_u64 v[154:155], s[10:11], 0, v[146:147]
	s_mov_b32 m0, s63
	ds_read_b128 v[188:191], v157 offset:16384
	ds_read_b128 v[192:195], v157 offset:17408
	ds_read_b128 v[196:199], v157 offset:18432
	ds_read_b128 v[200:203], v157 offset:19456
	ds_read_b128 v[204:207], v157 offset:20480
	ds_read_b128 v[208:211], v157 offset:21504
	ds_read_b128 v[212:215], v157 offset:22528
	ds_read_b128 v[216:219], v157 offset:23552
	global_load_lds_dwordx4 v[154:155], off
	s_add_i32 m0, s63, 0x2000
	s_add_u32 s94, s10, 0x40000
	v_lshl_add_u64 v[166:167], s[10:11], 0, v[142:143]
	s_addc_u32 s95, s11, 0
	s_add_i32 s63, s77, s13
	global_load_lds_dwordx4 v[166:167], off
	v_lshl_add_u64 v[220:221], s[94:95], 0, v[146:147]
	s_mov_b32 m0, s63
	v_lshl_add_u64 v[222:223], s[50:51], 0, v[144:145]
	global_load_lds_dwordx4 v[220:221], off
	v_lshl_add_u64 v[220:221], s[94:95], 0, v[142:143]
	s_add_i32 m0, s63, 0x2000
	s_nop 0
	global_load_lds_dwordx4 v[220:221], off
	v_lshl_add_u64 v[220:221], s[50:51], 0, v[148:149]
	s_mov_b32 m0, s22
	s_nop 0
	global_load_lds_dwordx4 v[220:221], off
	s_mov_b32 m0, s23
	s_nop 0
	global_load_lds_dwordx4 v[222:223], off
	s_cmp_lg_u32 s101, 0
	s_cbranch_scc1 .Lskw_0_2
	s_waitcnt vmcnt(8)
; #define PG8_STAGE(bufoff, gbase, voff) do { _Pragma("unroll") for (int _i = 0; _i < 2; ++_i) \
;         __builtin_amdgcn_global_load_lds((const unsigned*)((const char*)(gbase) + (voff)[_i]), (LAS unsigned*)(lds + (bufoff) + ldsw + _i * 8192), 16, 0, 0); } while (0)
; #define PG8_LDA(dst, b, h) do { _Pragma("unroll") for (int m = 0; m < 4; ++m) _Pragma("unroll") for (int k = 0; k < 2; ++k) dst[m][k] = *(const LAS bf16x8*)(lds + PG8_SA(b, h) + aoff + m * 2048 + k * 1024); } while (0)
; #define PG8_LDB(dst, b, h) do { _Pragma("unroll") for (int n = 0; n < 2; ++n) _Pragma("unroll") for (int k = 0; k < 2; ++k) dst[n][k] = *(const LAS bf16x8*)(lds + PG8_SB(b, h) + boff + n * 2048 + k * 1024); } while (0)
; #define PG8_MMA(ai, bj, At, Bt) do { __builtin_amdgcn_s_setprio(1); _Pragma("unroll") for (int m = 0; m < 4; ++m) _Pragma("unroll") for (int n = 0; n < 2; ++n) _Pragma("unroll") for (int k = 0; k < 2; ++k) \
;         acc[ai][bj][m][n] = __builtin_amdgcn_mfma_f32_16x16x32_bf16(Bt[n][k], At[m][k], acc[ai][bj][m][n], 0, 0, 0); __builtin_amdgcn_s_setprio(0); } while (0)
; #define PG8_WAIT_V(n) asm volatile("s_waitcnt vmcnt(" #n ")" ::: "memory")
; #define PG8_WAIT_L(n) asm volatile("s_waitcnt lgkmcnt(" #n ")" ::: "memory")
; #define PG8_BAR __builtin_amdgcn_s_barrier()
; #define PG8_SCHED __builtin_amdgcn_sched_barrier(0)
; template <class Epi, class Sched, int NSEG, int KK, int LDA, int LDB>
; __device__ __forceinline__ void gemm_phase(LAS unsigned char* lds, const Gemm g, const Sched& S, const Epi& E) {
;     ...
;             PG8_WAIT_V(8); PG8_WAIT_L(0); PG8_BAR; PG8_MMA(1, 0, At, B0); PG8_MMA(1, 1, At, B1); PG8_BAR; PG8_SCHED;
;             PG8_LDB(B0, 1, 0); PG8_LDB(B1, 1, 1); PG8_SCHED; PG8_LDA(At, 1, 0); PG8_STAGE(PG8_SA(0, 1), a2 + hstepA, voffA);
;             PG8_WAIT_V(8); PG8_WAIT_L(0); PG8_BAR; PG8_MMA(0, 0, At, B0); PG8_MMA(0, 1, At, B1); PG8_BAR; PG8_SCHED;
;             PG8_LDA(At, 1, 1); PG8_STAGE(PG8_SB(1, 0), b3, voffB); PG8_STAGE(PG8_SB(1, 1), b3 + hstepB, voffB); PG8_STAGE(PG8_SA(1, 0), a3, voffA);
;             PG8_WAIT_V(8); PG8_WAIT_L(0); PG8_BAR; PG8_MMA(1, 0, At, B0); PG8_MMA(1, 1, At, B1); PG8_BAR; PG8_SCHED;
.Lskw_0_2:
	s_mov_b32 s101, 0
	s_waitcnt lgkmcnt(0)
	s_barrier
	s_setprio 1
	s_waitcnt lgkmcnt(0)
	v_mfma_f32_16x16x32_bf16 v[62:65], v[130:133], v[188:191], v[62:65]
	v_mfma_f32_16x16x32_bf16 v[58:61], v[138:141], v[188:191], v[58:61]
	v_mfma_f32_16x16x32_bf16 v[46:49], v[130:133], v[196:199], v[46:49]
	v_mfma_f32_16x16x32_bf16 v[42:45], v[138:141], v[196:199], v[42:45]
	v_mfma_f32_16x16x32_bf16 v[30:33], v[130:133], v[204:207], v[30:33]
	v_mfma_f32_16x16x32_bf16 v[26:29], v[138:141], v[204:207], v[26:29]
	v_mfma_f32_16x16x32_bf16 v[14:17], v[130:133], v[212:215], v[14:17]
	v_mfma_f32_16x16x32_bf16 v[10:13], v[138:141], v[212:215], v[10:13]
	v_mfma_f32_16x16x32_bf16 v[62:65], v[134:137], v[192:195], v[62:65]
	v_mfma_f32_16x16x32_bf16 v[58:61], v[158:161], v[192:195], v[58:61]
	v_mfma_f32_16x16x32_bf16 v[46:49], v[134:137], v[200:203], v[46:49]
	v_mfma_f32_16x16x32_bf16 v[42:45], v[158:161], v[200:203], v[42:45]
	v_mfma_f32_16x16x32_bf16 v[30:33], v[134:137], v[208:211], v[30:33]
	v_mfma_f32_16x16x32_bf16 v[26:29], v[158:161], v[208:211], v[26:29]
	v_mfma_f32_16x16x32_bf16 v[14:17], v[134:137], v[216:219], v[14:17]
	v_mfma_f32_16x16x32_bf16 v[10:13], v[158:161], v[216:219], v[10:13]
	s_setprio 0
	s_setprio 1
	v_mfma_f32_16x16x32_bf16 v[54:57], v[162:165], v[188:191], v[54:57]
	v_mfma_f32_16x16x32_bf16 v[50:53], v[180:183], v[188:191], v[50:53]
	v_mfma_f32_16x16x32_bf16 v[38:41], v[162:165], v[196:199], v[38:41]
	v_mfma_f32_16x16x32_bf16 v[34:37], v[180:183], v[196:199], v[34:37]
	v_mfma_f32_16x16x32_bf16 v[22:25], v[162:165], v[204:207], v[22:25]
	v_mfma_f32_16x16x32_bf16 v[18:21], v[180:183], v[204:207], v[18:21]
	v_mfma_f32_16x16x32_bf16 v[6:9], v[162:165], v[212:215], v[6:9]
	v_mfma_f32_16x16x32_bf16 v[2:5], v[180:183], v[212:215], v[2:5]
	v_mfma_f32_16x16x32_bf16 v[54:57], v[176:179], v[192:195], v[54:57]
	v_mfma_f32_16x16x32_bf16 v[50:53], v[184:187], v[192:195], v[50:53]
	v_mfma_f32_16x16x32_bf16 v[38:41], v[176:179], v[200:203], v[38:41]
	v_mfma_f32_16x16x32_bf16 v[34:37], v[184:187], v[200:203], v[34:37]
	v_mfma_f32_16x16x32_bf16 v[22:25], v[176:179], v[208:211], v[22:25]
	v_mfma_f32_16x16x32_bf16 v[18:21], v[184:187], v[208:211], v[18:21]
	v_mfma_f32_16x16x32_bf16 v[6:9], v[176:179], v[216:219], v[6:9]
	v_mfma_f32_16x16x32_bf16 v[2:5], v[184:187], v[216:219], v[2:5]
	s_setprio 0
	s_barrier
	s_add_i32 s63, 0, 0x18000
	v_add_u32_e32 v0, s63, v156
	s_add_i32 s77, 0, 0x1c000
	ds_read_b128 v[130:133], v0
	ds_read_b128 v[134:137], v0 offset:1024
	ds_read_b128 v[138:141], v0 offset:2048
	ds_read_b128 v[158:161], v0 offset:3072
	v_add_u32_e32 v0, s77, v156
	ds_read_b128 v[162:165], v0
	ds_read_b128 v[176:179], v0 offset:1024
	ds_read_b128 v[180:183], v0 offset:2048
	ds_read_b128 v[184:187], v0 offset:3072
	s_add_u32 s50, s50, 0x40000
	s_addc_u32 s51, s51, 0
	s_mov_b32 m0, s26
	v_lshl_add_u64 v[224:225], s[50:51], 0, v[148:149]
	ds_read_b128 v[188:191], v157 offset:32768
	ds_read_b128 v[192:195], v157 offset:33792
	ds_read_b128 v[196:199], v157 offset:34816
	ds_read_b128 v[200:203], v157 offset:35840
	ds_read_b128 v[204:207], v157 offset:36864
	ds_read_b128 v[208:211], v157 offset:37888
	ds_read_b128 v[212:215], v157 offset:38912
	ds_read_b128 v[216:219], v157 offset:39936
	global_load_lds_dwordx4 v[224:225], off
	v_lshl_add_u64 v[224:225], s[50:51], 0, v[144:145]
	s_mov_b32 m0, s33
	s_nop 0
	global_load_lds_dwordx4 v[224:225], off
	s_waitcnt vmcnt(8)
	s_waitcnt lgkmcnt(0)
	s_barrier
	s_setprio 1
	s_waitcnt lgkmcnt(0)
	v_mfma_f32_16x16x32_bf16 v[126:129], v[130:133], v[188:191], v[126:129]
	v_mfma_f32_16x16x32_bf16 v[122:125], v[138:141], v[188:191], v[122:125]
	v_mfma_f32_16x16x32_bf16 v[110:113], v[130:133], v[196:199], v[110:113]
	v_mfma_f32_16x16x32_bf16 v[106:109], v[138:141], v[196:199], v[106:109]
	v_mfma_f32_16x16x32_bf16 v[94:97], v[130:133], v[204:207], v[94:97]
	v_mfma_f32_16x16x32_bf16 v[90:93], v[138:141], v[204:207], v[90:93]
	v_mfma_f32_16x16x32_bf16 v[78:81], v[130:133], v[212:215], v[78:81]
	v_mfma_f32_16x16x32_bf16 v[74:77], v[138:141], v[212:215], v[74:77]
	v_mfma_f32_16x16x32_bf16 v[126:129], v[134:137], v[192:195], v[126:129]
	v_mfma_f32_16x16x32_bf16 v[122:125], v[158:161], v[192:195], v[122:125]
	v_mfma_f32_16x16x32_bf16 v[110:113], v[134:137], v[200:203], v[110:113]
	v_mfma_f32_16x16x32_bf16 v[106:109], v[158:161], v[200:203], v[106:109]
	v_mfma_f32_16x16x32_bf16 v[94:97], v[134:137], v[208:211], v[94:97]
	v_mfma_f32_16x16x32_bf16 v[90:93], v[158:161], v[208:211], v[90:93]
	v_mfma_f32_16x16x32_bf16 v[78:81], v[134:137], v[216:219], v[78:81]
	v_mfma_f32_16x16x32_bf16 v[74:77], v[158:161], v[216:219], v[74:77]
	s_setprio 0
	s_setprio 1
	v_mfma_f32_16x16x32_bf16 v[118:121], v[162:165], v[188:191], v[118:121]
	v_mfma_f32_16x16x32_bf16 v[114:117], v[180:183], v[188:191], v[114:117]
	v_mfma_f32_16x16x32_bf16 v[102:105], v[162:165], v[196:199], v[102:105]
	v_mfma_f32_16x16x32_bf16 v[98:101], v[180:183], v[196:199], v[98:101]
	v_mfma_f32_16x16x32_bf16 v[86:89], v[162:165], v[204:207], v[86:89]
	v_mfma_f32_16x16x32_bf16 v[82:85], v[180:183], v[204:207], v[82:85]
	v_mfma_f32_16x16x32_bf16 v[70:73], v[162:165], v[212:215], v[70:73]
	v_mfma_f32_16x16x32_bf16 v[66:69], v[180:183], v[212:215], v[66:69]
	v_mfma_f32_16x16x32_bf16 v[118:121], v[176:179], v[192:195], v[118:121]
	v_mfma_f32_16x16x32_bf16 v[114:117], v[184:187], v[192:195], v[114:117]
	v_mfma_f32_16x16x32_bf16 v[102:105], v[176:179], v[200:203], v[102:105]
	v_mfma_f32_16x16x32_bf16 v[98:101], v[184:187], v[200:203], v[98:101]
	v_mfma_f32_16x16x32_bf16 v[86:89], v[176:179], v[208:211], v[86:89]
	v_mfma_f32_16x16x32_bf16 v[82:85], v[184:187], v[208:211], v[82:85]
	v_mfma_f32_16x16x32_bf16 v[70:73], v[176:179], v[216:219], v[70:73]
	v_mfma_f32_16x16x32_bf16 v[66:69], v[184:187], v[216:219], v[66:69]
	s_setprio 0
	s_barrier
; #define PG8_STAGE(bufoff, gbase, voff) do { _Pragma("unroll") for (int _i = 0; _i < 2; ++_i) \
;         __builtin_amdgcn_global_load_lds((const unsigned*)((const char*)(gbase) + (voff)[_i]), (LAS unsigned*)(lds + (bufoff) + ldsw + _i * 8192), 16, 0, 0); } while (0)
; #define PG8_LDA(dst, b, h) do { _Pragma("unroll") for (int m = 0; m < 4; ++m) _Pragma("unroll") for (int k = 0; k < 2; ++k) dst[m][k] = *(const LAS bf16x8*)(lds + PG8_SA(b, h) + aoff + m * 2048 + k * 1024); } while (0)
; #define PG8_MMA(ai, bj, At, Bt) do { __builtin_amdgcn_s_setprio(1); _Pragma("unroll") for (int m = 0; m < 4; ++m) _Pragma("unroll") for (int n = 0; n < 2; ++n) _Pragma("unroll") for (int k = 0; k < 2; ++k) \
;         acc[ai][bj][m][n] = __builtin_amdgcn_mfma_f32_16x16x32_bf16(Bt[n][k], At[m][k], acc[ai][bj][m][n], 0, 0, 0); __builtin_amdgcn_s_setprio(0); } while (0)
; #define PG8_WAIT_V(n) asm volatile("s_waitcnt vmcnt(" #n ")" ::: "memory")
; #define PG8_WAIT_L(n) asm volatile("s_waitcnt lgkmcnt(" #n ")" ::: "memory")
; #define PG8_BAR __builtin_amdgcn_s_barrier()
; #define PG8_SCHED __builtin_amdgcn_sched_barrier(0)
; template <class Epi, class Sched, int NSEG, int KK, int LDA, int LDB>
; __device__ __forceinline__ void gemm_phase(LAS unsigned char* lds, const Gemm g, const Sched& S, const Epi& E) {
;     ...
;             PG8_LDA(At, 1, 1); PG8_STAGE(PG8_SB(1, 0), b3, voffB); PG8_STAGE(PG8_SB(1, 1), b3 + hstepB, voffB); PG8_STAGE(PG8_SA(1, 0), a3, voffA);
;             PG8_WAIT_V(8); PG8_WAIT_L(0); PG8_BAR; PG8_MMA(1, 0, At, B0); PG8_MMA(1, 1, At, B1); PG8_BAR; PG8_SCHED;
;         }
;         if (wr == 0) PG8_BAR;
	s_add_i32 s50, s63, s13
	v_lshl_add_u64 v[154:155], v[154:155], 0, s[28:29]
	s_mov_b32 m0, s50
	ds_read_b128 v[188:191], v157 offset:49152
	ds_read_b128 v[192:195], v157 offset:50176
	ds_read_b128 v[196:199], v157 offset:51200
	ds_read_b128 v[200:203], v157 offset:52224
	ds_read_b128 v[204:207], v157 offset:53248
	ds_read_b128 v[208:211], v157 offset:54272
	ds_read_b128 v[212:215], v157 offset:55296
	ds_read_b128 v[216:219], v157 offset:56320
	global_load_lds_dwordx4 v[154:155], off
	s_add_i32 m0, s50, 0x2000
	s_add_u32 s10, s10, 0x40080
	v_lshl_add_u64 v[154:155], v[166:167], 0, s[28:29]
	s_addc_u32 s11, s11, 0
	s_add_i32 s50, s77, s13
	global_load_lds_dwordx4 v[154:155], off
	v_lshl_add_u64 v[154:155], s[10:11], 0, v[146:147]
	s_mov_b32 m0, s50
	s_nop 0
	global_load_lds_dwordx4 v[154:155], off
	v_lshl_add_u64 v[154:155], s[10:11], 0, v[142:143]
	s_add_i32 m0, s50, 0x2000
	s_nop 0
	global_load_lds_dwordx4 v[154:155], off
	v_lshl_add_u64 v[154:155], v[220:221], 0, s[28:29]
	s_mov_b32 m0, s53
	s_nop 0
	global_load_lds_dwordx4 v[154:155], off
	v_lshl_add_u64 v[154:155], v[222:223], 0, s[28:29]
	s_mov_b32 m0, s54
	s_nop 0
	global_load_lds_dwordx4 v[154:155], off
	s_waitcnt vmcnt(8)
	s_waitcnt lgkmcnt(0)
	s_barrier
	s_setprio 1
	s_waitcnt lgkmcnt(0)
	v_mfma_f32_16x16x32_bf16 v[62:65], v[130:133], v[188:191], v[62:65]
	v_mfma_f32_16x16x32_bf16 v[58:61], v[138:141], v[188:191], v[58:61]
	v_mfma_f32_16x16x32_bf16 v[46:49], v[130:133], v[196:199], v[46:49]
	v_mfma_f32_16x16x32_bf16 v[42:45], v[138:141], v[196:199], v[42:45]
	v_mfma_f32_16x16x32_bf16 v[30:33], v[130:133], v[204:207], v[30:33]
	v_mfma_f32_16x16x32_bf16 v[26:29], v[138:141], v[204:207], v[26:29]
	v_mfma_f32_16x16x32_bf16 v[14:17], v[130:133], v[212:215], v[14:17]
	v_mfma_f32_16x16x32_bf16 v[10:13], v[138:141], v[212:215], v[10:13]
	v_mfma_f32_16x16x32_bf16 v[62:65], v[134:137], v[192:195], v[62:65]
	v_mfma_f32_16x16x32_bf16 v[58:61], v[158:161], v[192:195], v[58:61]
	v_mfma_f32_16x16x32_bf16 v[46:49], v[134:137], v[200:203], v[46:49]
	v_mfma_f32_16x16x32_bf16 v[42:45], v[158:161], v[200:203], v[42:45]
	v_mfma_f32_16x16x32_bf16 v[30:33], v[134:137], v[208:211], v[30:33]
	v_mfma_f32_16x16x32_bf16 v[26:29], v[158:161], v[208:211], v[26:29]
	v_mfma_f32_16x16x32_bf16 v[14:17], v[134:137], v[216:219], v[14:17]
	v_mfma_f32_16x16x32_bf16 v[10:13], v[158:161], v[216:219], v[10:13]
	s_setprio 0
	s_setprio 1
	v_mfma_f32_16x16x32_bf16 v[54:57], v[162:165], v[188:191], v[54:57]
	v_mfma_f32_16x16x32_bf16 v[50:53], v[180:183], v[188:191], v[50:53]
	v_mfma_f32_16x16x32_bf16 v[38:41], v[162:165], v[196:199], v[38:41]
	v_mfma_f32_16x16x32_bf16 v[34:37], v[180:183], v[196:199], v[34:37]
	v_mfma_f32_16x16x32_bf16 v[22:25], v[162:165], v[204:207], v[22:25]
	v_mfma_f32_16x16x32_bf16 v[18:21], v[180:183], v[204:207], v[18:21]
	v_mfma_f32_16x16x32_bf16 v[6:9], v[162:165], v[212:215], v[6:9]
	v_mfma_f32_16x16x32_bf16 v[2:5], v[180:183], v[212:215], v[2:5]
	v_mfma_f32_16x16x32_bf16 v[54:57], v[176:179], v[192:195], v[54:57]
	v_mfma_f32_16x16x32_bf16 v[50:53], v[184:187], v[192:195], v[50:53]
	v_mfma_f32_16x16x32_bf16 v[38:41], v[176:179], v[200:203], v[38:41]
	v_mfma_f32_16x16x32_bf16 v[34:37], v[184:187], v[200:203], v[34:37]
	v_mfma_f32_16x16x32_bf16 v[22:25], v[176:179], v[208:211], v[22:25]
	v_mfma_f32_16x16x32_bf16 v[18:21], v[184:187], v[208:211], v[18:21]
	v_mfma_f32_16x16x32_bf16 v[6:9], v[176:179], v[216:219], v[6:9]
	v_mfma_f32_16x16x32_bf16 v[2:5], v[184:187], v[216:219], v[2:5]
	s_setprio 0
	s_barrier
	s_add_i32 s62, s62, 2
	s_add_u32 s40, s40, 0x100
	s_addc_u32 s41, s41, 0
	s_add_u32 s60, s60, 0x100
	s_addc_u32 s61, s61, 0
	s_cmp_gt_u32 s62, 13
	s_cbranch_scc0 .LBB0_388
	s_mov_b32 s101, 1
	s_and_b64 vcc, exec, s[24:25]
	s_cbranch_vccz .LBB0_391
	s_barrier

; __device__ __forceinline__ int fresh_tid() { int t = threadIdx.x; asm volatile("" : "+v"(t)); return t; }
; #define PG8_STAGE(bufoff, gbase, voff) do { _Pragma("unroll") for (int _i = 0; _i < 2; ++_i) \
;         __builtin_amdgcn_global_load_lds((const unsigned*)((const char*)(gbase) + (voff)[_i]), (LAS unsigned*)(lds + (bufoff) + ldsw + _i * 8192), 16, 0, 0); } while (0)
; #define PG8_WAIT_V(n) asm volatile("s_waitcnt vmcnt(" #n ")" ::: "memory")
; template <class Epi, class Sched, int NSEG, int KK, int LDA, int LDB>
; __device__ __forceinline__ void gemm_phase(LAS unsigned char* lds, const Gemm g, const Sched& S, const Epi& E) {
;     const int tid = fresh_tid(), wid = __builtin_amdgcn_readfirstlane(tid >> 6), lane = tid & 63, wr = wid >> 2, wc = wid & 3, fr = lane & 15, fq = lane >> 4;
;     constexpr int nt = KK / BK;
;     unsigned voffA[2], voffB[2];
; #pragma unroll
;     for (int i = 0; i < 2; ++i) { int R, C; stage_rc(tid * 16 + i * 8192, R, C); const int Rb = Epi::PERM ? ((R & ~31) + perm32(R & 31)) : R;
;         voffA[i] = (unsigned)(R * LDA + C) * 2u; voffB[i] = (unsigned)(Rb * LDB + C) * 2u; }
;     constexpr size_t kstep = (size_t)(BK * 2);
;     constexpr size_t hstepA = (size_t)HALF * LDA * 2, hstepB = (size_t)HALF * LDB * 2;
;     constexpr size_t tstepA = 2 * hstepA, tstepB = 2 * hstepB;
;     const unsigned ldsw = (unsigned)wid * 1024u;
;     const int aoff = lds_byte(wr * 64 + fr, fq * 8), boff = lds_byte(wc * 32 + fr, fq * 8);
;     ...
;     Unit cur, nxt; int ui = 0;
;     if (!S.next(0, cur)) return;
;     f32x4 acc[2][2][4][2];
; #pragma unroll
;     for (int a = 0; a < 2; ++a)
; #pragma unroll
;         for (int b = 0; b < 2; ++b)
; #pragma unroll
;             for (int m = 0; m < 4; ++m)
; #pragma unroll
;                 for (int n = 0; n < 2; ++n) acc[a][b][m][n] = (f32x4){0.f, 0.f, 0.f, 0.f};
;     bf16x8 At[4][2], B0[2][2], B1[2][2];
;     const char* cA = PG8_APTR(cur); const char* cB = PG8_BPTR(cur);
;     PG8_STAGE(PG8_SB(0, 0), cB, voffB); PG8_STAGE(PG8_SB(0, 1), cB + hstepB, voffB); PG8_STAGE(PG8_SA(0, 0), cA, voffA); PG8_STAGE(PG8_SA(0, 1), cA + hstepA, voffA);
;     if (wr == 1) PG8_BAR;
;     PG8_WAIT_V(2); PG8_BAR;
;     PG8_STAGE(PG8_SB(1, 0), cB + kstep, voffB); PG8_STAGE(PG8_SA(1, 0), cA + kstep, voffA); PG8_STAGE(PG8_SB(1, 1), cB + hstepB + kstep, voffB);
;     PG8_WAIT_V(6); PG8_BAR;
.LBB0_668:
	s_or_b64 exec, exec, s[0:1]
	v_readlane_b32 s0, v255, 20
	v_mov_b32_e32 v7, v246
	v_readlane_b32 s1, v255, 21
	s_waitcnt lgkmcnt(0)
	s_barrier
	s_mov_b32 s101, 0
	s_andn2_b64 vcc, exec, s[0:1]
	v_readfirstlane_b32 s8, v7
	s_cbranch_vccnz .LBB0_700
	v_lshlrev_b32_e32 v4, 4, v7
	v_add_u32_e32 v2, 0x2000, v4
	v_ashrrev_i32_e32 v0, 31, v2
	v_lshrrev_b32_e32 v0, 22, v0
	v_add_u32_e32 v0, v2, v0
	v_ashrrev_i32_e32 v0, 10, v0
	v_mul_i32_i24_e32 v3, 0x400, v0
	v_sub_u32_e32 v2, v2, v3
	v_lshrrev_b32_e32 v3, 4, v2
	v_bitop3_b32 v3, v3, v2, 32 bitop3:0x6c
	v_ashrrev_i32_e32 v2, 31, v3
	v_lshrrev_b32_e32 v2, 26, v2
	v_add_u32_e32 v5, v3, v2
	v_lshlrev_b32_e32 v6, 3, v0
	v_readlane_b32 s0, v254, 22
	v_ashrrev_i32_e32 v2, 6, v5
	v_and_b32_e32 v6, -16, v6
	s_add_u32 s12, s0, 0x900000
	v_readlane_b32 s0, v254, 23
	v_add_u32_e32 v6, v2, v6
	s_addc_u32 s13, s0, 0
	v_and_b32_e32 v8, 3, v2
	s_mov_b32 s0, 0x1fffe0
	v_lshrrev_b32_e32 v9, 2, v6
	v_lshlrev_b32_e32 v10, 1, v6
	v_and_b32_e32 v5, 0xc0, v5
	v_and_or_b32 v8, v6, s0, v8
	v_and_b32_e32 v9, 4, v9
	v_and_b32_e32 v10, 24, v10
	v_sub_u32_e32 v3, v3, v5
	v_or3_b32 v8, v8, v9, v10
	v_lshlrev_b32_e32 v9, 5, v0
	v_ashrrev_i16_sdwa v3, v248, sext(v3) dst_sel:DWORD dst_unused:UNUSED_PAD src0_sel:DWORD src1_sel:BYTE_0
	v_and_b32_e32 v9, 32, v9
	v_bfe_i32 v3, v3, 0, 16
	v_add_lshl_u32 v5, v9, v3, 1
	v_lshl_add_u32 v142, v8, 11, v5
	v_lshl_add_u32 v144, v6, 11, v5
	v_bfe_i32 v5, v7, 27, 1
	v_lshrrev_b32_e32 v5, 22, v5
	v_add_u32_e32 v5, v4, v5
	v_and_b32_e32 v5, 0xfffffc00, v5
	v_sub_u32_e32 v4, v4, v5
	v_lshrrev_b32_e32 v5, 4, v4
	v_bitop3_b32 v6, v5, v4, 32 bitop3:0x6c
	v_ashrrev_i32_e32 v5, 31, v7
	v_lshrrev_b32_e32 v5, 26, v5
	v_ashrrev_i32_e32 v4, 31, v4
	v_add_u32_e32 v5, v7, v5
	v_lshrrev_b32_e32 v4, 26, v4
	v_ashrrev_i32_e32 v5, 6, v5
	v_add_u32_e32 v4, v6, v4
	v_lshlrev_b32_e32 v8, 3, v5
	v_ashrrev_i32_e32 v4, 6, v4
	v_and_b32_e32 v8, -16, v8
	v_add_u32_e32 v8, v4, v8
	v_and_b32_e32 v9, 3, v4
	v_lshrrev_b32_e32 v10, 2, v8
	v_lshlrev_b32_e32 v11, 1, v8
	v_and_or_b32 v9, v8, s0, v9
	v_and_b32_e32 v10, 4, v10
	v_and_b32_e32 v11, 24, v11
	v_or3_b32 v9, v9, v10, v11
	v_mul_i32_i24_e32 v11, 64, v4
	s_ashr_i32 s9, s8, 6
	v_sub_u32_e32 v6, v6, v11
	s_ashr_i32 s22, s8, 8
	s_lshl_b32 s23, s9, 10
	v_lshlrev_b32_e32 v10, 5, v5
	v_ashrrev_i16_sdwa v6, v248, sext(v6) dst_sel:DWORD dst_unused:UNUSED_PAD src0_sel:DWORD src1_sel:BYTE_0
	v_readlane_b32 s0, v255, 25
	v_and_b32_e32 v10, 32, v10
	v_bfe_i32 v6, v6, 0, 16
	v_readlane_b32 s1, v255, 26
	s_add_u32 s10, s12, s0
	v_add_lshl_u32 v10, v10, v6, 1
	s_addc_u32 s11, s13, s1
	s_add_i32 s26, s23, 0
	v_lshl_add_u32 v146, v9, 11, v10
	s_add_i32 m0, s26, 0x10000
	v_lshl_add_u32 v148, v8, 11, v10
	global_load_lds_dwordx4 v146, s[10:11]
	s_add_i32 m0, s26, 0x12000
	s_add_u32 s0, s10, 0x40000
	global_load_lds_dwordx4 v142, s[10:11]
	s_addc_u32 s1, s11, 0
	s_add_i32 m0, s26, 0x14000
	s_add_i32 s33, s26, 0x2000
	global_load_lds_dwordx4 v146, s[0:1]
	s_add_i32 m0, s26, 0x16000
	s_add_i32 s38, s26, 0x4000
	global_load_lds_dwordx4 v142, s[0:1]
	v_readlane_b32 s0, v255, 27
	s_mov_b32 m0, s26
	v_readlane_b32 s1, v255, 28
	s_add_i32 s39, s26, 0x6000
	s_cmp_eq_u32 s22, 1
	s_nop 2
	global_load_lds_dwordx4 v148, s[0:1]
	s_mov_b32 m0, s33
	s_nop 0
	global_load_lds_dwordx4 v144, s[0:1]
	v_readlane_b32 s0, v255, 29
	s_mov_b32 m0, s38
	v_readlane_b32 s1, v255, 30
	s_nop 4
	global_load_lds_dwordx4 v148, s[0:1]
	s_mov_b32 m0, s39
	s_nop 0
	global_load_lds_dwordx4 v144, s[0:1]
	s_cselect_b64 s[0:1], -1, 0
	s_cmp_lg_u32 s22, 1
	s_cbranch_scc1 .LBB0_671
	s_barrier

; #define PG8_STAGE(bufoff, gbase, voff) do { _Pragma("unroll") for (int _i = 0; _i < 2; ++_i) \
;         __builtin_amdgcn_global_load_lds((const unsigned*)((const char*)(gbase) + (voff)[_i]), (LAS unsigned*)(lds + (bufoff) + ldsw + _i * 8192), 16, 0, 0); } while (0)
; #define PG8_LDA(dst, b, h) do { _Pragma("unroll") for (int m = 0; m < 4; ++m) _Pragma("unroll") for (int k = 0; k < 2; ++k) dst[m][k] = *(const LAS bf16x8*)(lds + PG8_SA(b, h) + aoff + m * 2048 + k * 1024); } while (0)
; #define PG8_LDB(dst, b, h) do { _Pragma("unroll") for (int n = 0; n < 2; ++n) _Pragma("unroll") for (int k = 0; k < 2; ++k) dst[n][k] = *(const LAS bf16x8*)(lds + PG8_SB(b, h) + boff + n * 2048 + k * 1024); } while (0)
; #define PG8_MMA(ai, bj, At, Bt) do { __builtin_amdgcn_s_setprio(1); _Pragma("unroll") for (int m = 0; m < 4; ++m) _Pragma("unroll") for (int n = 0; n < 2; ++n) _Pragma("unroll") for (int k = 0; k < 2; ++k) \
;         acc[ai][bj][m][n] = __builtin_amdgcn_mfma_f32_16x16x32_bf16(Bt[n][k], At[m][k], acc[ai][bj][m][n], 0, 0, 0); __builtin_amdgcn_s_setprio(0); } while (0)
; #define PG8_WAIT_V(n) asm volatile("s_waitcnt vmcnt(" #n ")" ::: "memory")
; #define PG8_WAIT_L(n) asm volatile("s_waitcnt lgkmcnt(" #n ")" ::: "memory")
; #define PG8_BAR __builtin_amdgcn_s_barrier()
; #define PG8_SCHED __builtin_amdgcn_sched_barrier(0)
; template <class Epi, class Sched, int NSEG, int KK, int LDA, int LDB>
; __device__ __forceinline__ void gemm_phase(LAS unsigned char* lds, const Gemm g, const Sched& S, const Epi& E) {
;     ...
;         for (int t = 0; t < nt; t += 2) {
;             const bool last = (t == nt - 2);
;             const char* a1 = cA + (size_t)(t + 1) * kstep;
;             const char* a2 = last ? nA : cA + (size_t)(t + 2) * kstep; const char* b2 = last ? nB : cB + (size_t)(t + 2) * kstep;
;             const char* a3 = a2 + kstep; const char* b3 = b2 + kstep;
;             PG8_LDB(B0, 0, 0); PG8_LDB(B1, 0, 1); PG8_SCHED; PG8_LDA(At, 0, 0); PG8_STAGE(PG8_SA(1, 1), a1 + hstepA, voffA);
;             PG8_WAIT_V(8); PG8_WAIT_L(0); PG8_BAR; PG8_MMA(0, 0, At, B0); PG8_MMA(0, 1, At, B1); PG8_BAR; PG8_SCHED;
;             PG8_LDA(At, 0, 1); PG8_STAGE(PG8_SB(0, 0), b2, voffB); PG8_STAGE(PG8_SB(0, 1), b2 + hstepB, voffB); PG8_STAGE(PG8_SA(0, 0), a2, voffA);
;             PG8_WAIT_V(8); PG8_WAIT_L(0); PG8_BAR; PG8_MMA(1, 0, At, B0); PG8_MMA(1, 1, At, B1); PG8_BAR; PG8_SCHED;
.LBB0_677:
	s_add_u32 s10, s48, 0xfffc0080
	s_addc_u32 s11, s49, -1
	s_add_i32 s63, 0, 0x10000
	s_cmp_eq_u32 s62, 12
	s_cselect_b32 s51, s43, s11
	s_cselect_b32 s50, s58, s10
	v_add_u32_e32 v0, s63, v154
	s_cselect_b32 s11, s25, s61
	s_cselect_b32 s10, s59, s60
	s_add_i32 s77, 0, 0x14000
	ds_read_b128 v[130:133], v0
	ds_read_b128 v[134:137], v0 offset:1024
	ds_read_b128 v[138:141], v0 offset:2048
	ds_read_b128 v[156:159], v0 offset:3072
	v_add_u32_e32 v0, s77, v154
	ds_read_b128 v[160:163], v0
	ds_read_b128 v[164:167], v0 offset:1024
	ds_read_b128 v[176:179], v0 offset:2048
	ds_read_b128 v[180:183], v0 offset:3072
	v_lshl_add_u64 v[216:217], s[48:49], 0, v[150:151]
	s_add_i32 m0, s26, 0xc000
	ds_read_b128 v[184:187], v155
	ds_read_b128 v[188:191], v155 offset:1024
	ds_read_b128 v[192:195], v155 offset:2048
	ds_read_b128 v[196:199], v155 offset:3072
	ds_read_b128 v[200:203], v155 offset:4096
	ds_read_b128 v[204:207], v155 offset:5120
	ds_read_b128 v[208:211], v155 offset:6144
	ds_read_b128 v[212:215], v155 offset:7168
	global_load_lds_dwordx4 v[216:217], off
	v_lshl_add_u64 v[216:217], s[48:49], 0, v[152:153]
	s_add_i32 m0, s26, 0xe000
	s_nop 0
	global_load_lds_dwordx4 v[216:217], off
	s_cmp_lg_u32 s101, 0
	s_cbranch_scc1 .Lskw_1_1
	s_waitcnt vmcnt(8)
.Lskw_1_1:
	s_waitcnt lgkmcnt(0)
	s_barrier
	s_setprio 1
	s_waitcnt lgkmcnt(0)
	v_mfma_f32_16x16x32_bf16 v[126:129], v[130:133], v[184:187], v[126:129]
	v_mfma_f32_16x16x32_bf16 v[122:125], v[138:141], v[184:187], v[122:125]
	v_mfma_f32_16x16x32_bf16 v[118:121], v[130:133], v[192:195], v[118:121]
	v_mfma_f32_16x16x32_bf16 v[114:117], v[138:141], v[192:195], v[114:117]
	v_mfma_f32_16x16x32_bf16 v[102:105], v[130:133], v[200:203], v[102:105]
	v_mfma_f32_16x16x32_bf16 v[98:101], v[138:141], v[200:203], v[98:101]
	v_mfma_f32_16x16x32_bf16 v[86:89], v[130:133], v[208:211], v[86:89]
	v_mfma_f32_16x16x32_bf16 v[82:85], v[138:141], v[208:211], v[82:85]
	v_mfma_f32_16x16x32_bf16 v[126:129], v[134:137], v[188:191], v[126:129]
	v_mfma_f32_16x16x32_bf16 v[122:125], v[156:159], v[188:191], v[122:125]
	v_mfma_f32_16x16x32_bf16 v[118:121], v[134:137], v[196:199], v[118:121]
	v_mfma_f32_16x16x32_bf16 v[114:117], v[156:159], v[196:199], v[114:117]
	v_mfma_f32_16x16x32_bf16 v[102:105], v[134:137], v[204:207], v[102:105]
	v_mfma_f32_16x16x32_bf16 v[98:101], v[156:159], v[204:207], v[98:101]
	v_mfma_f32_16x16x32_bf16 v[86:89], v[134:137], v[212:215], v[86:89]
	v_mfma_f32_16x16x32_bf16 v[82:85], v[156:159], v[212:215], v[82:85]
	s_setprio 0
	s_setprio 1
	v_mfma_f32_16x16x32_bf16 v[110:113], v[160:163], v[184:187], v[110:113]
	v_mfma_f32_16x16x32_bf16 v[106:109], v[176:179], v[184:187], v[106:109]
	v_mfma_f32_16x16x32_bf16 v[94:97], v[160:163], v[192:195], v[94:97]
	v_mfma_f32_16x16x32_bf16 v[90:93], v[176:179], v[192:195], v[90:93]
	v_mfma_f32_16x16x32_bf16 v[78:81], v[160:163], v[200:203], v[78:81]
	v_mfma_f32_16x16x32_bf16 v[74:77], v[176:179], v[200:203], v[74:77]
	v_mfma_f32_16x16x32_bf16 v[70:73], v[160:163], v[208:211], v[70:73]
	v_mfma_f32_16x16x32_bf16 v[66:69], v[176:179], v[208:211], v[66:69]
	v_mfma_f32_16x16x32_bf16 v[110:113], v[164:167], v[188:191], v[110:113]
	v_mfma_f32_16x16x32_bf16 v[106:109], v[180:183], v[188:191], v[106:109]
	v_mfma_f32_16x16x32_bf16 v[94:97], v[164:167], v[196:199], v[94:97]
	v_mfma_f32_16x16x32_bf16 v[90:93], v[180:183], v[196:199], v[90:93]
	v_mfma_f32_16x16x32_bf16 v[78:81], v[164:167], v[204:207], v[78:81]
	v_mfma_f32_16x16x32_bf16 v[74:77], v[180:183], v[204:207], v[74:77]
	v_mfma_f32_16x16x32_bf16 v[70:73], v[164:167], v[212:215], v[70:73]
	v_mfma_f32_16x16x32_bf16 v[66:69], v[180:183], v[212:215], v[66:69]
	s_setprio 0
	s_barrier
	s_add_i32 s63, s63, s23
	v_lshl_add_u64 v[216:217], s[10:11], 0, v[146:147]
	s_mov_b32 m0, s63
	ds_read_b128 v[184:187], v155 offset:16384
	ds_read_b128 v[188:191], v155 offset:17408
	ds_read_b128 v[192:195], v155 offset:18432
	ds_read_b128 v[196:199], v155 offset:19456
	ds_read_b128 v[200:203], v155 offset:20480
	ds_read_b128 v[204:207], v155 offset:21504
	ds_read_b128 v[208:211], v155 offset:22528
	ds_read_b128 v[212:215], v155 offset:23552
	global_load_lds_dwordx4 v[216:217], off
	s_add_i32 m0, s63, 0x2000
	s_add_u32 s94, s10, 0x40000
	v_lshl_add_u64 v[218:219], s[10:11], 0, v[142:143]
	s_addc_u32 s95, s11, 0
	s_add_i32 s63, s77, s23
	global_load_lds_dwordx4 v[218:219], off
	v_lshl_add_u64 v[220:221], s[94:95], 0, v[146:147]
	s_mov_b32 m0, s63
	v_lshl_add_u64 v[222:223], s[50:51], 0, v[144:145]
	global_load_lds_dwordx4 v[220:221], off
	v_lshl_add_u64 v[220:221], s[94:95], 0, v[142:143]
	s_add_i32 m0, s63, 0x2000
	s_nop 0
	global_load_lds_dwordx4 v[220:221], off
	v_lshl_add_u64 v[220:221], s[50:51], 0, v[148:149]
	s_mov_b32 m0, s26
	s_nop 0
	global_load_lds_dwordx4 v[220:221], off
	s_mov_b32 m0, s33
	s_nop 0
	global_load_lds_dwordx4 v[222:223], off
	s_cmp_lg_u32 s101, 0
	s_cbranch_scc1 .Lskw_1_2
	s_waitcnt vmcnt(8)
; #define PG8_STAGE(bufoff, gbase, voff) do { _Pragma("unroll") for (int _i = 0; _i < 2; ++_i) \
;         __builtin_amdgcn_global_load_lds((const unsigned*)((const char*)(gbase) + (voff)[_i]), (LAS unsigned*)(lds + (bufoff) + ldsw + _i * 8192), 16, 0, 0); } while (0)
; #define PG8_LDA(dst, b, h) do { _Pragma("unroll") for (int m = 0; m < 4; ++m) _Pragma("unroll") for (int k = 0; k < 2; ++k) dst[m][k] = *(const LAS bf16x8*)(lds + PG8_SA(b, h) + aoff + m * 2048 + k * 1024); } while (0)
; #define PG8_LDB(dst, b, h) do { _Pragma("unroll") for (int n = 0; n < 2; ++n) _Pragma("unroll") for (int k = 0; k < 2; ++k) dst[n][k] = *(const LAS bf16x8*)(lds + PG8_SB(b, h) + boff + n * 2048 + k * 1024); } while (0)
; #define PG8_MMA(ai, bj, At, Bt) do { __builtin_amdgcn_s_setprio(1); _Pragma("unroll") for (int m = 0; m < 4; ++m) _Pragma("unroll") for (int n = 0; n < 2; ++n) _Pragma("unroll") for (int k = 0; k < 2; ++k) \
;         acc[ai][bj][m][n] = __builtin_amdgcn_mfma_f32_16x16x32_bf16(Bt[n][k], At[m][k], acc[ai][bj][m][n], 0, 0, 0); __builtin_amdgcn_s_setprio(0); } while (0)
; #define PG8_WAIT_V(n) asm volatile("s_waitcnt vmcnt(" #n ")" ::: "memory")
; #define PG8_WAIT_L(n) asm volatile("s_waitcnt lgkmcnt(" #n ")" ::: "memory")
; #define PG8_BAR __builtin_amdgcn_s_barrier()
; #define PG8_SCHED __builtin_amdgcn_sched_barrier(0)
; template <class Epi, class Sched, int NSEG, int KK, int LDA, int LDB>
; __device__ __forceinline__ void gemm_phase(LAS unsigned char* lds, const Gemm g, const Sched& S, const Epi& E) {
;     ...
;             PG8_WAIT_V(8); PG8_WAIT_L(0); PG8_BAR; PG8_MMA(1, 0, At, B0); PG8_MMA(1, 1, At, B1); PG8_BAR; PG8_SCHED;
;             PG8_LDB(B0, 1, 0); PG8_LDB(B1, 1, 1); PG8_SCHED; PG8_LDA(At, 1, 0); PG8_STAGE(PG8_SA(0, 1), a2 + hstepA, voffA);
;             PG8_WAIT_V(8); PG8_WAIT_L(0); PG8_BAR; PG8_MMA(0, 0, At, B0); PG8_MMA(0, 1, At, B1); PG8_BAR; PG8_SCHED;
;             PG8_LDA(At, 1, 1); PG8_STAGE(PG8_SB(1, 0), b3, voffB); PG8_STAGE(PG8_SB(1, 1), b3 + hstepB, voffB); PG8_STAGE(PG8_SA(1, 0), a3, voffA);
;             PG8_WAIT_V(8); PG8_WAIT_L(0); PG8_BAR; PG8_MMA(1, 0, At, B0); PG8_MMA(1, 1, At, B1); PG8_BAR; PG8_SCHED;
.Lskw_1_2:
	s_mov_b32 s101, 0
	s_waitcnt lgkmcnt(0)
	s_barrier
	s_setprio 1
	s_waitcnt lgkmcnt(0)
	v_mfma_f32_16x16x32_bf16 v[62:65], v[130:133], v[184:187], v[62:65]
	v_mfma_f32_16x16x32_bf16 v[58:61], v[138:141], v[184:187], v[58:61]
	v_mfma_f32_16x16x32_bf16 v[54:57], v[130:133], v[192:195], v[54:57]
	v_mfma_f32_16x16x32_bf16 v[50:53], v[138:141], v[192:195], v[50:53]
	v_mfma_f32_16x16x32_bf16 v[38:41], v[130:133], v[200:203], v[38:41]
	v_mfma_f32_16x16x32_bf16 v[34:37], v[138:141], v[200:203], v[34:37]
	v_mfma_f32_16x16x32_bf16 v[22:25], v[130:133], v[208:211], v[22:25]
	v_mfma_f32_16x16x32_bf16 v[18:21], v[138:141], v[208:211], v[18:21]
	v_mfma_f32_16x16x32_bf16 v[62:65], v[134:137], v[188:191], v[62:65]
	v_mfma_f32_16x16x32_bf16 v[58:61], v[156:159], v[188:191], v[58:61]
	v_mfma_f32_16x16x32_bf16 v[54:57], v[134:137], v[196:199], v[54:57]
	v_mfma_f32_16x16x32_bf16 v[50:53], v[156:159], v[196:199], v[50:53]
	v_mfma_f32_16x16x32_bf16 v[38:41], v[134:137], v[204:207], v[38:41]
	v_mfma_f32_16x16x32_bf16 v[34:37], v[156:159], v[204:207], v[34:37]
	v_mfma_f32_16x16x32_bf16 v[22:25], v[134:137], v[212:215], v[22:25]
	v_mfma_f32_16x16x32_bf16 v[18:21], v[156:159], v[212:215], v[18:21]
	s_setprio 0
	s_setprio 1
	v_mfma_f32_16x16x32_bf16 v[46:49], v[160:163], v[184:187], v[46:49]
	v_mfma_f32_16x16x32_bf16 v[42:45], v[176:179], v[184:187], v[42:45]
	v_mfma_f32_16x16x32_bf16 v[30:33], v[160:163], v[192:195], v[30:33]
	v_mfma_f32_16x16x32_bf16 v[26:29], v[176:179], v[192:195], v[26:29]
	v_mfma_f32_16x16x32_bf16 v[14:17], v[160:163], v[200:203], v[14:17]
	v_mfma_f32_16x16x32_bf16 v[10:13], v[176:179], v[200:203], v[10:13]
	v_mfma_f32_16x16x32_bf16 v[6:9], v[160:163], v[208:211], v[6:9]
	v_mfma_f32_16x16x32_bf16 v[2:5], v[176:179], v[208:211], v[2:5]
	v_mfma_f32_16x16x32_bf16 v[46:49], v[164:167], v[188:191], v[46:49]
	v_mfma_f32_16x16x32_bf16 v[42:45], v[180:183], v[188:191], v[42:45]
	v_mfma_f32_16x16x32_bf16 v[30:33], v[164:167], v[196:199], v[30:33]
	v_mfma_f32_16x16x32_bf16 v[26:29], v[180:183], v[196:199], v[26:29]
	v_mfma_f32_16x16x32_bf16 v[14:17], v[164:167], v[204:207], v[14:17]
	v_mfma_f32_16x16x32_bf16 v[10:13], v[180:183], v[204:207], v[10:13]
	v_mfma_f32_16x16x32_bf16 v[6:9], v[164:167], v[212:215], v[6:9]
	v_mfma_f32_16x16x32_bf16 v[2:5], v[180:183], v[212:215], v[2:5]
	s_setprio 0
	s_barrier
	s_add_i32 s63, 0, 0x18000
	v_add_u32_e32 v0, s63, v154
	s_add_i32 s77, 0, 0x1c000
	ds_read_b128 v[130:133], v0
	ds_read_b128 v[134:137], v0 offset:1024
	ds_read_b128 v[138:141], v0 offset:2048
	ds_read_b128 v[156:159], v0 offset:3072
	v_add_u32_e32 v0, s77, v154
	ds_read_b128 v[160:163], v0
	ds_read_b128 v[164:167], v0 offset:1024
	ds_read_b128 v[176:179], v0 offset:2048
	ds_read_b128 v[180:183], v0 offset:3072
	s_add_u32 s50, s50, 0x40000
	s_addc_u32 s51, s51, 0
	s_mov_b32 m0, s38
	v_lshl_add_u64 v[224:225], s[50:51], 0, v[148:149]
	ds_read_b128 v[184:187], v155 offset:32768
	ds_read_b128 v[188:191], v155 offset:33792
	ds_read_b128 v[192:195], v155 offset:34816
	ds_read_b128 v[196:199], v155 offset:35840
	ds_read_b128 v[200:203], v155 offset:36864
	ds_read_b128 v[204:207], v155 offset:37888
	ds_read_b128 v[208:211], v155 offset:38912
	ds_read_b128 v[212:215], v155 offset:39936
	global_load_lds_dwordx4 v[224:225], off
	v_lshl_add_u64 v[224:225], s[50:51], 0, v[144:145]
	s_mov_b32 m0, s39
	s_nop 0
	global_load_lds_dwordx4 v[224:225], off
	s_waitcnt vmcnt(8)
	s_waitcnt lgkmcnt(0)
	s_barrier
	s_setprio 1
	s_waitcnt lgkmcnt(0)
	v_mfma_f32_16x16x32_bf16 v[126:129], v[130:133], v[184:187], v[126:129]
	v_mfma_f32_16x16x32_bf16 v[122:125], v[138:141], v[184:187], v[122:125]
	v_mfma_f32_16x16x32_bf16 v[118:121], v[130:133], v[192:195], v[118:121]
	v_mfma_f32_16x16x32_bf16 v[114:117], v[138:141], v[192:195], v[114:117]
	v_mfma_f32_16x16x32_bf16 v[102:105], v[130:133], v[200:203], v[102:105]
	v_mfma_f32_16x16x32_bf16 v[98:101], v[138:141], v[200:203], v[98:101]
	v_mfma_f32_16x16x32_bf16 v[86:89], v[130:133], v[208:211], v[86:89]
	v_mfma_f32_16x16x32_bf16 v[82:85], v[138:141], v[208:211], v[82:85]
	v_mfma_f32_16x16x32_bf16 v[126:129], v[134:137], v[188:191], v[126:129]
	v_mfma_f32_16x16x32_bf16 v[122:125], v[156:159], v[188:191], v[122:125]
	v_mfma_f32_16x16x32_bf16 v[118:121], v[134:137], v[196:199], v[118:121]
	v_mfma_f32_16x16x32_bf16 v[114:117], v[156:159], v[196:199], v[114:117]
	v_mfma_f32_16x16x32_bf16 v[102:105], v[134:137], v[204:207], v[102:105]
	v_mfma_f32_16x16x32_bf16 v[98:101], v[156:159], v[204:207], v[98:101]
	v_mfma_f32_16x16x32_bf16 v[86:89], v[134:137], v[212:215], v[86:89]
	v_mfma_f32_16x16x32_bf16 v[82:85], v[156:159], v[212:215], v[82:85]
	s_setprio 0
	s_setprio 1
	v_mfma_f32_16x16x32_bf16 v[110:113], v[160:163], v[184:187], v[110:113]
	v_mfma_f32_16x16x32_bf16 v[106:109], v[176:179], v[184:187], v[106:109]
	v_mfma_f32_16x16x32_bf16 v[94:97], v[160:163], v[192:195], v[94:97]
	v_mfma_f32_16x16x32_bf16 v[90:93], v[176:179], v[192:195], v[90:93]
	v_mfma_f32_16x16x32_bf16 v[78:81], v[160:163], v[200:203], v[78:81]
	v_mfma_f32_16x16x32_bf16 v[74:77], v[176:179], v[200:203], v[74:77]
	v_mfma_f32_16x16x32_bf16 v[70:73], v[160:163], v[208:211], v[70:73]
	v_mfma_f32_16x16x32_bf16 v[66:69], v[176:179], v[208:211], v[66:69]
	v_mfma_f32_16x16x32_bf16 v[110:113], v[164:167], v[188:191], v[110:113]
	v_mfma_f32_16x16x32_bf16 v[106:109], v[180:183], v[188:191], v[106:109]
	v_mfma_f32_16x16x32_bf16 v[94:97], v[164:167], v[196:199], v[94:97]
	v_mfma_f32_16x16x32_bf16 v[90:93], v[180:183], v[196:199], v[90:93]
	v_mfma_f32_16x16x32_bf16 v[78:81], v[164:167], v[204:207], v[78:81]
	v_mfma_f32_16x16x32_bf16 v[74:77], v[180:183], v[204:207], v[74:77]
	v_mfma_f32_16x16x32_bf16 v[70:73], v[164:167], v[212:215], v[70:73]
	v_mfma_f32_16x16x32_bf16 v[66:69], v[180:183], v[212:215], v[66:69]
	s_setprio 0
	s_barrier
; #define PG8_STAGE(bufoff, gbase, voff) do { _Pragma("unroll") for (int _i = 0; _i < 2; ++_i) \
;         __builtin_amdgcn_global_load_lds((const unsigned*)((const char*)(gbase) + (voff)[_i]), (LAS unsigned*)(lds + (bufoff) + ldsw + _i * 8192), 16, 0, 0); } while (0)
; #define PG8_LDA(dst, b, h) do { _Pragma("unroll") for (int m = 0; m < 4; ++m) _Pragma("unroll") for (int k = 0; k < 2; ++k) dst[m][k] = *(const LAS bf16x8*)(lds + PG8_SA(b, h) + aoff + m * 2048 + k * 1024); } while (0)
; #define PG8_MMA(ai, bj, At, Bt) do { __builtin_amdgcn_s_setprio(1); _Pragma("unroll") for (int m = 0; m < 4; ++m) _Pragma("unroll") for (int n = 0; n < 2; ++n) _Pragma("unroll") for (int k = 0; k < 2; ++k) \
;         acc[ai][bj][m][n] = __builtin_amdgcn_mfma_f32_16x16x32_bf16(Bt[n][k], At[m][k], acc[ai][bj][m][n], 0, 0, 0); __builtin_amdgcn_s_setprio(0); } while (0)
; #define PG8_WAIT_V(n) asm volatile("s_waitcnt vmcnt(" #n ")" ::: "memory")
; #define PG8_WAIT_L(n) asm volatile("s_waitcnt lgkmcnt(" #n ")" ::: "memory")
; #define PG8_BAR __builtin_amdgcn_s_barrier()
; #define PG8_SCHED __builtin_amdgcn_sched_barrier(0)
; template <class Epi, class Sched, int NSEG, int KK, int LDA, int LDB>
; __device__ __forceinline__ void gemm_phase(LAS unsigned char* lds, const Gemm g, const Sched& S, const Epi& E) {
;     ...
;             PG8_LDA(At, 1, 1); PG8_STAGE(PG8_SB(1, 0), b3, voffB); PG8_STAGE(PG8_SB(1, 1), b3 + hstepB, voffB); PG8_STAGE(PG8_SA(1, 0), a3, voffA);
;             PG8_WAIT_V(8); PG8_WAIT_L(0); PG8_BAR; PG8_MMA(1, 0, At, B0); PG8_MMA(1, 1, At, B1); PG8_BAR; PG8_SCHED;
;         }
;         if (wr == 0) PG8_BAR;
	s_add_i32 s50, s63, s23
	v_lshl_add_u64 v[216:217], v[216:217], 0, s[28:29]
	s_mov_b32 m0, s50
	ds_read_b128 v[184:187], v155 offset:49152
	ds_read_b128 v[188:191], v155 offset:50176
	ds_read_b128 v[192:195], v155 offset:51200
	ds_read_b128 v[196:199], v155 offset:52224
	ds_read_b128 v[200:203], v155 offset:53248
	ds_read_b128 v[204:207], v155 offset:54272
	ds_read_b128 v[208:211], v155 offset:55296
	ds_read_b128 v[212:215], v155 offset:56320
	global_load_lds_dwordx4 v[216:217], off
	s_add_i32 m0, s50, 0x2000
	s_add_u32 s10, s10, 0x40080
	v_lshl_add_u64 v[216:217], v[218:219], 0, s[28:29]
	s_addc_u32 s11, s11, 0
	s_add_i32 s50, s77, s23
	global_load_lds_dwordx4 v[216:217], off
	v_lshl_add_u64 v[216:217], s[10:11], 0, v[146:147]
	s_mov_b32 m0, s50
	s_nop 0
	global_load_lds_dwordx4 v[216:217], off
	v_lshl_add_u64 v[216:217], s[10:11], 0, v[142:143]
	s_add_i32 m0, s50, 0x2000
	s_nop 0
	global_load_lds_dwordx4 v[216:217], off
	v_lshl_add_u64 v[216:217], v[220:221], 0, s[28:29]
	s_mov_b32 m0, s53
	s_nop 0
	global_load_lds_dwordx4 v[216:217], off
	v_lshl_add_u64 v[216:217], v[222:223], 0, s[28:29]
	s_mov_b32 m0, s54
	s_nop 0
	global_load_lds_dwordx4 v[216:217], off
	s_waitcnt vmcnt(8)
	s_waitcnt lgkmcnt(0)
	s_barrier
	s_setprio 1
	s_waitcnt lgkmcnt(0)
	v_mfma_f32_16x16x32_bf16 v[62:65], v[130:133], v[184:187], v[62:65]
	v_mfma_f32_16x16x32_bf16 v[58:61], v[138:141], v[184:187], v[58:61]
	v_mfma_f32_16x16x32_bf16 v[54:57], v[130:133], v[192:195], v[54:57]
	v_mfma_f32_16x16x32_bf16 v[50:53], v[138:141], v[192:195], v[50:53]
	v_mfma_f32_16x16x32_bf16 v[38:41], v[130:133], v[200:203], v[38:41]
	v_mfma_f32_16x16x32_bf16 v[34:37], v[138:141], v[200:203], v[34:37]
	v_mfma_f32_16x16x32_bf16 v[22:25], v[130:133], v[208:211], v[22:25]
	v_mfma_f32_16x16x32_bf16 v[18:21], v[138:141], v[208:211], v[18:21]
	v_mfma_f32_16x16x32_bf16 v[62:65], v[134:137], v[188:191], v[62:65]
	v_mfma_f32_16x16x32_bf16 v[58:61], v[156:159], v[188:191], v[58:61]
	v_mfma_f32_16x16x32_bf16 v[54:57], v[134:137], v[196:199], v[54:57]
	v_mfma_f32_16x16x32_bf16 v[50:53], v[156:159], v[196:199], v[50:53]
	v_mfma_f32_16x16x32_bf16 v[38:41], v[134:137], v[204:207], v[38:41]
	v_mfma_f32_16x16x32_bf16 v[34:37], v[156:159], v[204:207], v[34:37]
	v_mfma_f32_16x16x32_bf16 v[22:25], v[134:137], v[212:215], v[22:25]
	v_mfma_f32_16x16x32_bf16 v[18:21], v[156:159], v[212:215], v[18:21]
	s_setprio 0
	s_setprio 1
	v_mfma_f32_16x16x32_bf16 v[46:49], v[160:163], v[184:187], v[46:49]
	v_mfma_f32_16x16x32_bf16 v[42:45], v[176:179], v[184:187], v[42:45]
	v_mfma_f32_16x16x32_bf16 v[30:33], v[160:163], v[192:195], v[30:33]
	v_mfma_f32_16x16x32_bf16 v[26:29], v[176:179], v[192:195], v[26:29]
	v_mfma_f32_16x16x32_bf16 v[14:17], v[160:163], v[200:203], v[14:17]
	v_mfma_f32_16x16x32_bf16 v[10:13], v[176:179], v[200:203], v[10:13]
	v_mfma_f32_16x16x32_bf16 v[6:9], v[160:163], v[208:211], v[6:9]
	v_mfma_f32_16x16x32_bf16 v[2:5], v[176:179], v[208:211], v[2:5]
	v_mfma_f32_16x16x32_bf16 v[46:49], v[164:167], v[188:191], v[46:49]
	v_mfma_f32_16x16x32_bf16 v[42:45], v[180:183], v[188:191], v[42:45]
	v_mfma_f32_16x16x32_bf16 v[30:33], v[164:167], v[196:199], v[30:33]
	v_mfma_f32_16x16x32_bf16 v[26:29], v[180:183], v[196:199], v[26:29]
	v_mfma_f32_16x16x32_bf16 v[14:17], v[164:167], v[204:207], v[14:17]
	v_mfma_f32_16x16x32_bf16 v[10:13], v[180:183], v[204:207], v[10:13]
	v_mfma_f32_16x16x32_bf16 v[6:9], v[164:167], v[212:215], v[6:9]
	v_mfma_f32_16x16x32_bf16 v[2:5], v[180:183], v[212:215], v[2:5]
	s_setprio 0
	s_barrier
	s_add_i32 s62, s62, 2
	s_add_u32 s48, s48, 0x100
	s_addc_u32 s49, s49, 0
	s_add_u32 s60, s60, 0x100
	s_addc_u32 s61, s61, 0
	s_cmp_gt_u32 s62, 13
	s_cbranch_scc0 .LBB0_677
	s_mov_b32 s101, 1
	s_and_b64 vcc, exec, s[8:9]
	s_cbranch_vccz .LBB0_680
	s_barrier

;     ...
;         for (int m = 0; m < 4; ++m) { float sq = (p[ai][m].x + p[ai][m].y) + (p[ai][m].z + p[ai][m].w);
;             sq += __shfl_xor(sq, 16); sq += __shfl_xor(sq, 32);
;             const float rs = __builtin_amdgcn_rsqf(sq * (1.0f / DM) + EPS) * mul;
; #pragma unroll
;             for (int bj = 0; bj < 2; ++bj)
; #pragma unroll
;                 for (int n = 0; n < 2; ++n) acc[ai][bj][m][n] = acc[ai][bj][m][n] * rs; }
;     __device__ __forceinline__ void operator()(f32x4 (&acc)[2][2][4][2], const Unit& u, int wr, int wc, int fr, int fq) const {
;     ...
;                     if (MODE == 1) {
;                         unsigned g0 = 0u, g1 = 0u;
; #pragma unroll
;                         for (int e = 0; e < 4; ++e) { g0 = __builtin_amdgcn_cvt_pk_u8_f32(fmaxf(floorf(255.f * __builtin_amdgcn_rcpf(1.0f + __builtin_amdgcn_exp2f(v0[e])) + 0.5f), 1.f), e, g0);
;                                                       g1 = __builtin_amdgcn_cvt_pk_u8_f32(fmaxf(floorf(255.f * __builtin_amdgcn_rcpf(1.0f + __builtin_amdgcn_exp2f(v1[e])) + 0.5f), 1.f), e, g1); }
;                         *(u32x2*)((unsigned char*)O + ((size_t)(row0 + ai * HALF + m * 16) * ldc + colt) * 2 + bj * HALF + wc * 32 + 8 * fq) = (u32x2){g0, g1};
.LBB0_696:
	s_waitcnt lgkmcnt(7)
	v_add_f32_e32 v0, v0, v158
	v_fmamk_f32 v0, v0, 0x3a800000, v247
	v_rsq_f32_e32 v0, v0
	s_ashr_i32 s51, s50, 31
	s_lshl_b32 s48, s48, 6
	s_ashr_i32 s49, s48, 31
	v_mul_f32_e32 v0, 0xbfb8aa3b, v0
	v_pk_mul_f32 v[176:177], v[122:123], v[0:1] op_sel_hi:[1,0]
	v_pk_mul_f32 v[122:123], v[112:113], v[0:1] op_sel_hi:[1,0]
	s_waitcnt lgkmcnt(6)
	v_add_f32_e32 v112, v159, v160
	v_fmamk_f32 v112, v112, 0x3a800000, v247
	v_rsq_f32_e32 v112, v112
	v_pk_mul_f32 v[132:133], v[128:129], v[0:1] op_sel_hi:[1,0]
	v_pk_mul_f32 v[140:141], v[126:127], v[0:1] op_sel_hi:[1,0]
	v_pk_mul_f32 v[130:131], v[124:125], v[0:1] op_sel_hi:[1,0]
	v_pk_mul_f32 v[128:129], v[110:111], v[0:1] op_sel_hi:[1,0]
	v_pk_mul_f32 v[124:125], v[108:109], v[0:1] op_sel_hi:[1,0]
	v_pk_mul_f32 v[126:127], v[106:107], v[0:1] op_sel_hi:[1,0]
	v_mul_f32_e32 v0, 0xbfb8aa3b, v112
	v_pk_mul_f32 v[106:107], v[96:97], v[0:1] op_sel_hi:[1,0]
	s_waitcnt lgkmcnt(5)
	v_add_f32_e32 v96, v161, v162
	v_fmamk_f32 v96, v96, 0x3a800000, v247
	v_rsq_f32_e32 v96, v96
	v_pk_mul_f32 v[120:121], v[120:121], v[0:1] op_sel_hi:[1,0]
	v_pk_mul_f32 v[118:119], v[118:119], v[0:1] op_sel_hi:[1,0]
	v_pk_mul_f32 v[116:117], v[116:117], v[0:1] op_sel_hi:[1,0]
	v_pk_mul_f32 v[114:115], v[114:115], v[0:1] op_sel_hi:[1,0]
	v_pk_mul_f32 v[112:113], v[94:95], v[0:1] op_sel_hi:[1,0]
	v_pk_mul_f32 v[108:109], v[92:93], v[0:1] op_sel_hi:[1,0]
	v_pk_mul_f32 v[110:111], v[90:91], v[0:1] op_sel_hi:[1,0]
	v_mul_f32_e32 v0, 0xbfb8aa3b, v96
	v_pk_mul_f32 v[90:91], v[80:81], v[0:1] op_sel_hi:[1,0]
	s_waitcnt lgkmcnt(4)
	v_add_f32_e32 v80, v163, v164
	v_fmamk_f32 v80, v80, 0x3a800000, v247
	v_rsq_f32_e32 v80, v80
	v_pk_mul_f32 v[104:105], v[104:105], v[0:1] op_sel_hi:[1,0]
	v_pk_mul_f32 v[102:103], v[102:103], v[0:1] op_sel_hi:[1,0]
	v_pk_mul_f32 v[100:101], v[100:101], v[0:1] op_sel_hi:[1,0]
	v_pk_mul_f32 v[98:99], v[98:99], v[0:1] op_sel_hi:[1,0]
	v_pk_mul_f32 v[96:97], v[78:79], v[0:1] op_sel_hi:[1,0]
	v_pk_mul_f32 v[92:93], v[76:77], v[0:1] op_sel_hi:[1,0]
	v_pk_mul_f32 v[94:95], v[74:75], v[0:1] op_sel_hi:[1,0]
	v_mul_f32_e32 v0, 0xbfb8aa3b, v80
	v_pk_mul_f32 v[74:75], v[72:73], v[0:1] op_sel_hi:[1,0]
	s_waitcnt lgkmcnt(3)
	v_add_f32_e32 v72, v165, v166
	v_fmamk_f32 v72, v72, 0x3a800000, v247
	v_rsq_f32_e32 v72, v72
	v_pk_mul_f32 v[88:89], v[88:89], v[0:1] op_sel_hi:[1,0]
	v_pk_mul_f32 v[86:87], v[86:87], v[0:1] op_sel_hi:[1,0]
	v_pk_mul_f32 v[84:85], v[84:85], v[0:1] op_sel_hi:[1,0]
	v_pk_mul_f32 v[82:83], v[82:83], v[0:1] op_sel_hi:[1,0]
	v_pk_mul_f32 v[80:81], v[70:71], v[0:1] op_sel_hi:[1,0]
	v_pk_mul_f32 v[76:77], v[68:69], v[0:1] op_sel_hi:[1,0]
	v_pk_mul_f32 v[78:79], v[66:67], v[0:1] op_sel_hi:[1,0]
	v_mul_f32_e32 v0, 0xbfb8aa3b, v72
	v_pk_mul_f32 v[70:71], v[58:59], v[0:1] op_sel_hi:[1,0]
	v_pk_mul_f32 v[58:59], v[48:49], v[0:1] op_sel_hi:[1,0]
	s_waitcnt lgkmcnt(2)
	v_add_f32_e32 v48, v138, v139
	v_fmamk_f32 v48, v48, 0x3a800000, v247
	v_rsq_f32_e32 v48, v48
	v_pk_mul_f32 v[68:69], v[64:65], v[0:1] op_sel_hi:[1,0]
	v_pk_mul_f32 v[72:73], v[62:63], v[0:1] op_sel_hi:[1,0]
	v_pk_mul_f32 v[66:67], v[60:61], v[0:1] op_sel_hi:[1,0]
	v_pk_mul_f32 v[64:65], v[46:47], v[0:1] op_sel_hi:[1,0]
	v_pk_mul_f32 v[60:61], v[44:45], v[0:1] op_sel_hi:[1,0]
	v_pk_mul_f32 v[62:63], v[42:43], v[0:1] op_sel_hi:[1,0]
	v_mul_f32_e32 v0, 0xbfb8aa3b, v48
	v_pk_mul_f32 v[42:43], v[32:33], v[0:1] op_sel_hi:[1,0]
	s_waitcnt lgkmcnt(1)
	v_add_f32_e32 v32, v134, v135
	v_fmamk_f32 v32, v32, 0x3a800000, v247
	v_rsq_f32_e32 v32, v32
	v_pk_mul_f32 v[56:57], v[56:57], v[0:1] op_sel_hi:[1,0]
	v_pk_mul_f32 v[54:55], v[54:55], v[0:1] op_sel_hi:[1,0]
	v_pk_mul_f32 v[52:53], v[52:53], v[0:1] op_sel_hi:[1,0]
	v_pk_mul_f32 v[50:51], v[50:51], v[0:1] op_sel_hi:[1,0]
	v_pk_mul_f32 v[48:49], v[30:31], v[0:1] op_sel_hi:[1,0]
	v_pk_mul_f32 v[44:45], v[28:29], v[0:1] op_sel_hi:[1,0]
	v_pk_mul_f32 v[46:47], v[26:27], v[0:1] op_sel_hi:[1,0]
	v_mul_f32_e32 v0, 0xbfb8aa3b, v32
	v_pk_mul_f32 v[26:27], v[16:17], v[0:1] op_sel_hi:[1,0]
	s_waitcnt lgkmcnt(0)
	v_add_f32_e32 v16, v136, v137
	v_fmamk_f32 v16, v16, 0x3a800000, v247
	v_rsq_f32_e32 v16, v16
	v_pk_mul_f32 v[40:41], v[40:41], v[0:1] op_sel_hi:[1,0]
	v_pk_mul_f32 v[38:39], v[38:39], v[0:1] op_sel_hi:[1,0]
	v_pk_mul_f32 v[36:37], v[36:37], v[0:1] op_sel_hi:[1,0]
	v_pk_mul_f32 v[34:35], v[34:35], v[0:1] op_sel_hi:[1,0]
	v_pk_mul_f32 v[32:33], v[14:15], v[0:1] op_sel_hi:[1,0]
	v_pk_mul_f32 v[28:29], v[12:13], v[0:1] op_sel_hi:[1,0]
	v_pk_mul_f32 v[30:31], v[10:11], v[0:1] op_sel_hi:[1,0]
	v_mul_f32_e32 v0, 0xbfb8aa3b, v16
	v_pk_mul_f32 v[14:15], v[18:19], v[0:1] op_sel_hi:[1,0]
	v_exp_f32_e32 v18, v140
	v_pk_mul_f32 v[10:11], v[20:21], v[0:1] op_sel_hi:[1,0]
	v_exp_f32_e32 v21, v141
	v_pk_mul_f32 v[16:17], v[22:23], v[0:1] op_sel_hi:[1,0]
	v_or_b32_e32 v19, s43, v156
	v_add_f32_e32 v18, 1.0, v18
	v_exp_f32_e32 v22, v177
	v_add_u32_e32 v20, s25, v19
	v_rcp_f32_e32 v18, v18
	v_exp_f32_e32 v19, v176
	v_add_f32_e32 v21, 1.0, v21
	v_rcp_f32_e32 v21, v21
	v_add_f32_e32 v22, 1.0, v22
	v_fma_f32 v18, v18, s66, 0.5
	v_add_f32_e32 v19, 1.0, v19
	v_rcp_f32_e32 v22, v22
	v_exp_f32_e32 v23, v132
	v_floor_f32_e32 v18, v18
	v_rcp_f32_e32 v19, v19
	v_fma_f32 v21, v21, s66, 0.5
	v_max_f32_e32 v18, 1.0, v18
	v_floor_f32_e32 v21, v21
	v_cvt_pk_u8_f32 v18, v18, 0, 0
	v_max_f32_e32 v21, 1.0, v21
	v_cvt_pk_u8_f32 v18, v21, 1, v18
	v_fma_f32 v21, v22, s66, 0.5
	v_add_f32_e32 v22, 1.0, v23
	v_fma_f32 v19, v19, s66, 0.5
	v_rcp_f32_e32 v22, v22
	v_exp_f32_e32 v23, v130
	v_floor_f32_e32 v19, v19
	v_max_f32_e32 v19, 1.0, v19
	v_floor_f32_e32 v21, v21
	v_cvt_pk_u8_f32 v19, v19, 0, 0
	v_max_f32_e32 v21, 1.0, v21
;     __device__ __forceinline__ void operator()(f32x4 (&acc)[2][2][4][2], const Unit& u, int wr, int wc, int fr, int fq) const {
;     ...
;                     if (MODE == 1) {
;                         unsigned g0 = 0u, g1 = 0u;
; #pragma unroll
;                         for (int e = 0; e < 4; ++e) { g0 = __builtin_amdgcn_cvt_pk_u8_f32(fmaxf(floorf(255.f * __builtin_amdgcn_rcpf(1.0f + __builtin_amdgcn_exp2f(v0[e])) + 0.5f), 1.f), e, g0);
;                                                       g1 = __builtin_amdgcn_cvt_pk_u8_f32(fmaxf(floorf(255.f * __builtin_amdgcn_rcpf(1.0f + __builtin_amdgcn_exp2f(v1[e])) + 0.5f), 1.f), e, g1); }
;                         *(u32x2*)((unsigned char*)O + ((size_t)(row0 + ai * HALF + m * 16) * ldc + colt) * 2 + bj * HALF + wc * 32 + 8 * fq) = (u32x2){g0, g1};
	v_cvt_pk_u8_f32 v19, v21, 1, v19
	v_fma_f32 v21, v22, s66, 0.5
	v_add_f32_e32 v22, 1.0, v23
	v_rcp_f32_e32 v22, v22
	v_exp_f32_e32 v23, v133
	v_floor_f32_e32 v21, v21
	v_max_f32_e32 v21, 1.0, v21
	v_cvt_pk_u8_f32 v18, v21, 2, v18
	v_fma_f32 v21, v22, s66, 0.5
	v_add_f32_e32 v22, 1.0, v23
	v_rcp_f32_e32 v22, v22
	v_exp_f32_e32 v23, v131
	v_floor_f32_e32 v21, v21
	v_max_f32_e32 v21, 1.0, v21
	v_cvt_pk_u8_f32 v19, v21, 2, v19
	v_fma_f32 v21, v22, s66, 0.5
	v_add_f32_e32 v22, 1.0, v23
	v_rcp_f32_e32 v23, v22
	v_floor_f32_e32 v21, v21
	v_max_f32_e32 v21, 1.0, v21
	v_cvt_pk_u8_f32 v22, v21, 3, v18
	v_fma_f32 v18, v23, s66, 0.5
	v_floor_f32_e32 v18, v18
	v_max_f32_e32 v18, 1.0, v18
	v_cvt_pk_u8_f32 v23, v18, 3, v19
	v_mov_b64_e32 v[18:19], s[50:51]
	s_movk_i32 s25, 0x1200
	v_pk_mul_f32 v[12:13], v[24:25], v[0:1] op_sel_hi:[1,0]
	v_mad_i64_i32 v[24:25], s[10:11], v20, s25, v[18:19]
	v_lshl_add_u64 v[24:25], v[24:25], 1, s[68:69]
	v_pk_mul_f32 v[8:9], v[8:9], v[0:1] op_sel_hi:[1,0]
	v_pk_mul_f32 v[6:7], v[6:7], v[0:1] op_sel_hi:[1,0]
	v_pk_mul_f32 v[4:5], v[4:5], v[0:1] op_sel_hi:[1,0]
	v_pk_mul_f32 v[2:3], v[2:3], v[0:1] op_sel_hi:[1,0]
	v_lshlrev_b32_e32 v0, 4, v157
	v_lshl_add_u64 v[24:25], v[24:25], 0, s[48:49]
	v_exp_f32_e32 v21, v128
	v_lshl_add_u64 v[24:25], v[24:25], 0, v[0:1]
	v_exp_f32_e32 v126, v126
	v_mov_b32_e32 v240, v22
	v_mov_b32_e32 v241, v23
	v_exp_f32_e32 v23, v129
	v_add_f32_e32 v21, 1.0, v21
	v_add_f32_e32 v22, 1.0, v126
	v_exp_f32_e32 v126, v127
	v_rcp_f32_e32 v21, v21
	v_add_f32_e32 v23, 1.0, v23
	v_rcp_f32_e32 v23, v23
	v_exp_f32_e32 v122, v122
	v_rcp_f32_e32 v22, v22
	v_add_f32_e32 v126, 1.0, v126
	v_fma_f32 v21, v21, s66, 0.5
	v_rcp_f32_e32 v126, v126
	v_floor_f32_e32 v21, v21
	v_fma_f32 v23, v23, s66, 0.5
	v_max_f32_e32 v21, 1.0, v21
	v_floor_f32_e32 v23, v23
	v_add_f32_e32 v122, 1.0, v122
	v_cvt_pk_u8_f32 v21, v21, 0, 0
	v_fma_f32 v22, v22, s66, 0.5
	v_max_f32_e32 v23, 1.0, v23
	v_rcp_f32_e32 v122, v122
	v_exp_f32_e32 v124, v124
	v_floor_f32_e32 v22, v22
	v_cvt_pk_u8_f32 v21, v23, 1, v21
	v_fma_f32 v23, v126, s66, 0.5
	v_max_f32_e32 v22, 1.0, v22
	v_floor_f32_e32 v23, v23
	v_cvt_pk_u8_f32 v22, v22, 0, 0
	v_max_f32_e32 v23, 1.0, v23
	v_cvt_pk_u8_f32 v22, v23, 1, v22
	v_fma_f32 v23, v122, s66, 0.5
	v_add_f32_e32 v122, 1.0, v124
	v_rcp_f32_e32 v122, v122
	v_exp_f32_e32 v123, v123
	v_floor_f32_e32 v23, v23
	v_max_f32_e32 v23, 1.0, v23
	v_cvt_pk_u8_f32 v21, v23, 2, v21
	v_fma_f32 v23, v122, s66, 0.5
	v_add_f32_e32 v122, 1.0, v123
	v_rcp_f32_e32 v122, v122
	v_exp_f32_e32 v123, v125
	v_floor_f32_e32 v23, v23
	v_max_f32_e32 v23, 1.0, v23
	v_cvt_pk_u8_f32 v23, v23, 2, v22
	v_fma_f32 v22, v122, s66, 0.5
	v_add_f32_e32 v122, 1.0, v123
	v_rcp_f32_e32 v122, v122
	v_floor_f32_e32 v22, v22
	v_max_f32_e32 v22, 1.0, v22
	v_cvt_pk_u8_f32 v22, v22, 3, v21
	v_fma_f32 v21, v122, s66, 0.5
	v_floor_f32_e32 v21, v21
	v_max_f32_e32 v21, 1.0, v21
	v_exp_f32_e32 v118, v118
	v_cvt_pk_u8_f32 v23, v21, 3, v23
	v_mov_b32_e32 v242, v22
	v_mov_b32_e32 v243, v23
	global_store_dwordx4 v[24:25], v[240:243], off
	v_exp_f32_e32 v23, v119
	v_add_f32_e32 v21, 1.0, v118
	v_exp_f32_e32 v25, v115
	v_rcp_f32_e32 v21, v21
	v_exp_f32_e32 v22, v114
	v_add_f32_e32 v23, 1.0, v23
	v_rcp_f32_e32 v23, v23
	v_add_f32_e32 v25, 1.0, v25
	v_fma_f32 v21, v21, s66, 0.5
	v_add_f32_e32 v22, 1.0, v22
	v_rcp_f32_e32 v25, v25
	v_exp_f32_e32 v114, v120
	v_floor_f32_e32 v21, v21
	v_rcp_f32_e32 v22, v22
	v_fma_f32 v23, v23, s66, 0.5
	v_max_f32_e32 v21, 1.0, v21
	v_floor_f32_e32 v23, v23
	v_cvt_pk_u8_f32 v21, v21, 0, 0
	v_max_f32_e32 v23, 1.0, v23
	v_cvt_pk_u8_f32 v21, v23, 1, v21
	v_fma_f32 v23, v25, s66, 0.5
	v_add_f32_e32 v25, 1.0, v114
	v_fma_f32 v22, v22, s66, 0.5
	v_rcp_f32_e32 v25, v25
	v_exp_f32_e32 v114, v116
	v_floor_f32_e32 v22, v22
	v_max_f32_e32 v22, 1.0, v22
	v_floor_f32_e32 v23, v23
	v_cvt_pk_u8_f32 v22, v22, 0, 0
	v_max_f32_e32 v23, 1.0, v23
	v_cvt_pk_u8_f32 v22, v23, 1, v22
	v_fma_f32 v23, v25, s66, 0.5
	v_add_f32_e32 v25, 1.0, v114
	v_rcp_f32_e32 v25, v25
	v_exp_f32_e32 v114, v121
	v_floor_f32_e32 v23, v23
	v_max_f32_e32 v23, 1.0, v23
	v_cvt_pk_u8_f32 v21, v23, 2, v21
	v_fma_f32 v23, v25, s66, 0.5
	v_add_f32_e32 v25, 1.0, v114
	v_rcp_f32_e32 v25, v25
	v_exp_f32_e32 v114, v117
	v_floor_f32_e32 v23, v23
	v_max_f32_e32 v23, 1.0, v23
	v_cvt_pk_u8_f32 v23, v23, 2, v22
	v_fma_f32 v22, v25, s66, 0.5
	v_add_f32_e32 v25, 1.0, v114
	v_rcp_f32_e32 v25, v25
	v_floor_f32_e32 v22, v22
	v_or_b32_e32 v24, 16, v20
	v_max_f32_e32 v22, 1.0, v22
	v_cvt_pk_u8_f32 v22, v22, 3, v21
	v_fma_f32 v21, v25, s66, 0.5
	v_mad_i64_i32 v[24:25], s[10:11], v24, s25, v[18:19]
	v_floor_f32_e32 v21, v21
	v_lshl_add_u64 v[24:25], v[24:25], 1, s[68:69]
	v_max_f32_e32 v21, 1.0, v21
	v_lshl_add_u64 v[24:25], v[24:25], 0, s[48:49]
	v_cvt_pk_u8_f32 v23, v21, 3, v23
	v_exp_f32_e32 v21, v112
	v_lshl_add_u64 v[24:25], v[24:25], 0, v[0:1]
	v_exp_f32_e32 v110, v110
	v_mov_b32_e32 v236, v22
	v_mov_b32_e32 v237, v23
	v_exp_f32_e32 v23, v113
	v_add_f32_e32 v21, 1.0, v21
	v_add_f32_e32 v22, 1.0, v110
	v_exp_f32_e32 v110, v111
	v_rcp_f32_e32 v21, v21
	v_add_f32_e32 v23, 1.0, v23
	v_rcp_f32_e32 v23, v23
	v_exp_f32_e32 v106, v106
	v_rcp_f32_e32 v22, v22
	v_add_f32_e32 v110, 1.0, v110
	v_fma_f32 v21, v21, s66, 0.5
	v_rcp_f32_e32 v110, v110
	v_floor_f32_e32 v21, v21
	v_fma_f32 v23, v23, s66, 0.5
	v_max_f32_e32 v21, 1.0, v21
	v_floor_f32_e32 v23, v23
	v_add_f32_e32 v106, 1.0, v106
	v_cvt_pk_u8_f32 v21, v21, 0, 0
	v_fma_f32 v22, v22, s66, 0.5
	v_max_f32_e32 v23, 1.0, v23
	v_rcp_f32_e32 v106, v106
	v_exp_f32_e32 v108, v108
	v_floor_f32_e32 v22, v22
	v_cvt_pk_u8_f32 v21, v23, 1, v21
	v_fma_f32 v23, v110, s66, 0.5
;     __device__ __forceinline__ void operator()(f32x4 (&acc)[2][2][4][2], const Unit& u, int wr, int wc, int fr, int fq) const {
;     ...
;                     if (MODE == 1) {
;                         unsigned g0 = 0u, g1 = 0u;
; #pragma unroll
;                         for (int e = 0; e < 4; ++e) { g0 = __builtin_amdgcn_cvt_pk_u8_f32(fmaxf(floorf(255.f * __builtin_amdgcn_rcpf(1.0f + __builtin_amdgcn_exp2f(v0[e])) + 0.5f), 1.f), e, g0);
;                                                       g1 = __builtin_amdgcn_cvt_pk_u8_f32(fmaxf(floorf(255.f * __builtin_amdgcn_rcpf(1.0f + __builtin_amdgcn_exp2f(v1[e])) + 0.5f), 1.f), e, g1); }
;                         *(u32x2*)((unsigned char*)O + ((size_t)(row0 + ai * HALF + m * 16) * ldc + colt) * 2 + bj * HALF + wc * 32 + 8 * fq) = (u32x2){g0, g1};
	v_max_f32_e32 v22, 1.0, v22
	v_floor_f32_e32 v23, v23
	v_cvt_pk_u8_f32 v22, v22, 0, 0
	v_max_f32_e32 v23, 1.0, v23
	v_cvt_pk_u8_f32 v22, v23, 1, v22
	v_fma_f32 v23, v106, s66, 0.5
	v_add_f32_e32 v106, 1.0, v108
	v_rcp_f32_e32 v106, v106
	v_exp_f32_e32 v107, v107
	v_floor_f32_e32 v23, v23
	v_max_f32_e32 v23, 1.0, v23
	v_cvt_pk_u8_f32 v21, v23, 2, v21
	v_fma_f32 v23, v106, s66, 0.5
	v_add_f32_e32 v106, 1.0, v107
	v_rcp_f32_e32 v106, v106
	v_exp_f32_e32 v107, v109
	v_floor_f32_e32 v23, v23
	v_max_f32_e32 v23, 1.0, v23
	v_cvt_pk_u8_f32 v23, v23, 2, v22
	v_fma_f32 v22, v106, s66, 0.5
	v_add_f32_e32 v106, 1.0, v107
	v_rcp_f32_e32 v106, v106
	v_floor_f32_e32 v22, v22
	v_max_f32_e32 v22, 1.0, v22
	v_cvt_pk_u8_f32 v22, v22, 3, v21
	v_fma_f32 v21, v106, s66, 0.5
	v_floor_f32_e32 v21, v21
	v_max_f32_e32 v21, 1.0, v21
	v_exp_f32_e32 v102, v102
	v_cvt_pk_u8_f32 v23, v21, 3, v23
	v_mov_b32_e32 v238, v22
	v_mov_b32_e32 v239, v23
	global_store_dwordx4 v[24:25], v[236:239], off
	v_exp_f32_e32 v23, v103
	v_add_f32_e32 v21, 1.0, v102
	v_exp_f32_e32 v25, v99
	v_rcp_f32_e32 v21, v21
	v_exp_f32_e32 v22, v98
	v_add_f32_e32 v23, 1.0, v23
	v_rcp_f32_e32 v23, v23
	v_add_f32_e32 v25, 1.0, v25
	v_fma_f32 v21, v21, s66, 0.5
	v_add_f32_e32 v22, 1.0, v22
	v_rcp_f32_e32 v25, v25
	v_exp_f32_e32 v98, v104
	v_floor_f32_e32 v21, v21
	v_rcp_f32_e32 v22, v22
	v_fma_f32 v23, v23, s66, 0.5
	v_max_f32_e32 v21, 1.0, v21
	v_floor_f32_e32 v23, v23
	v_cvt_pk_u8_f32 v21, v21, 0, 0
	v_max_f32_e32 v23, 1.0, v23
	v_cvt_pk_u8_f32 v21, v23, 1, v21
	v_fma_f32 v23, v25, s66, 0.5
	v_add_f32_e32 v25, 1.0, v98
	v_fma_f32 v22, v22, s66, 0.5
	v_rcp_f32_e32 v25, v25
	v_exp_f32_e32 v98, v100
	v_floor_f32_e32 v22, v22
	v_max_f32_e32 v22, 1.0, v22
	v_floor_f32_e32 v23, v23
	v_cvt_pk_u8_f32 v22, v22, 0, 0
	v_max_f32_e32 v23, 1.0, v23
	v_cvt_pk_u8_f32 v22, v23, 1, v22
	v_fma_f32 v23, v25, s66, 0.5
	v_add_f32_e32 v25, 1.0, v98
	v_rcp_f32_e32 v25, v25
	v_exp_f32_e32 v98, v105
	v_floor_f32_e32 v23, v23
	v_max_f32_e32 v23, 1.0, v23
	v_cvt_pk_u8_f32 v21, v23, 2, v21
	v_fma_f32 v23, v25, s66, 0.5
	v_add_f32_e32 v25, 1.0, v98
	v_rcp_f32_e32 v25, v25
	v_exp_f32_e32 v98, v101
	v_floor_f32_e32 v23, v23
	v_max_f32_e32 v23, 1.0, v23
	v_cvt_pk_u8_f32 v23, v23, 2, v22
	v_fma_f32 v22, v25, s66, 0.5
	v_add_f32_e32 v25, 1.0, v98
	v_rcp_f32_e32 v25, v25
	v_floor_f32_e32 v22, v22
	v_or_b32_e32 v24, 32, v20
	v_max_f32_e32 v22, 1.0, v22
	v_cvt_pk_u8_f32 v22, v22, 3, v21
	v_fma_f32 v21, v25, s66, 0.5
	v_mad_i64_i32 v[24:25], s[10:11], v24, s25, v[18:19]
	v_floor_f32_e32 v21, v21
	v_lshl_add_u64 v[24:25], v[24:25], 1, s[68:69]
	v_max_f32_e32 v21, 1.0, v21
	v_lshl_add_u64 v[24:25], v[24:25], 0, s[48:49]
	v_cvt_pk_u8_f32 v23, v21, 3, v23
	v_exp_f32_e32 v21, v96
	v_lshl_add_u64 v[24:25], v[24:25], 0, v[0:1]
	v_exp_f32_e32 v94, v94
	v_mov_b32_e32 v240, v22
	v_mov_b32_e32 v241, v23
	v_exp_f32_e32 v23, v97
	v_add_f32_e32 v21, 1.0, v21
	v_add_f32_e32 v22, 1.0, v94
	v_exp_f32_e32 v94, v95
	v_rcp_f32_e32 v21, v21
	v_add_f32_e32 v23, 1.0, v23
	v_rcp_f32_e32 v23, v23
	v_exp_f32_e32 v90, v90
	v_rcp_f32_e32 v22, v22
	v_add_f32_e32 v94, 1.0, v94
	v_fma_f32 v21, v21, s66, 0.5
	v_rcp_f32_e32 v94, v94
	v_floor_f32_e32 v21, v21
	v_fma_f32 v23, v23, s66, 0.5
	v_max_f32_e32 v21, 1.0, v21
	v_floor_f32_e32 v23, v23
	v_add_f32_e32 v90, 1.0, v90
	v_cvt_pk_u8_f32 v21, v21, 0, 0
	v_fma_f32 v22, v22, s66, 0.5
	v_max_f32_e32 v23, 1.0, v23
	v_rcp_f32_e32 v90, v90
	v_exp_f32_e32 v92, v92
	v_floor_f32_e32 v22, v22
	v_cvt_pk_u8_f32 v21, v23, 1, v21
	v_fma_f32 v23, v94, s66, 0.5
	v_max_f32_e32 v22, 1.0, v22
	v_floor_f32_e32 v23, v23
	v_cvt_pk_u8_f32 v22, v22, 0, 0
	v_max_f32_e32 v23, 1.0, v23
	v_cvt_pk_u8_f32 v22, v23, 1, v22
	v_fma_f32 v23, v90, s66, 0.5
	v_add_f32_e32 v90, 1.0, v92
	v_rcp_f32_e32 v90, v90
	v_exp_f32_e32 v91, v91
	v_floor_f32_e32 v23, v23
	v_max_f32_e32 v23, 1.0, v23
	v_cvt_pk_u8_f32 v21, v23, 2, v21
	v_fma_f32 v23, v90, s66, 0.5
	v_add_f32_e32 v90, 1.0, v91
	v_rcp_f32_e32 v90, v90
	v_exp_f32_e32 v91, v93
	v_floor_f32_e32 v23, v23
	v_max_f32_e32 v23, 1.0, v23
	v_cvt_pk_u8_f32 v23, v23, 2, v22
	v_fma_f32 v22, v90, s66, 0.5
	v_add_f32_e32 v90, 1.0, v91
	v_rcp_f32_e32 v90, v90
	v_floor_f32_e32 v22, v22
	v_max_f32_e32 v22, 1.0, v22
	v_cvt_pk_u8_f32 v22, v22, 3, v21
	v_fma_f32 v21, v90, s66, 0.5
	v_floor_f32_e32 v21, v21
	v_max_f32_e32 v21, 1.0, v21
	v_exp_f32_e32 v86, v86
	v_cvt_pk_u8_f32 v23, v21, 3, v23
	v_mov_b32_e32 v242, v22
	v_mov_b32_e32 v243, v23
	global_store_dwordx4 v[24:25], v[240:243], off
	v_exp_f32_e32 v23, v87
	v_add_f32_e32 v21, 1.0, v86
	v_exp_f32_e32 v25, v83
	v_rcp_f32_e32 v21, v21
	v_exp_f32_e32 v22, v82
	v_add_f32_e32 v23, 1.0, v23
	v_rcp_f32_e32 v23, v23
	v_add_f32_e32 v25, 1.0, v25
	v_fma_f32 v21, v21, s66, 0.5
	v_add_f32_e32 v22, 1.0, v22
	v_rcp_f32_e32 v25, v25
	v_exp_f32_e32 v82, v88
	v_floor_f32_e32 v21, v21
	v_rcp_f32_e32 v22, v22
	v_fma_f32 v23, v23, s66, 0.5
	v_max_f32_e32 v21, 1.0, v21
	v_floor_f32_e32 v23, v23
	v_cvt_pk_u8_f32 v21, v21, 0, 0
	v_max_f32_e32 v23, 1.0, v23
	v_cvt_pk_u8_f32 v21, v23, 1, v21
	v_fma_f32 v23, v25, s66, 0.5
	v_add_f32_e32 v25, 1.0, v82
	v_fma_f32 v22, v22, s66, 0.5
	v_rcp_f32_e32 v25, v25
	v_exp_f32_e32 v82, v84
	v_floor_f32_e32 v22, v22
	v_max_f32_e32 v22, 1.0, v22
	v_floor_f32_e32 v23, v23
	v_cvt_pk_u8_f32 v22, v22, 0, 0
	v_max_f32_e32 v23, 1.0, v23
	v_cvt_pk_u8_f32 v22, v23, 1, v22
	v_fma_f32 v23, v25, s66, 0.5
	v_add_f32_e32 v25, 1.0, v82
	v_rcp_f32_e32 v25, v25
	v_exp_f32_e32 v82, v89
	v_floor_f32_e32 v23, v23
	v_max_f32_e32 v23, 1.0, v23
	v_cvt_pk_u8_f32 v21, v23, 2, v21
	v_fma_f32 v23, v25, s66, 0.5
	v_add_f32_e32 v25, 1.0, v82
	v_rcp_f32_e32 v25, v25
	v_exp_f32_e32 v82, v85
;     __device__ __forceinline__ void operator()(f32x4 (&acc)[2][2][4][2], const Unit& u, int wr, int wc, int fr, int fq) const {
;     ...
;                     if (MODE == 1) {
;                         unsigned g0 = 0u, g1 = 0u;
; #pragma unroll
;                         for (int e = 0; e < 4; ++e) { g0 = __builtin_amdgcn_cvt_pk_u8_f32(fmaxf(floorf(255.f * __builtin_amdgcn_rcpf(1.0f + __builtin_amdgcn_exp2f(v0[e])) + 0.5f), 1.f), e, g0);
;                                                       g1 = __builtin_amdgcn_cvt_pk_u8_f32(fmaxf(floorf(255.f * __builtin_amdgcn_rcpf(1.0f + __builtin_amdgcn_exp2f(v1[e])) + 0.5f), 1.f), e, g1); }
;                         *(u32x2*)((unsigned char*)O + ((size_t)(row0 + ai * HALF + m * 16) * ldc + colt) * 2 + bj * HALF + wc * 32 + 8 * fq) = (u32x2){g0, g1};
	v_floor_f32_e32 v23, v23
	v_max_f32_e32 v23, 1.0, v23
	v_cvt_pk_u8_f32 v23, v23, 2, v22
	v_fma_f32 v22, v25, s66, 0.5
	v_add_f32_e32 v25, 1.0, v82
	v_rcp_f32_e32 v25, v25
	v_floor_f32_e32 v22, v22
	v_or_b32_e32 v24, 48, v20
	v_max_f32_e32 v22, 1.0, v22
	v_cvt_pk_u8_f32 v22, v22, 3, v21
	v_fma_f32 v21, v25, s66, 0.5
	v_mad_i64_i32 v[24:25], s[10:11], v24, s25, v[18:19]
	v_floor_f32_e32 v21, v21
	v_lshl_add_u64 v[24:25], v[24:25], 1, s[68:69]
	v_max_f32_e32 v21, 1.0, v21
	v_lshl_add_u64 v[24:25], v[24:25], 0, s[48:49]
	v_cvt_pk_u8_f32 v23, v21, 3, v23
	v_exp_f32_e32 v21, v80
	v_lshl_add_u64 v[24:25], v[24:25], 0, v[0:1]
	v_exp_f32_e32 v78, v78
	v_mov_b32_e32 v236, v22
	v_mov_b32_e32 v237, v23
	v_exp_f32_e32 v23, v81
	v_add_f32_e32 v21, 1.0, v21
	v_add_f32_e32 v22, 1.0, v78
	v_exp_f32_e32 v78, v79
	v_rcp_f32_e32 v21, v21
	v_add_f32_e32 v23, 1.0, v23
	v_rcp_f32_e32 v23, v23
	v_exp_f32_e32 v74, v74
	v_rcp_f32_e32 v22, v22
	v_add_f32_e32 v78, 1.0, v78
	v_fma_f32 v21, v21, s66, 0.5
	v_rcp_f32_e32 v78, v78
	v_floor_f32_e32 v21, v21
	v_fma_f32 v23, v23, s66, 0.5
	v_max_f32_e32 v21, 1.0, v21
	v_floor_f32_e32 v23, v23
	v_add_f32_e32 v74, 1.0, v74
	v_cvt_pk_u8_f32 v21, v21, 0, 0
	v_fma_f32 v22, v22, s66, 0.5
	v_max_f32_e32 v23, 1.0, v23
	v_rcp_f32_e32 v74, v74
	v_exp_f32_e32 v76, v76
	v_floor_f32_e32 v22, v22
	v_cvt_pk_u8_f32 v21, v23, 1, v21
	v_fma_f32 v23, v78, s66, 0.5
	v_max_f32_e32 v22, 1.0, v22
	v_floor_f32_e32 v23, v23
	v_cvt_pk_u8_f32 v22, v22, 0, 0
	v_max_f32_e32 v23, 1.0, v23
	v_cvt_pk_u8_f32 v22, v23, 1, v22
	v_fma_f32 v23, v74, s66, 0.5
	v_add_f32_e32 v74, 1.0, v76
	v_rcp_f32_e32 v74, v74
	v_exp_f32_e32 v75, v75
	v_floor_f32_e32 v23, v23
	v_max_f32_e32 v23, 1.0, v23
	v_cvt_pk_u8_f32 v21, v23, 2, v21
	v_fma_f32 v23, v74, s66, 0.5
	v_add_f32_e32 v74, 1.0, v75
	v_rcp_f32_e32 v74, v74
	v_exp_f32_e32 v75, v77
	v_floor_f32_e32 v23, v23
	v_max_f32_e32 v23, 1.0, v23
	v_cvt_pk_u8_f32 v23, v23, 2, v22
	v_fma_f32 v22, v74, s66, 0.5
	v_add_f32_e32 v74, 1.0, v75
	v_rcp_f32_e32 v74, v74
	v_floor_f32_e32 v22, v22
	v_max_f32_e32 v22, 1.0, v22
	v_cvt_pk_u8_f32 v22, v22, 3, v21
	v_fma_f32 v21, v74, s66, 0.5
	v_floor_f32_e32 v21, v21
	v_max_f32_e32 v21, 1.0, v21
	v_exp_f32_e32 v72, v72
	v_cvt_pk_u8_f32 v23, v21, 3, v23
	v_mov_b32_e32 v238, v22
	v_mov_b32_e32 v239, v23
	global_store_dwordx4 v[24:25], v[236:239], off
	v_exp_f32_e32 v23, v73
	v_add_f32_e32 v21, 1.0, v72
	v_exp_f32_e32 v25, v71
	v_rcp_f32_e32 v21, v21
	v_exp_f32_e32 v22, v70
	v_add_f32_e32 v23, 1.0, v23
	v_rcp_f32_e32 v23, v23
	v_add_f32_e32 v25, 1.0, v25
	v_fma_f32 v21, v21, s66, 0.5
	v_add_f32_e32 v22, 1.0, v22
	v_rcp_f32_e32 v25, v25
	v_exp_f32_e32 v68, v68
	v_floor_f32_e32 v21, v21
	v_rcp_f32_e32 v22, v22
	v_fma_f32 v23, v23, s66, 0.5
	v_max_f32_e32 v21, 1.0, v21
	v_floor_f32_e32 v23, v23
	v_cvt_pk_u8_f32 v21, v21, 0, 0
	v_max_f32_e32 v23, 1.0, v23
	v_cvt_pk_u8_f32 v21, v23, 1, v21
	v_fma_f32 v23, v25, s66, 0.5
	v_add_f32_e32 v25, 1.0, v68
	v_fma_f32 v22, v22, s66, 0.5
	v_rcp_f32_e32 v25, v25
	v_exp_f32_e32 v66, v66
	v_floor_f32_e32 v22, v22
	v_max_f32_e32 v22, 1.0, v22
	v_floor_f32_e32 v23, v23
	v_cvt_pk_u8_f32 v22, v22, 0, 0
	v_max_f32_e32 v23, 1.0, v23
	v_cvt_pk_u8_f32 v22, v23, 1, v22
	v_fma_f32 v23, v25, s66, 0.5
	v_add_f32_e32 v25, 1.0, v66
	v_rcp_f32_e32 v25, v25
	v_exp_f32_e32 v66, v69
	v_floor_f32_e32 v23, v23
	v_max_f32_e32 v23, 1.0, v23
	v_cvt_pk_u8_f32 v21, v23, 2, v21
	v_fma_f32 v23, v25, s66, 0.5
	v_add_f32_e32 v25, 1.0, v66
	v_rcp_f32_e32 v25, v25
	v_exp_f32_e32 v66, v67
	v_floor_f32_e32 v23, v23
	v_max_f32_e32 v23, 1.0, v23
	v_cvt_pk_u8_f32 v23, v23, 2, v22
	v_fma_f32 v22, v25, s66, 0.5
	v_add_f32_e32 v25, 1.0, v66
	v_rcp_f32_e32 v25, v25
	v_floor_f32_e32 v22, v22
	v_add_u32_e32 v24, 0x80, v20
	v_max_f32_e32 v22, 1.0, v22
	v_cvt_pk_u8_f32 v22, v22, 3, v21
	v_fma_f32 v21, v25, s66, 0.5
	v_mad_i64_i32 v[24:25], s[10:11], v24, s25, v[18:19]
	v_floor_f32_e32 v21, v21
	v_lshl_add_u64 v[24:25], v[24:25], 1, s[68:69]
	v_max_f32_e32 v21, 1.0, v21
	v_lshl_add_u64 v[24:25], v[24:25], 0, s[48:49]
	v_cvt_pk_u8_f32 v23, v21, 3, v23
	v_exp_f32_e32 v21, v64
	v_lshl_add_u64 v[24:25], v[24:25], 0, v[0:1]
	v_exp_f32_e32 v62, v62
	v_mov_b32_e32 v240, v22
	v_mov_b32_e32 v241, v23
	v_exp_f32_e32 v23, v65
	v_add_f32_e32 v21, 1.0, v21
	v_add_f32_e32 v22, 1.0, v62
	v_exp_f32_e32 v62, v63
	v_rcp_f32_e32 v21, v21
	v_add_f32_e32 v23, 1.0, v23
	v_rcp_f32_e32 v23, v23
	v_exp_f32_e32 v58, v58
	v_rcp_f32_e32 v22, v22
	v_add_f32_e32 v62, 1.0, v62
	v_fma_f32 v21, v21, s66, 0.5
	v_rcp_f32_e32 v62, v62
	v_floor_f32_e32 v21, v21
	v_fma_f32 v23, v23, s66, 0.5
	v_max_f32_e32 v21, 1.0, v21
	v_floor_f32_e32 v23, v23
	v_add_f32_e32 v58, 1.0, v58
	v_cvt_pk_u8_f32 v21, v21, 0, 0
	v_fma_f32 v22, v22, s66, 0.5
	v_max_f32_e32 v23, 1.0, v23
	v_rcp_f32_e32 v58, v58
	v_exp_f32_e32 v60, v60
	v_floor_f32_e32 v22, v22
	v_cvt_pk_u8_f32 v21, v23, 1, v21
	v_fma_f32 v23, v62, s66, 0.5
	v_max_f32_e32 v22, 1.0, v22
	v_floor_f32_e32 v23, v23
	v_cvt_pk_u8_f32 v22, v22, 0, 0
	v_max_f32_e32 v23, 1.0, v23
	v_cvt_pk_u8_f32 v22, v23, 1, v22
	v_fma_f32 v23, v58, s66, 0.5
	v_add_f32_e32 v58, 1.0, v60
	v_rcp_f32_e32 v58, v58
	v_exp_f32_e32 v59, v59
	v_floor_f32_e32 v23, v23
	v_max_f32_e32 v23, 1.0, v23
	v_cvt_pk_u8_f32 v21, v23, 2, v21
	v_fma_f32 v23, v58, s66, 0.5
	v_add_f32_e32 v58, 1.0, v59
	v_rcp_f32_e32 v58, v58
	v_exp_f32_e32 v59, v61
	v_floor_f32_e32 v23, v23
	v_max_f32_e32 v23, 1.0, v23
	v_cvt_pk_u8_f32 v23, v23, 2, v22
	v_fma_f32 v22, v58, s66, 0.5
	v_add_f32_e32 v58, 1.0, v59
	v_rcp_f32_e32 v58, v58
	v_floor_f32_e32 v22, v22
	v_max_f32_e32 v22, 1.0, v22
	v_cvt_pk_u8_f32 v22, v22, 3, v21
	v_fma_f32 v21, v58, s66, 0.5
;     __device__ __forceinline__ void operator()(f32x4 (&acc)[2][2][4][2], const Unit& u, int wr, int wc, int fr, int fq) const {
;     ...
;                     if (MODE == 1) {
;                         unsigned g0 = 0u, g1 = 0u;
; #pragma unroll
;                         for (int e = 0; e < 4; ++e) { g0 = __builtin_amdgcn_cvt_pk_u8_f32(fmaxf(floorf(255.f * __builtin_amdgcn_rcpf(1.0f + __builtin_amdgcn_exp2f(v0[e])) + 0.5f), 1.f), e, g0);
;                                                       g1 = __builtin_amdgcn_cvt_pk_u8_f32(fmaxf(floorf(255.f * __builtin_amdgcn_rcpf(1.0f + __builtin_amdgcn_exp2f(v1[e])) + 0.5f), 1.f), e, g1); }
;                         *(u32x2*)((unsigned char*)O + ((size_t)(row0 + ai * HALF + m * 16) * ldc + colt) * 2 + bj * HALF + wc * 32 + 8 * fq) = (u32x2){g0, g1};
	v_floor_f32_e32 v21, v21
	v_max_f32_e32 v21, 1.0, v21
	v_exp_f32_e32 v54, v54
	v_cvt_pk_u8_f32 v23, v21, 3, v23
	v_mov_b32_e32 v242, v22
	v_mov_b32_e32 v243, v23
	global_store_dwordx4 v[24:25], v[240:243], off
	v_exp_f32_e32 v23, v55
	v_add_f32_e32 v21, 1.0, v54
	v_exp_f32_e32 v25, v51
	v_rcp_f32_e32 v21, v21
	v_exp_f32_e32 v22, v50
	v_add_f32_e32 v23, 1.0, v23
	v_rcp_f32_e32 v23, v23
	v_add_f32_e32 v25, 1.0, v25
	v_fma_f32 v21, v21, s66, 0.5
	v_add_f32_e32 v22, 1.0, v22
	v_rcp_f32_e32 v25, v25
	v_exp_f32_e32 v50, v56
	v_floor_f32_e32 v21, v21
	v_rcp_f32_e32 v22, v22
	v_fma_f32 v23, v23, s66, 0.5
	v_max_f32_e32 v21, 1.0, v21
	v_floor_f32_e32 v23, v23
	v_cvt_pk_u8_f32 v21, v21, 0, 0
	v_max_f32_e32 v23, 1.0, v23
	v_cvt_pk_u8_f32 v21, v23, 1, v21
	v_fma_f32 v23, v25, s66, 0.5
	v_add_f32_e32 v25, 1.0, v50
	v_fma_f32 v22, v22, s66, 0.5
	v_rcp_f32_e32 v25, v25
	v_exp_f32_e32 v50, v52
	v_floor_f32_e32 v22, v22
	v_max_f32_e32 v22, 1.0, v22
	v_floor_f32_e32 v23, v23
	v_cvt_pk_u8_f32 v22, v22, 0, 0
	v_max_f32_e32 v23, 1.0, v23
	v_cvt_pk_u8_f32 v22, v23, 1, v22
	v_fma_f32 v23, v25, s66, 0.5
	v_add_f32_e32 v25, 1.0, v50
	v_rcp_f32_e32 v25, v25
	v_exp_f32_e32 v50, v57
	v_floor_f32_e32 v23, v23
	v_max_f32_e32 v23, 1.0, v23
	v_cvt_pk_u8_f32 v21, v23, 2, v21
	v_fma_f32 v23, v25, s66, 0.5
	v_add_f32_e32 v25, 1.0, v50
	v_rcp_f32_e32 v25, v25
	v_exp_f32_e32 v50, v53
	v_floor_f32_e32 v23, v23
	v_max_f32_e32 v23, 1.0, v23
	v_cvt_pk_u8_f32 v23, v23, 2, v22
	v_fma_f32 v22, v25, s66, 0.5
	v_add_f32_e32 v25, 1.0, v50
	v_rcp_f32_e32 v25, v25
	v_floor_f32_e32 v22, v22
	v_add_u32_e32 v24, 0x90, v20
	v_max_f32_e32 v22, 1.0, v22
	v_cvt_pk_u8_f32 v22, v22, 3, v21
	v_fma_f32 v21, v25, s66, 0.5
	v_mad_i64_i32 v[24:25], s[10:11], v24, s25, v[18:19]
	v_floor_f32_e32 v21, v21
	v_lshl_add_u64 v[24:25], v[24:25], 1, s[68:69]
	v_max_f32_e32 v21, 1.0, v21
	v_lshl_add_u64 v[24:25], v[24:25], 0, s[48:49]
	v_cvt_pk_u8_f32 v23, v21, 3, v23
	v_exp_f32_e32 v21, v48
	v_lshl_add_u64 v[24:25], v[24:25], 0, v[0:1]
	v_exp_f32_e32 v46, v46
	v_mov_b32_e32 v236, v22
	v_mov_b32_e32 v237, v23
	v_exp_f32_e32 v23, v49
	v_add_f32_e32 v21, 1.0, v21
	v_add_f32_e32 v22, 1.0, v46
	v_exp_f32_e32 v46, v47
	v_rcp_f32_e32 v21, v21
	v_add_f32_e32 v23, 1.0, v23
	v_rcp_f32_e32 v23, v23
	v_exp_f32_e32 v42, v42
	v_rcp_f32_e32 v22, v22
	v_add_f32_e32 v46, 1.0, v46
	v_fma_f32 v21, v21, s66, 0.5
	v_rcp_f32_e32 v46, v46
	v_floor_f32_e32 v21, v21
	v_fma_f32 v23, v23, s66, 0.5
	v_max_f32_e32 v21, 1.0, v21
	v_floor_f32_e32 v23, v23
	v_add_f32_e32 v42, 1.0, v42
	v_cvt_pk_u8_f32 v21, v21, 0, 0
	v_fma_f32 v22, v22, s66, 0.5
	v_max_f32_e32 v23, 1.0, v23
	v_rcp_f32_e32 v42, v42
	v_exp_f32_e32 v44, v44
	v_floor_f32_e32 v22, v22
	v_cvt_pk_u8_f32 v21, v23, 1, v21
	v_fma_f32 v23, v46, s66, 0.5
	v_max_f32_e32 v22, 1.0, v22
	v_floor_f32_e32 v23, v23
	v_cvt_pk_u8_f32 v22, v22, 0, 0
	v_max_f32_e32 v23, 1.0, v23
	v_cvt_pk_u8_f32 v22, v23, 1, v22
	v_fma_f32 v23, v42, s66, 0.5
	v_add_f32_e32 v42, 1.0, v44
	v_rcp_f32_e32 v42, v42
	v_exp_f32_e32 v43, v43
	v_floor_f32_e32 v23, v23
	v_max_f32_e32 v23, 1.0, v23
	v_cvt_pk_u8_f32 v21, v23, 2, v21
	v_fma_f32 v23, v42, s66, 0.5
	v_add_f32_e32 v42, 1.0, v43
	v_rcp_f32_e32 v42, v42
	v_exp_f32_e32 v43, v45
	v_floor_f32_e32 v23, v23
	v_max_f32_e32 v23, 1.0, v23
	v_cvt_pk_u8_f32 v23, v23, 2, v22
	v_fma_f32 v22, v42, s66, 0.5
	v_add_f32_e32 v42, 1.0, v43
	v_rcp_f32_e32 v42, v42
	v_floor_f32_e32 v22, v22
	v_max_f32_e32 v22, 1.0, v22
	v_cvt_pk_u8_f32 v22, v22, 3, v21
	v_fma_f32 v21, v42, s66, 0.5
	v_floor_f32_e32 v21, v21
	v_max_f32_e32 v21, 1.0, v21
	v_exp_f32_e32 v38, v38
	v_cvt_pk_u8_f32 v23, v21, 3, v23
	v_mov_b32_e32 v238, v22
	v_mov_b32_e32 v239, v23
	global_store_dwordx4 v[24:25], v[236:239], off
	v_exp_f32_e32 v23, v39
	v_add_f32_e32 v21, 1.0, v38
	v_exp_f32_e32 v25, v35
	v_rcp_f32_e32 v21, v21
	v_exp_f32_e32 v22, v34
	v_add_f32_e32 v23, 1.0, v23
	v_rcp_f32_e32 v23, v23
	v_add_f32_e32 v25, 1.0, v25
	v_fma_f32 v21, v21, s66, 0.5
	v_add_f32_e32 v22, 1.0, v22
	v_rcp_f32_e32 v25, v25
	v_exp_f32_e32 v34, v40
	v_floor_f32_e32 v21, v21
	v_rcp_f32_e32 v22, v22
	v_fma_f32 v23, v23, s66, 0.5
	v_max_f32_e32 v21, 1.0, v21
	v_floor_f32_e32 v23, v23
	v_cvt_pk_u8_f32 v21, v21, 0, 0
	v_max_f32_e32 v23, 1.0, v23
	v_cvt_pk_u8_f32 v21, v23, 1, v21
	v_fma_f32 v23, v25, s66, 0.5
	v_add_f32_e32 v25, 1.0, v34
	v_fma_f32 v22, v22, s66, 0.5
	v_rcp_f32_e32 v25, v25
	v_exp_f32_e32 v34, v36
	v_floor_f32_e32 v22, v22
	v_max_f32_e32 v22, 1.0, v22
	v_floor_f32_e32 v23, v23
	v_exp_f32_e32 v14, v14
	v_cvt_pk_u8_f32 v22, v22, 0, 0
	v_max_f32_e32 v23, 1.0, v23
	v_exp_f32_e32 v15, v15
	v_cvt_pk_u8_f32 v22, v23, 1, v22
	v_fma_f32 v23, v25, s66, 0.5
	v_add_f32_e32 v25, 1.0, v34
	v_exp_f32_e32 v16, v16
	v_exp_f32_e32 v10, v10
	v_rcp_f32_e32 v25, v25
	v_exp_f32_e32 v34, v41
	v_exp_f32_e32 v17, v17
	v_add_f32_e32 v14, 1.0, v14
	v_exp_f32_e32 v12, v12
	v_floor_f32_e32 v23, v23
	v_rcp_f32_e32 v14, v14
	v_add_f32_e32 v15, 1.0, v15
	v_exp_f32_e32 v13, v13
	v_max_f32_e32 v23, 1.0, v23
	v_add_f32_e32 v16, 1.0, v16
	v_rcp_f32_e32 v15, v15
	v_add_f32_e32 v10, 1.0, v10
	v_cvt_pk_u8_f32 v21, v23, 2, v21
	v_fma_f32 v23, v25, s66, 0.5
	v_add_f32_e32 v25, 1.0, v34
	v_rcp_f32_e32 v16, v16
	v_add_f32_e32 v17, 1.0, v17
	v_rcp_f32_e32 v10, v10
	v_rcp_f32_e32 v25, v25
	v_exp_f32_e32 v34, v37
	v_rcp_f32_e32 v17, v17
	v_add_f32_e32 v12, 1.0, v12
	v_fma_f32 v14, v14, s66, 0.5
; #define PG8_BAR __builtin_amdgcn_s_barrier()
;     __device__ __forceinline__ void operator()(f32x4 (&acc)[2][2][4][2], const Unit& u, int wr, int wc, int fr, int fq) const {
;     ...
;                     if (MODE == 1) {
;                         unsigned g0 = 0u, g1 = 0u;
; #pragma unroll
;                         for (int e = 0; e < 4; ++e) { g0 = __builtin_amdgcn_cvt_pk_u8_f32(fmaxf(floorf(255.f * __builtin_amdgcn_rcpf(1.0f + __builtin_amdgcn_exp2f(v0[e])) + 0.5f), 1.f), e, g0);
;                                                       g1 = __builtin_amdgcn_cvt_pk_u8_f32(fmaxf(floorf(255.f * __builtin_amdgcn_rcpf(1.0f + __builtin_amdgcn_exp2f(v1[e])) + 0.5f), 1.f), e, g1); }
;                         *(u32x2*)((unsigned char*)O + ((size_t)(row0 + ai * HALF + m * 16) * ldc + colt) * 2 + bj * HALF + wc * 32 + 8 * fq) = (u32x2){g0, g1};
; template <class Epi, class Sched, int NSEG, int KK, int LDA, int LDB>
; __device__ __forceinline__ void gemm_phase(LAS unsigned char* lds, const Gemm g, const Sched& S, const Epi& E) {
;     ...
;         if (!has_next) break;
;         if (!E.keep(cur)) {
; #pragma unroll
;             for (int a = 0; a < 2; ++a)
; #pragma unroll
;                 for (int b = 0; b < 2; ++b)
; #pragma unroll
;                     for (int m = 0; m < 4; ++m)
; #pragma unroll
;                         for (int n = 0; n < 2; ++n) acc[a][b][m][n] = (f32x4){0.f, 0.f, 0.f, 0.f};
;         }
;         cur = nxt; cA = nA; cB = nB; ++ui;
;         if (wr == 1) PG8_BAR;
	v_rcp_f32_e32 v12, v12
	v_add_f32_e32 v13, 1.0, v13
	v_floor_f32_e32 v23, v23
	v_floor_f32_e32 v14, v14
	v_fma_f32 v15, v15, s66, 0.5
	v_rcp_f32_e32 v13, v13
	v_max_f32_e32 v23, 1.0, v23
	v_fma_f32 v16, v16, s66, 0.5
	v_max_f32_e32 v14, 1.0, v14
	v_floor_f32_e32 v15, v15
	v_fma_f32 v10, v10, s66, 0.5
	v_exp_f32_e32 v6, v6
	v_cvt_pk_u8_f32 v23, v23, 2, v22
	v_fma_f32 v22, v25, s66, 0.5
	v_add_f32_e32 v25, 1.0, v34
	v_floor_f32_e32 v16, v16
	v_cvt_pk_u8_f32 v14, v14, 0, 0
	v_fma_f32 v17, v17, s66, 0.5
	v_max_f32_e32 v15, 1.0, v15
	v_floor_f32_e32 v10, v10
	v_rcp_f32_e32 v25, v25
	v_max_f32_e32 v16, 1.0, v16
	v_floor_f32_e32 v17, v17
	v_cvt_pk_u8_f32 v14, v15, 1, v14
	v_fma_f32 v12, v12, s66, 0.5
	v_max_f32_e32 v10, 1.0, v10
	v_cvt_pk_u8_f32 v16, v16, 0, 0
	v_max_f32_e32 v17, 1.0, v17
	v_floor_f32_e32 v12, v12
	v_cvt_pk_u8_f32 v14, v10, 2, v14
	v_fma_f32 v10, v13, s66, 0.5
	v_floor_f32_e32 v22, v22
	v_cvt_pk_u8_f32 v16, v17, 1, v16
	v_max_f32_e32 v12, 1.0, v12
	v_floor_f32_e32 v10, v10
	v_add_f32_e32 v6, 1.0, v6
	v_add_u32_e32 v24, 0xa0, v20
	v_max_f32_e32 v22, 1.0, v22
	v_add_u32_e32 v20, 0xb0, v20
	v_cvt_pk_u8_f32 v12, v12, 2, v16
	v_max_f32_e32 v10, 1.0, v10
	v_rcp_f32_e32 v6, v6
	v_cvt_pk_u8_f32 v22, v22, 3, v21
	v_fma_f32 v21, v25, s66, 0.5
	v_mad_i64_i32 v[24:25], s[10:11], v24, s25, v[18:19]
	v_cvt_pk_u8_f32 v10, v10, 3, v12
	v_mad_i64_i32 v[12:13], s[10:11], v20, s25, v[18:19]
	v_floor_f32_e32 v21, v21
	v_lshl_add_u64 v[24:25], v[24:25], 1, s[68:69]
	v_lshl_add_u64 v[12:13], v[12:13], 1, s[68:69]
	v_max_f32_e32 v21, 1.0, v21
	v_lshl_add_u64 v[24:25], v[24:25], 0, s[48:49]
	v_lshl_add_u64 v[12:13], v[12:13], 0, s[48:49]
	v_cvt_pk_u8_f32 v23, v21, 3, v23
	v_exp_f32_e32 v21, v32
	v_lshl_add_u64 v[24:25], v[24:25], 0, v[0:1]
	v_exp_f32_e32 v30, v30
	v_lshl_add_u64 v[12:13], v[12:13], 0, v[0:1]
	v_exp_f32_e32 v0, v2
	v_fma_f32 v2, v6, s66, 0.5
	v_exp_f32_e32 v6, v7
	v_mov_b32_e32 v240, v22
	v_mov_b32_e32 v241, v23
	v_exp_f32_e32 v23, v33
	v_add_f32_e32 v21, 1.0, v21
	v_add_f32_e32 v22, 1.0, v30
	v_exp_f32_e32 v30, v31
	v_add_f32_e32 v6, 1.0, v6
	v_rcp_f32_e32 v21, v21
	v_add_f32_e32 v23, 1.0, v23
	v_rcp_f32_e32 v6, v6
	v_exp_f32_e32 v3, v3
	v_rcp_f32_e32 v23, v23
	v_exp_f32_e32 v26, v26
	v_rcp_f32_e32 v22, v22
	v_add_f32_e32 v30, 1.0, v30
	v_add_f32_e32 v0, 1.0, v0
	v_exp_f32_e32 v7, v8
	v_fma_f32 v21, v21, s66, 0.5
	v_rcp_f32_e32 v30, v30
	v_floor_f32_e32 v2, v2
	v_rcp_f32_e32 v0, v0
	v_fma_f32 v6, v6, s66, 0.5
	v_add_f32_e32 v3, 1.0, v3
	v_floor_f32_e32 v21, v21
	v_fma_f32 v23, v23, s66, 0.5
	v_max_f32_e32 v2, 1.0, v2
	v_floor_f32_e32 v6, v6
	v_rcp_f32_e32 v3, v3
	v_max_f32_e32 v21, 1.0, v21
	v_floor_f32_e32 v23, v23
	v_add_f32_e32 v26, 1.0, v26
	v_cvt_pk_u8_f32 v2, v2, 0, 0
	v_max_f32_e32 v6, 1.0, v6
	v_cvt_pk_u8_f32 v21, v21, 0, 0
	v_fma_f32 v22, v22, s66, 0.5
	v_max_f32_e32 v23, 1.0, v23
	v_rcp_f32_e32 v26, v26
	v_exp_f32_e32 v28, v28
	v_cvt_pk_u8_f32 v2, v6, 1, v2
	v_add_f32_e32 v6, 1.0, v7
	v_exp_f32_e32 v4, v4
	v_floor_f32_e32 v22, v22
	v_cvt_pk_u8_f32 v21, v23, 1, v21
	v_fma_f32 v23, v30, s66, 0.5
	v_fma_f32 v0, v0, s66, 0.5
	v_rcp_f32_e32 v6, v6
	v_max_f32_e32 v22, 1.0, v22
	v_floor_f32_e32 v23, v23
	v_floor_f32_e32 v0, v0
	v_fma_f32 v3, v3, s66, 0.5
	v_cvt_pk_u8_f32 v22, v22, 0, 0
	v_max_f32_e32 v23, 1.0, v23
	v_max_f32_e32 v0, 1.0, v0
	v_floor_f32_e32 v3, v3
	v_cvt_pk_u8_f32 v22, v23, 1, v22
	v_fma_f32 v23, v26, s66, 0.5
	v_add_f32_e32 v26, 1.0, v28
	v_cvt_pk_u8_f32 v0, v0, 0, 0
	v_max_f32_e32 v3, 1.0, v3
	v_add_f32_e32 v4, 1.0, v4
	v_rcp_f32_e32 v26, v26
	v_exp_f32_e32 v27, v27
	v_cvt_pk_u8_f32 v0, v3, 1, v0
	v_fma_f32 v3, v6, s66, 0.5
	v_rcp_f32_e32 v4, v4
	v_exp_f32_e32 v6, v9
	v_floor_f32_e32 v23, v23
	v_floor_f32_e32 v3, v3
	v_max_f32_e32 v23, 1.0, v23
	v_max_f32_e32 v3, 1.0, v3
	v_cvt_pk_u8_f32 v21, v23, 2, v21
	v_fma_f32 v23, v26, s66, 0.5
	v_add_f32_e32 v26, 1.0, v27
	v_cvt_pk_u8_f32 v2, v3, 2, v2
	v_fma_f32 v3, v4, s66, 0.5
	v_add_f32_e32 v4, 1.0, v6
	v_rcp_f32_e32 v26, v26
	v_exp_f32_e32 v27, v29
	v_exp_f32_e32 v11, v11
	v_rcp_f32_e32 v4, v4
	v_exp_f32_e32 v5, v5
	v_floor_f32_e32 v23, v23
	v_floor_f32_e32 v3, v3
	v_max_f32_e32 v23, 1.0, v23
	v_max_f32_e32 v3, 1.0, v3
	v_cvt_pk_u8_f32 v23, v23, 2, v22
	v_fma_f32 v22, v26, s66, 0.5
	v_add_f32_e32 v26, 1.0, v27
	v_add_f32_e32 v11, 1.0, v11
	v_cvt_pk_u8_f32 v0, v3, 2, v0
	v_fma_f32 v3, v4, s66, 0.5
	v_add_f32_e32 v4, 1.0, v5
	v_rcp_f32_e32 v26, v26
	v_rcp_f32_e32 v11, v11
	v_rcp_f32_e32 v4, v4
	v_floor_f32_e32 v22, v22
	v_floor_f32_e32 v3, v3
	v_max_f32_e32 v22, 1.0, v22
	v_max_f32_e32 v3, 1.0, v3
	v_cvt_pk_u8_f32 v22, v22, 3, v21
	v_fma_f32 v21, v26, s66, 0.5
	v_fma_f32 v11, v11, s66, 0.5
	v_cvt_pk_u8_f32 v2, v3, 3, v2
	v_fma_f32 v3, v4, s66, 0.5
	v_floor_f32_e32 v21, v21
	v_floor_f32_e32 v11, v11
	v_floor_f32_e32 v3, v3
	v_max_f32_e32 v21, 1.0, v21
	v_max_f32_e32 v11, 1.0, v11
	v_max_f32_e32 v3, 1.0, v3
	v_cvt_pk_u8_f32 v23, v21, 3, v23
	v_cvt_pk_u8_f32 v11, v11, 3, v14
	v_cvt_pk_u8_f32 v3, v3, 3, v0
	s_andn2_b64 vcc, exec, s[40:41]
	s_mov_b64 s[10:11], -1
	v_mov_b32_e32 v242, v22
	v_mov_b32_e32 v243, v23
	global_store_dwordx4 v[24:25], v[240:243], off
	v_mov_b32_e32 v236, v10
	v_mov_b32_e32 v237, v11
	v_mov_b32_e32 v238, v2
	v_mov_b32_e32 v239, v3
	global_store_dwordx4 v[12:13], v[236:239], off
	s_cbranch_vccnz .LBB0_673
	s_andn2_b64 vcc, exec, s[0:1]
	s_cbranch_vccnz .LBB0_672
	s_barrier
	s_branch .LBB0_672

; __device__ __forceinline__ int fresh_tid() { int t = threadIdx.x; asm volatile("" : "+v"(t)); return t; }
; #define PG8_STAGE(bufoff, gbase, voff) do { _Pragma("unroll") for (int _i = 0; _i < 2; ++_i) \
;         __builtin_amdgcn_global_load_lds((const unsigned*)((const char*)(gbase) + (voff)[_i]), (LAS unsigned*)(lds + (bufoff) + ldsw + _i * 8192), 16, 0, 0); } while (0)
; #define PG8_WAIT_V(n) asm volatile("s_waitcnt vmcnt(" #n ")" ::: "memory")
; template <class Epi, class Sched, int NSEG, int KK, int LDA, int LDB>
; __device__ __forceinline__ void gemm_phase(LAS unsigned char* lds, const Gemm g, const Sched& S, const Epi& E) {
;     const int tid = fresh_tid(), wid = __builtin_amdgcn_readfirstlane(tid >> 6), lane = tid & 63, wr = wid >> 2, wc = wid & 3, fr = lane & 15, fq = lane >> 4;
;     constexpr int nt = KK / BK;
;     unsigned voffA[2], voffB[2];
; #pragma unroll
;     for (int i = 0; i < 2; ++i) { int R, C; stage_rc(tid * 16 + i * 8192, R, C); const int Rb = Epi::PERM ? ((R & ~31) + perm32(R & 31)) : R;
;         voffA[i] = (unsigned)(R * LDA + C) * 2u; voffB[i] = (unsigned)(Rb * LDB + C) * 2u; }
;     constexpr size_t kstep = (size_t)(BK * 2);
;     constexpr size_t hstepA = (size_t)HALF * LDA * 2, hstepB = (size_t)HALF * LDB * 2;
;     constexpr size_t tstepA = 2 * hstepA, tstepB = 2 * hstepB;
;     const unsigned ldsw = (unsigned)wid * 1024u;
;     const int aoff = lds_byte(wr * 64 + fr, fq * 8), boff = lds_byte(wc * 32 + fr, fq * 8);
;     ...
;     Unit cur, nxt; int ui = 0;
;     if (!S.next(0, cur)) return;
;     f32x4 acc[2][2][4][2];
; #pragma unroll
;     for (int a = 0; a < 2; ++a)
; #pragma unroll
;         for (int b = 0; b < 2; ++b)
; #pragma unroll
;             for (int m = 0; m < 4; ++m)
; #pragma unroll
;                 for (int n = 0; n < 2; ++n) acc[a][b][m][n] = (f32x4){0.f, 0.f, 0.f, 0.f};
;     bf16x8 At[4][2], B0[2][2], B1[2][2];
;     const char* cA = PG8_APTR(cur); const char* cB = PG8_BPTR(cur);
;     PG8_STAGE(PG8_SB(0, 0), cB, voffB); PG8_STAGE(PG8_SB(0, 1), cB + hstepB, voffB); PG8_STAGE(PG8_SA(0, 0), cA, voffA); PG8_STAGE(PG8_SA(0, 1), cA + hstepA, voffA);
;     if (wr == 1) PG8_BAR;
;     PG8_WAIT_V(2); PG8_BAR;
;     PG8_STAGE(PG8_SB(1, 0), cB + kstep, voffB); PG8_STAGE(PG8_SA(1, 0), cA + kstep, voffA); PG8_STAGE(PG8_SB(1, 1), cB + hstepB + kstep, voffB);
;     PG8_WAIT_V(6); PG8_BAR;
.LBB0_744:
	s_or_b64 exec, exec, s[0:1]
	v_readlane_b32 s0, v254, 26
	v_mov_b32_e32 v10, v246
	v_readlane_b32 s1, v254, 27
	s_waitcnt lgkmcnt(0)
	s_barrier
	s_mov_b32 s101, 0
	s_and_b64 vcc, exec, s[0:1]
	v_readfirstlane_b32 s8, v10
	s_cbranch_vccnz .LBB0_928
	v_lshlrev_b32_e32 v0, 4, v10
	v_add_u32_e32 v2, 0x2000, v0
	v_ashrrev_i32_e32 v3, 31, v2
	v_lshrrev_b32_e32 v3, 22, v3
	v_add_u32_e32 v3, v2, v3
	v_ashrrev_i32_e32 v6, 10, v3
	v_mul_i32_i24_e32 v3, 0x400, v6
	v_sub_u32_e32 v2, v2, v3
	v_lshrrev_b32_e32 v3, 4, v2
	v_bitop3_b32 v2, v3, v2, 32 bitop3:0x6c
	v_ashrrev_i32_e32 v3, 31, v2
	v_lshrrev_b32_e32 v3, 26, v3
	v_add_u32_e32 v3, v2, v3
	v_lshlrev_b32_e32 v4, 3, v6
	v_ashrrev_i32_e32 v7, 6, v3
	v_and_b32_e32 v4, -16, v4
	v_add_u32_e32 v4, v7, v4
	v_and_b32_e32 v5, 3, v7
	s_mov_b32 s1, 0x3fffe0
	v_lshrrev_b32_e32 v8, 2, v4
	v_lshlrev_b32_e32 v9, 1, v4
	v_and_b32_e32 v3, 0xc0, v3
	v_and_or_b32 v5, v4, s1, v5
	v_and_b32_e32 v8, 4, v8
	v_and_b32_e32 v9, 24, v9
	v_sub_u32_e32 v2, v2, v3
	v_or3_b32 v5, v5, v8, v9
	v_lshlrev_b32_e32 v8, 5, v6
	v_ashrrev_i16_sdwa v2, v248, sext(v2) dst_sel:DWORD dst_unused:UNUSED_PAD src0_sel:DWORD src1_sel:BYTE_0
	v_readlane_b32 s0, v254, 22
	v_and_b32_e32 v8, 32, v8
	v_bfe_i32 v9, v2, 0, 16
	s_add_u32 s23, s0, 0xf00000
	v_readlane_b32 s0, v254, 23
	v_add_u32_e32 v2, v8, v9
	s_addc_u32 s26, s0, 0
	v_lshlrev_b32_e32 v3, 1, v2
	s_movk_i32 s0, 0x1200
	v_lshl_add_u32 v130, v5, 10, v3
	v_mul_lo_u32 v3, v4, s0
	v_add_lshl_u32 v132, v2, v3, 1
	v_bfe_i32 v2, v10, 27, 1
	v_lshrrev_b32_e32 v2, 22, v2
	v_add_u32_e32 v2, v0, v2
	v_and_b32_e32 v2, 0xfffffc00, v2
	v_sub_u32_e32 v0, v0, v2
	v_lshrrev_b32_e32 v2, 4, v0
	v_bitop3_b32 v2, v2, v0, 32 bitop3:0x6c
	v_ashrrev_i32_e32 v0, 31, v0
	v_lshrrev_b32_e32 v0, 26, v0
	v_add_u32_e32 v0, v2, v0
	v_ashrrev_i32_e32 v11, 6, v0
	v_ashrrev_i32_e32 v0, 31, v10
	v_lshrrev_b32_e32 v0, 26, v0
	v_add_u32_e32 v0, v10, v0
	v_ashrrev_i32_e32 v12, 6, v0
	v_lshlrev_b32_e32 v0, 3, v12
	v_and_b32_e32 v0, -16, v0
	v_add_u32_e32 v3, v11, v0
	v_and_b32_e32 v0, 3, v11
	v_lshrrev_b32_e32 v4, 2, v3
	v_lshlrev_b32_e32 v5, 1, v3
	v_and_or_b32 v0, v3, s1, v0
	v_and_b32_e32 v4, 4, v4
	v_and_b32_e32 v5, 24, v5
	v_or3_b32 v0, v0, v4, v5
	v_lshlrev_b32_e32 v4, 5, v12
	v_and_b32_e32 v13, 32, v4
	v_mul_i32_i24_e32 v4, 64, v11
	v_sub_u32_e32 v2, v2, v4
	s_ashr_i32 s9, s8, 6
	v_ashrrev_i16_sdwa v2, v248, sext(v2) dst_sel:DWORD dst_unused:UNUSED_PAD src0_sel:DWORD src1_sel:BYTE_0
	s_ashr_i32 s52, s8, 8
	s_lshl_b32 s53, s9, 10
	v_bfe_i32 v14, v2, 0, 16
	v_mul_lo_u32 v3, v3, s0
	v_readlane_b32 s0, v255, 53
	v_add_u32_e32 v2, v13, v14
	v_readlane_b32 s1, v255, 54
	s_add_u32 s44, s23, s0
	v_lshlrev_b32_e32 v4, 1, v2
	s_addc_u32 s45, s26, s1
	s_add_i32 s54, s53, 0
	v_lshl_add_u32 v0, v0, 10, v4
	s_add_i32 m0, s54, 0x10000
	v_add_lshl_u32 v134, v2, v3, 1
	global_load_lds_dwordx4 v0, s[44:45]
	s_add_i32 m0, s54, 0x12000
	s_add_u32 s0, s44, 0x20000
	global_load_lds_dwordx4 v130, s[44:45]
	s_addc_u32 s1, s45, 0
	s_add_i32 m0, s54, 0x14000
	s_add_i32 s55, s54, 0x2000
	global_load_lds_dwordx4 v0, s[0:1]
	s_add_i32 m0, s54, 0x16000
	s_add_i32 s56, s54, 0x4000
	global_load_lds_dwordx4 v130, s[0:1]
	v_readlane_b32 s0, v255, 57
	s_mov_b32 m0, s54
	v_readlane_b32 s1, v255, 58
	s_add_i32 s57, s54, 0x6000
	v_mov_b32_e32 v131, v1
	s_cmp_eq_u32 s52, 1
	v_lshl_add_u64 v[2:3], s[44:45], 0, v[0:1]
	v_lshl_add_u64 v[4:5], s[44:45], 0, v[130:131]
	global_load_lds_dwordx4 v134, s[0:1]
	s_mov_b32 m0, s55
	s_nop 0
	global_load_lds_dwordx4 v132, s[0:1]
	v_readlane_b32 s0, v255, 59
	s_mov_b32 m0, s56
	v_readlane_b32 s1, v255, 60
	s_nop 4
	global_load_lds_dwordx4 v134, s[0:1]
	s_mov_b32 m0, s57
	s_nop 0
	global_load_lds_dwordx4 v132, s[0:1]
	s_cselect_b64 s[0:1], -1, 0
	s_cmp_lg_u32 s52, 1
	s_cbranch_scc1 .LBB0_747
	s_barrier

; #define PG8_STAGE(bufoff, gbase, voff) do { _Pragma("unroll") for (int _i = 0; _i < 2; ++_i) \
;         __builtin_amdgcn_global_load_lds((const unsigned*)((const char*)(gbase) + (voff)[_i]), (LAS unsigned*)(lds + (bufoff) + ldsw + _i * 8192), 16, 0, 0); } while (0)
; #define PG8_LDA(dst, b, h) do { _Pragma("unroll") for (int m = 0; m < 4; ++m) _Pragma("unroll") for (int k = 0; k < 2; ++k) dst[m][k] = *(const LAS bf16x8*)(lds + PG8_SA(b, h) + aoff + m * 2048 + k * 1024); } while (0)
; #define PG8_LDB(dst, b, h) do { _Pragma("unroll") for (int n = 0; n < 2; ++n) _Pragma("unroll") for (int k = 0; k < 2; ++k) dst[n][k] = *(const LAS bf16x8*)(lds + PG8_SB(b, h) + boff + n * 2048 + k * 1024); } while (0)
; #define PG8_MMA(ai, bj, At, Bt) do { __builtin_amdgcn_s_setprio(1); _Pragma("unroll") for (int m = 0; m < 4; ++m) _Pragma("unroll") for (int n = 0; n < 2; ++n) _Pragma("unroll") for (int k = 0; k < 2; ++k) \
;         acc[ai][bj][m][n] = __builtin_amdgcn_mfma_f32_16x16x32_bf16(Bt[n][k], At[m][k], acc[ai][bj][m][n], 0, 0, 0); __builtin_amdgcn_s_setprio(0); } while (0)
; #define PG8_WAIT_V(n) asm volatile("s_waitcnt vmcnt(" #n ")" ::: "memory")
; template <class Epi, class Sched, int NSEG, int KK, int LDA, int LDB>
; __device__ __forceinline__ void gemm_phase(LAS unsigned char* lds, const Gemm g, const Sched& S, const Epi& E) {
;     ...
;         const bool has_next = S.next(ui + 1, nxt);
;         const char* nA = has_next ? PG8_APTR(nxt) : cA; const char* nB = has_next ? PG8_BPTR(nxt) : cB;
;         for (int t = 0; t < nt; t += 2) {
;             const bool last = (t == nt - 2);
;             const char* a1 = cA + (size_t)(t + 1) * kstep;
;             const char* a2 = last ? nA : cA + (size_t)(t + 2) * kstep; const char* b2 = last ? nB : cB + (size_t)(t + 2) * kstep;
;             const char* a3 = a2 + kstep; const char* b3 = b2 + kstep;
;             PG8_LDB(B0, 0, 0); PG8_LDB(B1, 0, 1); PG8_SCHED; PG8_LDA(At, 0, 0); PG8_STAGE(PG8_SA(1, 1), a1 + hstepA, voffA);
;             PG8_WAIT_V(8); PG8_WAIT_L(0); PG8_BAR; PG8_MMA(0, 0, At, B0); PG8_MMA(0, 1, At, B1); PG8_BAR; PG8_SCHED;
;             PG8_LDA(At, 0, 1); PG8_STAGE(PG8_SB(0, 0), b2, voffB); PG8_STAGE(PG8_SB(0, 1), b2 + hstepB, voffB); PG8_STAGE(PG8_SA(0, 0), a2, voffA);
;             PG8_WAIT_V(8); PG8_WAIT_L(0); PG8_BAR; PG8_MMA(1, 0, At, B0); PG8_MMA(1, 1, At, B1); PG8_BAR; PG8_SCHED;
.LBB0_759:
	s_add_u32 s42, s8, 0x100
	s_addc_u32 s43, s9, 0
	s_add_i32 s83, 0, 0x10000
	s_cmp_eq_u32 s77, 4
	s_cselect_b32 s45, s25, s43
	s_cselect_b32 s44, s24, s42
	s_cselect_b32 s11, s38, s63
	s_cselect_b32 s10, s39, s49
	s_add_i32 s91, 0, 0x14000
	v_add_u32_e32 v152, s83, v244
	v_add_u32_e32 v172, s91, v244
	ds_read_b128 v[140:143], v152
	ds_read_b128 v[144:147], v152 offset:1024
	ds_read_b128 v[148:151], v152 offset:2048
	ds_read_b128 v[152:155], v152 offset:3072
	ds_read_b128 v[156:159], v172
	ds_read_b128 v[160:163], v172 offset:1024
	ds_read_b128 v[164:167], v172 offset:2048
	ds_read_b128 v[176:179], v172 offset:3072
	v_lshl_add_u64 v[212:213], s[8:9], 0, v[136:137]
	s_add_i32 m0, s54, 0xc000
	ds_read_b128 v[180:183], v245
	ds_read_b128 v[184:187], v245 offset:1024
	ds_read_b128 v[188:191], v245 offset:2048
	ds_read_b128 v[192:195], v245 offset:3072
	ds_read_b128 v[196:199], v245 offset:4096
	ds_read_b128 v[200:203], v245 offset:5120
	ds_read_b128 v[204:207], v245 offset:6144
	ds_read_b128 v[208:211], v245 offset:7168
	global_load_lds_dwordx4 v[212:213], off
	v_lshl_add_u64 v[212:213], s[8:9], 0, v[138:139]
	s_add_i32 m0, s54, 0xe000
	s_nop 0
	global_load_lds_dwordx4 v[212:213], off
	s_cmp_lg_u32 s101, 0
	s_cbranch_scc1 .Lskw_2_1
	s_waitcnt vmcnt(8)
.Lskw_2_1:
	s_waitcnt lgkmcnt(0)
	s_barrier
	s_setprio 1
	s_waitcnt lgkmcnt(0)
	v_mfma_f32_16x16x32_bf16 v[126:129], v[140:143], v[180:183], v[126:129]
	v_mfma_f32_16x16x32_bf16 v[122:125], v[148:151], v[180:183], v[122:125]
	v_mfma_f32_16x16x32_bf16 v[118:121], v[140:143], v[188:191], v[118:121]
	v_mfma_f32_16x16x32_bf16 v[114:117], v[148:151], v[188:191], v[114:117]
	v_mfma_f32_16x16x32_bf16 v[110:113], v[140:143], v[196:199], v[110:113]
	v_mfma_f32_16x16x32_bf16 v[106:109], v[148:151], v[196:199], v[106:109]
	v_mfma_f32_16x16x32_bf16 v[102:105], v[140:143], v[204:207], v[102:105]
	v_mfma_f32_16x16x32_bf16 v[98:101], v[148:151], v[204:207], v[98:101]
	v_mfma_f32_16x16x32_bf16 v[126:129], v[144:147], v[184:187], v[126:129]
	v_mfma_f32_16x16x32_bf16 v[122:125], v[152:155], v[184:187], v[122:125]
	v_mfma_f32_16x16x32_bf16 v[118:121], v[144:147], v[192:195], v[118:121]
	v_mfma_f32_16x16x32_bf16 v[114:117], v[152:155], v[192:195], v[114:117]
	v_mfma_f32_16x16x32_bf16 v[110:113], v[144:147], v[200:203], v[110:113]
	v_mfma_f32_16x16x32_bf16 v[106:109], v[152:155], v[200:203], v[106:109]
	v_mfma_f32_16x16x32_bf16 v[102:105], v[144:147], v[208:211], v[102:105]
	v_mfma_f32_16x16x32_bf16 v[98:101], v[152:155], v[208:211], v[98:101]
	s_setprio 0
	s_setprio 1
	v_mfma_f32_16x16x32_bf16 v[94:97], v[156:159], v[180:183], v[94:97]
	v_mfma_f32_16x16x32_bf16 v[90:93], v[164:167], v[180:183], v[90:93]
	v_mfma_f32_16x16x32_bf16 v[86:89], v[156:159], v[188:191], v[86:89]
	v_mfma_f32_16x16x32_bf16 v[82:85], v[164:167], v[188:191], v[82:85]
	v_mfma_f32_16x16x32_bf16 v[78:81], v[156:159], v[196:199], v[78:81]
	v_mfma_f32_16x16x32_bf16 v[74:77], v[164:167], v[196:199], v[74:77]
	v_mfma_f32_16x16x32_bf16 v[70:73], v[156:159], v[204:207], v[70:73]
	v_mfma_f32_16x16x32_bf16 v[66:69], v[164:167], v[204:207], v[66:69]
	v_mfma_f32_16x16x32_bf16 v[94:97], v[160:163], v[184:187], v[94:97]
	v_mfma_f32_16x16x32_bf16 v[90:93], v[176:179], v[184:187], v[90:93]
	v_mfma_f32_16x16x32_bf16 v[86:89], v[160:163], v[192:195], v[86:89]
	v_mfma_f32_16x16x32_bf16 v[82:85], v[176:179], v[192:195], v[82:85]
	v_mfma_f32_16x16x32_bf16 v[78:81], v[160:163], v[200:203], v[78:81]
	v_mfma_f32_16x16x32_bf16 v[74:77], v[176:179], v[200:203], v[74:77]
	v_mfma_f32_16x16x32_bf16 v[70:73], v[160:163], v[208:211], v[70:73]
	v_mfma_f32_16x16x32_bf16 v[66:69], v[176:179], v[208:211], v[66:69]
	s_setprio 0
	s_barrier
	s_add_i32 s8, s83, s53
	v_lshl_add_u64 v[212:213], s[10:11], 0, v[0:1]
	s_mov_b32 m0, s8
	ds_read_b128 v[180:183], v245 offset:16384
	ds_read_b128 v[184:187], v245 offset:17408
	ds_read_b128 v[188:191], v245 offset:18432
	ds_read_b128 v[192:195], v245 offset:19456
	ds_read_b128 v[196:199], v245 offset:20480
	ds_read_b128 v[200:203], v245 offset:21504
	ds_read_b128 v[204:207], v245 offset:22528
	ds_read_b128 v[208:211], v245 offset:23552
	global_load_lds_dwordx4 v[212:213], off
	s_add_i32 m0, s8, 0x2000
	s_add_u32 s8, s10, 0x20000
	v_lshl_add_u64 v[214:215], s[10:11], 0, v[130:131]
	s_addc_u32 s9, s11, 0
	s_add_i32 s83, s91, s53
	global_load_lds_dwordx4 v[214:215], off
	v_lshl_add_u64 v[216:217], s[8:9], 0, v[0:1]
	s_mov_b32 m0, s83
	v_lshl_add_u64 v[218:219], s[44:45], 0, v[132:133]
	global_load_lds_dwordx4 v[216:217], off
	v_lshl_add_u64 v[216:217], s[8:9], 0, v[130:131]
	s_add_i32 m0, s83, 0x2000
	s_nop 0
	global_load_lds_dwordx4 v[216:217], off
	v_lshl_add_u64 v[216:217], s[44:45], 0, v[134:135]
	s_mov_b32 m0, s54
	s_nop 0
	global_load_lds_dwordx4 v[216:217], off
	s_mov_b32 m0, s55
	s_nop 0
	global_load_lds_dwordx4 v[218:219], off
	s_cmp_lg_u32 s101, 0
	s_cbranch_scc1 .Lskw_2_2
	s_waitcnt vmcnt(8)
; #define PG8_STAGE(bufoff, gbase, voff) do { _Pragma("unroll") for (int _i = 0; _i < 2; ++_i) \
;         __builtin_amdgcn_global_load_lds((const unsigned*)((const char*)(gbase) + (voff)[_i]), (LAS unsigned*)(lds + (bufoff) + ldsw + _i * 8192), 16, 0, 0); } while (0)
; #define PG8_LDA(dst, b, h) do { _Pragma("unroll") for (int m = 0; m < 4; ++m) _Pragma("unroll") for (int k = 0; k < 2; ++k) dst[m][k] = *(const LAS bf16x8*)(lds + PG8_SA(b, h) + aoff + m * 2048 + k * 1024); } while (0)
; #define PG8_LDB(dst, b, h) do { _Pragma("unroll") for (int n = 0; n < 2; ++n) _Pragma("unroll") for (int k = 0; k < 2; ++k) dst[n][k] = *(const LAS bf16x8*)(lds + PG8_SB(b, h) + boff + n * 2048 + k * 1024); } while (0)
; #define PG8_MMA(ai, bj, At, Bt) do { __builtin_amdgcn_s_setprio(1); _Pragma("unroll") for (int m = 0; m < 4; ++m) _Pragma("unroll") for (int n = 0; n < 2; ++n) _Pragma("unroll") for (int k = 0; k < 2; ++k) \
;         acc[ai][bj][m][n] = __builtin_amdgcn_mfma_f32_16x16x32_bf16(Bt[n][k], At[m][k], acc[ai][bj][m][n], 0, 0, 0); __builtin_amdgcn_s_setprio(0); } while (0)
; #define PG8_WAIT_V(n) asm volatile("s_waitcnt vmcnt(" #n ")" ::: "memory")
; #define PG8_WAIT_L(n) asm volatile("s_waitcnt lgkmcnt(" #n ")" ::: "memory")
; #define PG8_BAR __builtin_amdgcn_s_barrier()
; #define PG8_SCHED __builtin_amdgcn_sched_barrier(0)
; template <class Epi, class Sched, int NSEG, int KK, int LDA, int LDB>
; __device__ __forceinline__ void gemm_phase(LAS unsigned char* lds, const Gemm g, const Sched& S, const Epi& E) {
;     ...
;             PG8_WAIT_V(8); PG8_WAIT_L(0); PG8_BAR; PG8_MMA(1, 0, At, B0); PG8_MMA(1, 1, At, B1); PG8_BAR; PG8_SCHED;
;             PG8_LDB(B0, 1, 0); PG8_LDB(B1, 1, 1); PG8_SCHED; PG8_LDA(At, 1, 0); PG8_STAGE(PG8_SA(0, 1), a2 + hstepA, voffA);
;             PG8_WAIT_V(8); PG8_WAIT_L(0); PG8_BAR; PG8_MMA(0, 0, At, B0); PG8_MMA(0, 1, At, B1); PG8_BAR; PG8_SCHED;
.Lskw_2_2:
	s_mov_b32 s101, 0
	s_waitcnt lgkmcnt(0)
	s_barrier
	s_setprio 1
	s_waitcnt lgkmcnt(0)
	v_mfma_f32_16x16x32_bf16 v[62:65], v[140:143], v[180:183], v[62:65]
	v_mfma_f32_16x16x32_bf16 v[58:61], v[148:151], v[180:183], v[58:61]
	v_mfma_f32_16x16x32_bf16 v[54:57], v[140:143], v[188:191], v[54:57]
	v_mfma_f32_16x16x32_bf16 v[50:53], v[148:151], v[188:191], v[50:53]
	v_mfma_f32_16x16x32_bf16 v[46:49], v[140:143], v[196:199], v[46:49]
	v_mfma_f32_16x16x32_bf16 v[42:45], v[148:151], v[196:199], v[42:45]
	v_mfma_f32_16x16x32_bf16 v[38:41], v[140:143], v[204:207], v[38:41]
	v_mfma_f32_16x16x32_bf16 v[34:37], v[148:151], v[204:207], v[34:37]
	v_mfma_f32_16x16x32_bf16 v[62:65], v[144:147], v[184:187], v[62:65]
	v_mfma_f32_16x16x32_bf16 v[58:61], v[152:155], v[184:187], v[58:61]
	v_mfma_f32_16x16x32_bf16 v[54:57], v[144:147], v[192:195], v[54:57]
	v_mfma_f32_16x16x32_bf16 v[50:53], v[152:155], v[192:195], v[50:53]
	v_mfma_f32_16x16x32_bf16 v[46:49], v[144:147], v[200:203], v[46:49]
	v_mfma_f32_16x16x32_bf16 v[42:45], v[152:155], v[200:203], v[42:45]
	v_mfma_f32_16x16x32_bf16 v[38:41], v[144:147], v[208:211], v[38:41]
	v_mfma_f32_16x16x32_bf16 v[34:37], v[152:155], v[208:211], v[34:37]
	s_setprio 0
	s_setprio 1
	v_mfma_f32_16x16x32_bf16 v[30:33], v[156:159], v[180:183], v[30:33]
	v_mfma_f32_16x16x32_bf16 v[26:29], v[164:167], v[180:183], v[26:29]
	v_mfma_f32_16x16x32_bf16 v[22:25], v[156:159], v[188:191], v[22:25]
	v_mfma_f32_16x16x32_bf16 v[18:21], v[164:167], v[188:191], v[18:21]
	v_mfma_f32_16x16x32_bf16 v[14:17], v[156:159], v[196:199], v[14:17]
	v_mfma_f32_16x16x32_bf16 v[10:13], v[164:167], v[196:199], v[10:13]
	v_mfma_f32_16x16x32_bf16 v[6:9], v[156:159], v[204:207], v[6:9]
	v_mfma_f32_16x16x32_bf16 v[2:5], v[164:167], v[204:207], v[2:5]
	v_mfma_f32_16x16x32_bf16 v[30:33], v[160:163], v[184:187], v[30:33]
	v_mfma_f32_16x16x32_bf16 v[26:29], v[176:179], v[184:187], v[26:29]
	v_mfma_f32_16x16x32_bf16 v[22:25], v[160:163], v[192:195], v[22:25]
	v_mfma_f32_16x16x32_bf16 v[18:21], v[176:179], v[192:195], v[18:21]
	v_mfma_f32_16x16x32_bf16 v[14:17], v[160:163], v[200:203], v[14:17]
	v_mfma_f32_16x16x32_bf16 v[10:13], v[176:179], v[200:203], v[10:13]
	v_mfma_f32_16x16x32_bf16 v[6:9], v[160:163], v[208:211], v[6:9]
	v_mfma_f32_16x16x32_bf16 v[2:5], v[176:179], v[208:211], v[2:5]
	s_setprio 0
	s_barrier
	s_add_i32 s83, 0, 0x18000
	s_add_i32 s91, 0, 0x1c000
	v_add_u32_e32 v152, s83, v244
	v_add_u32_e32 v172, s91, v244
	ds_read_b128 v[140:143], v152
	ds_read_b128 v[144:147], v152 offset:1024
	ds_read_b128 v[148:151], v152 offset:2048
	ds_read_b128 v[152:155], v152 offset:3072
	ds_read_b128 v[156:159], v172
	ds_read_b128 v[160:163], v172 offset:1024
	ds_read_b128 v[164:167], v172 offset:2048
	ds_read_b128 v[176:179], v172 offset:3072
	s_add_u32 s8, s44, 0x120000
	s_addc_u32 s9, s45, 0
	s_mov_b32 m0, s56
	v_lshl_add_u64 v[220:221], s[8:9], 0, v[134:135]
	ds_read_b128 v[180:183], v245 offset:32768
	ds_read_b128 v[184:187], v245 offset:33792
	ds_read_b128 v[188:191], v245 offset:34816
	ds_read_b128 v[192:195], v245 offset:35840
	ds_read_b128 v[196:199], v245 offset:36864
	ds_read_b128 v[200:203], v245 offset:37888
	ds_read_b128 v[204:207], v245 offset:38912
	ds_read_b128 v[208:211], v245 offset:39936
	global_load_lds_dwordx4 v[220:221], off
	v_lshl_add_u64 v[220:221], s[8:9], 0, v[132:133]
	s_mov_b32 m0, s57
	s_nop 0
	global_load_lds_dwordx4 v[220:221], off
	s_waitcnt vmcnt(8)
	s_waitcnt lgkmcnt(0)
	s_barrier
	s_setprio 1
	s_waitcnt lgkmcnt(0)
	v_mfma_f32_16x16x32_bf16 v[126:129], v[140:143], v[180:183], v[126:129]
	v_mfma_f32_16x16x32_bf16 v[122:125], v[148:151], v[180:183], v[122:125]
	v_mfma_f32_16x16x32_bf16 v[118:121], v[140:143], v[188:191], v[118:121]
	v_mfma_f32_16x16x32_bf16 v[114:117], v[148:151], v[188:191], v[114:117]
	v_mfma_f32_16x16x32_bf16 v[110:113], v[140:143], v[196:199], v[110:113]
	v_mfma_f32_16x16x32_bf16 v[106:109], v[148:151], v[196:199], v[106:109]
	v_mfma_f32_16x16x32_bf16 v[102:105], v[140:143], v[204:207], v[102:105]
	v_mfma_f32_16x16x32_bf16 v[98:101], v[148:151], v[204:207], v[98:101]
	v_mfma_f32_16x16x32_bf16 v[126:129], v[144:147], v[184:187], v[126:129]
	v_mfma_f32_16x16x32_bf16 v[122:125], v[152:155], v[184:187], v[122:125]
	v_mfma_f32_16x16x32_bf16 v[118:121], v[144:147], v[192:195], v[118:121]
	v_mfma_f32_16x16x32_bf16 v[114:117], v[152:155], v[192:195], v[114:117]
	v_mfma_f32_16x16x32_bf16 v[110:113], v[144:147], v[200:203], v[110:113]
	v_mfma_f32_16x16x32_bf16 v[106:109], v[152:155], v[200:203], v[106:109]
	v_mfma_f32_16x16x32_bf16 v[102:105], v[144:147], v[208:211], v[102:105]
	v_mfma_f32_16x16x32_bf16 v[98:101], v[152:155], v[208:211], v[98:101]
	s_setprio 0
	s_setprio 1
	v_mfma_f32_16x16x32_bf16 v[94:97], v[156:159], v[180:183], v[94:97]
	v_mfma_f32_16x16x32_bf16 v[90:93], v[164:167], v[180:183], v[90:93]
	v_mfma_f32_16x16x32_bf16 v[86:89], v[156:159], v[188:191], v[86:89]
	v_mfma_f32_16x16x32_bf16 v[82:85], v[164:167], v[188:191], v[82:85]
	v_mfma_f32_16x16x32_bf16 v[78:81], v[156:159], v[196:199], v[78:81]
	v_mfma_f32_16x16x32_bf16 v[74:77], v[164:167], v[196:199], v[74:77]
	v_mfma_f32_16x16x32_bf16 v[70:73], v[156:159], v[204:207], v[70:73]
	v_mfma_f32_16x16x32_bf16 v[66:69], v[164:167], v[204:207], v[66:69]
	v_mfma_f32_16x16x32_bf16 v[94:97], v[160:163], v[184:187], v[94:97]
	v_mfma_f32_16x16x32_bf16 v[90:93], v[176:179], v[184:187], v[90:93]
	v_mfma_f32_16x16x32_bf16 v[86:89], v[160:163], v[192:195], v[86:89]
	v_mfma_f32_16x16x32_bf16 v[82:85], v[176:179], v[192:195], v[82:85]
	v_mfma_f32_16x16x32_bf16 v[78:81], v[160:163], v[200:203], v[78:81]
	v_mfma_f32_16x16x32_bf16 v[74:77], v[176:179], v[200:203], v[74:77]
	v_mfma_f32_16x16x32_bf16 v[70:73], v[160:163], v[208:211], v[70:73]
	v_mfma_f32_16x16x32_bf16 v[66:69], v[176:179], v[208:211], v[66:69]
	s_setprio 0
	s_barrier
; #define PG8_STAGE(bufoff, gbase, voff) do { _Pragma("unroll") for (int _i = 0; _i < 2; ++_i) \
;         __builtin_amdgcn_global_load_lds((const unsigned*)((const char*)(gbase) + (voff)[_i]), (LAS unsigned*)(lds + (bufoff) + ldsw + _i * 8192), 16, 0, 0); } while (0)
; #define PG8_LDA(dst, b, h) do { _Pragma("unroll") for (int m = 0; m < 4; ++m) _Pragma("unroll") for (int k = 0; k < 2; ++k) dst[m][k] = *(const LAS bf16x8*)(lds + PG8_SA(b, h) + aoff + m * 2048 + k * 1024); } while (0)
; #define PG8_MMA(ai, bj, At, Bt) do { __builtin_amdgcn_s_setprio(1); _Pragma("unroll") for (int m = 0; m < 4; ++m) _Pragma("unroll") for (int n = 0; n < 2; ++n) _Pragma("unroll") for (int k = 0; k < 2; ++k) \
;         acc[ai][bj][m][n] = __builtin_amdgcn_mfma_f32_16x16x32_bf16(Bt[n][k], At[m][k], acc[ai][bj][m][n], 0, 0, 0); __builtin_amdgcn_s_setprio(0); } while (0)
; #define PG8_WAIT_V(n) asm volatile("s_waitcnt vmcnt(" #n ")" ::: "memory")
; #define PG8_WAIT_L(n) asm volatile("s_waitcnt lgkmcnt(" #n ")" ::: "memory")
; #define PG8_BAR __builtin_amdgcn_s_barrier()
; #define PG8_SCHED __builtin_amdgcn_sched_barrier(0)
; template <class Epi, class Sched, int NSEG, int KK, int LDA, int LDB>
; __device__ __forceinline__ void gemm_phase(LAS unsigned char* lds, const Gemm g, const Sched& S, const Epi& E) {
;     ...
;             PG8_LDA(At, 1, 1); PG8_STAGE(PG8_SB(1, 0), b3, voffB); PG8_STAGE(PG8_SB(1, 1), b3 + hstepB, voffB); PG8_STAGE(PG8_SA(1, 0), a3, voffA);
;             PG8_WAIT_V(8); PG8_WAIT_L(0); PG8_BAR; PG8_MMA(1, 0, At, B0); PG8_MMA(1, 1, At, B1); PG8_BAR; PG8_SCHED;
;         }
;         if (wr == 0) PG8_BAR;
	s_add_i32 s8, s83, s53
	v_lshl_add_u64 v[212:213], v[212:213], 0, s[28:29]
	s_mov_b32 m0, s8
	ds_read_b128 v[180:183], v245 offset:49152
	ds_read_b128 v[184:187], v245 offset:50176
	ds_read_b128 v[188:191], v245 offset:51200
	ds_read_b128 v[192:195], v245 offset:52224
	ds_read_b128 v[196:199], v245 offset:53248
	ds_read_b128 v[200:203], v245 offset:54272
	ds_read_b128 v[204:207], v245 offset:55296
	ds_read_b128 v[208:211], v245 offset:56320
	global_load_lds_dwordx4 v[212:213], off
	s_add_i32 m0, s8, 0x2000
	s_add_u32 s8, s10, 0x20080
	v_lshl_add_u64 v[212:213], v[214:215], 0, s[28:29]
	s_addc_u32 s9, s11, 0
	s_add_i32 s10, s91, s53
	global_load_lds_dwordx4 v[212:213], off
	v_lshl_add_u64 v[212:213], s[8:9], 0, v[0:1]
	s_mov_b32 m0, s10
	s_nop 0
	global_load_lds_dwordx4 v[212:213], off
	v_lshl_add_u64 v[212:213], s[8:9], 0, v[130:131]
	s_add_i32 m0, s10, 0x2000
	s_nop 0
	global_load_lds_dwordx4 v[212:213], off
	v_lshl_add_u64 v[212:213], v[216:217], 0, s[28:29]
	s_mov_b32 m0, s59
	s_nop 0
	global_load_lds_dwordx4 v[212:213], off
	v_lshl_add_u64 v[212:213], v[218:219], 0, s[28:29]
	s_mov_b32 m0, s60
	s_nop 0
	global_load_lds_dwordx4 v[212:213], off
	s_waitcnt vmcnt(8)
	s_waitcnt lgkmcnt(0)
	s_barrier
	s_setprio 1
	s_waitcnt lgkmcnt(0)
	v_mfma_f32_16x16x32_bf16 v[62:65], v[140:143], v[180:183], v[62:65]
	v_mfma_f32_16x16x32_bf16 v[58:61], v[148:151], v[180:183], v[58:61]
	v_mfma_f32_16x16x32_bf16 v[54:57], v[140:143], v[188:191], v[54:57]
	v_mfma_f32_16x16x32_bf16 v[50:53], v[148:151], v[188:191], v[50:53]
	v_mfma_f32_16x16x32_bf16 v[46:49], v[140:143], v[196:199], v[46:49]
	v_mfma_f32_16x16x32_bf16 v[42:45], v[148:151], v[196:199], v[42:45]
	v_mfma_f32_16x16x32_bf16 v[38:41], v[140:143], v[204:207], v[38:41]
	v_mfma_f32_16x16x32_bf16 v[34:37], v[148:151], v[204:207], v[34:37]
	v_mfma_f32_16x16x32_bf16 v[62:65], v[144:147], v[184:187], v[62:65]
	v_mfma_f32_16x16x32_bf16 v[58:61], v[152:155], v[184:187], v[58:61]
	v_mfma_f32_16x16x32_bf16 v[54:57], v[144:147], v[192:195], v[54:57]
	v_mfma_f32_16x16x32_bf16 v[50:53], v[152:155], v[192:195], v[50:53]
	v_mfma_f32_16x16x32_bf16 v[46:49], v[144:147], v[200:203], v[46:49]
	v_mfma_f32_16x16x32_bf16 v[42:45], v[152:155], v[200:203], v[42:45]
	v_mfma_f32_16x16x32_bf16 v[38:41], v[144:147], v[208:211], v[38:41]
	v_mfma_f32_16x16x32_bf16 v[34:37], v[152:155], v[208:211], v[34:37]
	s_setprio 0
	s_setprio 1
	v_mfma_f32_16x16x32_bf16 v[30:33], v[156:159], v[180:183], v[30:33]
	v_mfma_f32_16x16x32_bf16 v[26:29], v[164:167], v[180:183], v[26:29]
	v_mfma_f32_16x16x32_bf16 v[22:25], v[156:159], v[188:191], v[22:25]
	v_mfma_f32_16x16x32_bf16 v[18:21], v[164:167], v[188:191], v[18:21]
	v_mfma_f32_16x16x32_bf16 v[14:17], v[156:159], v[196:199], v[14:17]
	v_mfma_f32_16x16x32_bf16 v[10:13], v[164:167], v[196:199], v[10:13]
	v_mfma_f32_16x16x32_bf16 v[6:9], v[156:159], v[204:207], v[6:9]
	v_mfma_f32_16x16x32_bf16 v[2:5], v[164:167], v[204:207], v[2:5]
	v_mfma_f32_16x16x32_bf16 v[30:33], v[160:163], v[184:187], v[30:33]
	v_mfma_f32_16x16x32_bf16 v[26:29], v[176:179], v[184:187], v[26:29]
	v_mfma_f32_16x16x32_bf16 v[22:25], v[160:163], v[192:195], v[22:25]
	v_mfma_f32_16x16x32_bf16 v[18:21], v[176:179], v[192:195], v[18:21]
	v_mfma_f32_16x16x32_bf16 v[14:17], v[160:163], v[200:203], v[14:17]
	v_mfma_f32_16x16x32_bf16 v[10:13], v[176:179], v[200:203], v[10:13]
	v_mfma_f32_16x16x32_bf16 v[6:9], v[160:163], v[208:211], v[6:9]
	v_mfma_f32_16x16x32_bf16 v[2:5], v[176:179], v[208:211], v[2:5]
	s_setprio 0
	s_barrier
	s_add_i32 s77, s77, 2
	s_add_u32 s49, s49, 0x100
	s_addc_u32 s63, s63, 0
	s_cmp_gt_u32 s77, 5
	s_mov_b64 s[8:9], s[42:43]
	s_cbranch_scc0 .LBB0_759
	s_mov_b32 s101, 1
	s_and_b64 vcc, exec, s[46:47]
	s_cbranch_vccz .LBB0_762
	s_barrier

;     __device__ __forceinline__ void operator()(f32x4 (&acc)[2][2][4][2], const Unit& u, int wr, int wc, int fr, int fq) const {
;         const int row0 = u.pm * BM + wr * 64 + fr;
;         const int seg = u.seg;
;         const int gnum = EpiBf16<1>::gate_zcol(4 * seg + u.pn) * 2 + wc * 32 + 8 * fq;
;         const int gden = EpiBf16<1>::gate_zcol(4 * (seg < 2 ? seg + 1 : 2) + u.pn) * 2 + wc * 32 + 8 * fq;
;         const int col0 = u.pn * BM + wc * 32 + 8 * fq;
;         const unsigned char* Zb = (const unsigned char*)Zg;
;         u32x2 gnv[2][4][2], gdv[2][4][2];
; #pragma unroll
;         for (int ai = 0; ai < 2; ++ai)
; #pragma unroll
;             for (int m = 0; m < 4; ++m) { const size_t r = (size_t)(row0 + ai * HALF + m * 16);
; #pragma unroll
;                 for (int bj = 0; bj < 2; ++bj) { gnv[ai][m][bj] = *(const u32x2*)(Zb + r * (ZLD * 2) + gnum + bj * HALF);
;                     gdv[ai][m][bj] = (seg < 2) ? *(const u32x2*)(Zb + r * (ZLD * 2) + gden + bj * HALF) : (u32x2){0u, 0u}; } }
.LBB0_794:
	v_lshrrev_b32_e32 v140, 1, v141
	s_lshl_b32 s38, s10, 5
	v_and_b32_e32 v157, 24, v140
	v_or_b32_e32 v144, s38, v157
	v_lshlrev_b32_e32 v144, 1, v144
	s_cmp_lt_i32 s13, 2
	v_lshl_add_u32 v140, s11, 1, v144
	s_cselect_b64 s[10:11], -1, 0
	s_cmp_gt_i32 s13, 1
	s_cselect_b64 s[8:9], -1, 0
	s_lshl_b32 s33, s33, 8
	s_lshl_b32 s39, s39, 6
	s_add_i32 s39, s39, s33
	v_and_or_b32 v226, v141, 15, s39
	v_mov_b64_e32 v[142:143], s[68:69]
	v_ashrrev_i32_e32 v141, 31, v140
	v_mad_i64_i32 v[142:143], s[44:45], v226, s74, v[142:143]
	v_lshl_add_u64 v[148:149], v[142:143], 0, v[140:141]
	global_load_dwordx2 v[228:229], v[148:149], off
	v_lshl_add_u32 v144, s42, 1, v144
	v_ashrrev_i32_e32 v145, 31, v144
	v_lshl_add_u64 v[146:147], v[142:143], 0, v[144:145]
	v_mov_b32_e32 v222, 0
	s_and_b64 vcc, exec, s[8:9]
	v_mov_b32_e32 v142, 0
	v_mov_b32_e32 v143, 0
	s_cbranch_vccnz .LBB0_796
	global_load_dwordx2 v[142:143], v[146:147], off
.LBB0_796:
	global_load_dwordx2 v[224:225], v[148:149], off offset:8
	v_cndmask_b32_e64 v148, 0, 1, s[10:11]
	v_cmp_ne_u32_e64 s[42:43], 1, v148
	s_andn2_b64 vcc, exec, s[10:11]
	v_mov_b32_e32 v223, 0
	s_cbranch_vccnz .LBB0_798
	global_load_dwordx2 v[222:223], v[146:147], off offset:8

;     __device__ __forceinline__ void operator()(f32x4 (&acc)[2][2][4][2], const Unit& u, int wr, int wc, int fr, int fq) const {
;     ...
;             for (int m = 0; m < 4; ++m) { const size_t r = (size_t)(row0 + ai * HALF + m * 16);
; #pragma unroll
;                 for (int bj = 0; bj < 2; ++bj) { gnv[ai][m][bj] = *(const u32x2*)(Zb + r * (ZLD * 2) + gnum + bj * HALF);
;                     gdv[ai][m][bj] = (seg < 2) ? *(const u32x2*)(Zb + r * (ZLD * 2) + gden + bj * HALF) : (u32x2){0u, 0u}; } }
.LBB0_800:
	global_load_dwordx2 v[214:215], v[148:149], off offset:8
	s_and_b64 vcc, exec, s[42:43]
	v_mov_b32_e32 v213, 0
	s_cbranch_vccnz .LBB0_802
	global_load_dwordx2 v[212:213], v[146:147], off offset:8

;     __device__ __forceinline__ void operator()(f32x4 (&acc)[2][2][4][2], const Unit& u, int wr, int wc, int fr, int fq) const {
;     ...
;             for (int m = 0; m < 4; ++m) { const size_t r = (size_t)(row0 + ai * HALF + m * 16);
; #pragma unroll
;                 for (int bj = 0; bj < 2; ++bj) { gnv[ai][m][bj] = *(const u32x2*)(Zb + r * (ZLD * 2) + gnum + bj * HALF);
;                     gdv[ai][m][bj] = (seg < 2) ? *(const u32x2*)(Zb + r * (ZLD * 2) + gden + bj * HALF) : (u32x2){0u, 0u}; } }
.LBB0_804:
	global_load_dwordx2 v[204:205], v[148:149], off offset:8
	s_and_b64 vcc, exec, s[42:43]
	v_mov_b32_e32 v203, 0
	s_cbranch_vccnz .LBB0_806
	global_load_dwordx2 v[202:203], v[146:147], off offset:8

;     __device__ __forceinline__ void operator()(f32x4 (&acc)[2][2][4][2], const Unit& u, int wr, int wc, int fr, int fq) const {
;     ...
;             for (int m = 0; m < 4; ++m) { const size_t r = (size_t)(row0 + ai * HALF + m * 16);
; #pragma unroll
;                 for (int bj = 0; bj < 2; ++bj) { gnv[ai][m][bj] = *(const u32x2*)(Zb + r * (ZLD * 2) + gnum + bj * HALF);
;                     gdv[ai][m][bj] = (seg < 2) ? *(const u32x2*)(Zb + r * (ZLD * 2) + gden + bj * HALF) : (u32x2){0u, 0u}; } }
.LBB0_808:
	global_load_dwordx2 v[194:195], v[148:149], off offset:8
	s_and_b64 vcc, exec, s[42:43]
	v_mov_b32_e32 v193, 0
	s_cbranch_vccnz .LBB0_810
	global_load_dwordx2 v[192:193], v[146:147], off offset:8

;     __device__ __forceinline__ void operator()(f32x4 (&acc)[2][2][4][2], const Unit& u, int wr, int wc, int fr, int fq) const {
;     ...
;             for (int m = 0; m < 4; ++m) { const size_t r = (size_t)(row0 + ai * HALF + m * 16);
; #pragma unroll
;                 for (int bj = 0; bj < 2; ++bj) { gnv[ai][m][bj] = *(const u32x2*)(Zb + r * (ZLD * 2) + gnum + bj * HALF);
;                     gdv[ai][m][bj] = (seg < 2) ? *(const u32x2*)(Zb + r * (ZLD * 2) + gden + bj * HALF) : (u32x2){0u, 0u}; } }
.LBB0_812:
	global_load_dwordx2 v[184:185], v[148:149], off offset:8
	s_and_b64 vcc, exec, s[42:43]
	v_mov_b32_e32 v183, 0
	s_cbranch_vccnz .LBB0_814
	global_load_dwordx2 v[182:183], v[146:147], off offset:8

;     __device__ __forceinline__ void operator()(f32x4 (&acc)[2][2][4][2], const Unit& u, int wr, int wc, int fr, int fq) const {
;     ...
;             for (int m = 0; m < 4; ++m) { const size_t r = (size_t)(row0 + ai * HALF + m * 16);
; #pragma unroll
;                 for (int bj = 0; bj < 2; ++bj) { gnv[ai][m][bj] = *(const u32x2*)(Zb + r * (ZLD * 2) + gnum + bj * HALF);
;                     gdv[ai][m][bj] = (seg < 2) ? *(const u32x2*)(Zb + r * (ZLD * 2) + gden + bj * HALF) : (u32x2){0u, 0u}; } }
.LBB0_816:
	global_load_dwordx2 v[164:165], v[148:149], off offset:8
	s_and_b64 vcc, exec, s[42:43]
	v_mov_b32_e32 v163, 0
	s_cbranch_vccnz .LBB0_818
	global_load_dwordx2 v[162:163], v[146:147], off offset:8

;     __device__ __forceinline__ void operator()(f32x4 (&acc)[2][2][4][2], const Unit& u, int wr, int wc, int fr, int fq) const {
;     ...
;             for (int m = 0; m < 4; ++m) { const size_t r = (size_t)(row0 + ai * HALF + m * 16);
; #pragma unroll
;                 for (int bj = 0; bj < 2; ++bj) { gnv[ai][m][bj] = *(const u32x2*)(Zb + r * (ZLD * 2) + gnum + bj * HALF);
;                     gdv[ai][m][bj] = (seg < 2) ? *(const u32x2*)(Zb + r * (ZLD * 2) + gden + bj * HALF) : (u32x2){0u, 0u}; } }
.LBB0_820:
	global_load_dwordx2 v[154:155], v[148:149], off offset:8
	s_and_b64 vcc, exec, s[42:43]
	v_mov_b32_e32 v153, 0
	s_cbranch_vccnz .LBB0_822
	global_load_dwordx2 v[152:153], v[146:147], off offset:8

;     __device__ __forceinline__ void operator()(f32x4 (&acc)[2][2][4][2], const Unit& u, int wr, int wc, int fr, int fq) const {
;     ...
;             for (int m = 0; m < 4; ++m) { const size_t r = (size_t)(row0 + ai * HALF + m * 16);
; #pragma unroll
;                 for (int bj = 0; bj < 2; ++bj) { gnv[ai][m][bj] = *(const u32x2*)(Zb + r * (ZLD * 2) + gnum + bj * HALF);
;                     gdv[ai][m][bj] = (seg < 2) ? *(const u32x2*)(Zb + r * (ZLD * 2) + gden + bj * HALF) : (u32x2){0u, 0u}; } }
.LBB0_824:
	global_load_dwordx2 v[144:145], v[232:233], off offset:8
	s_and_b64 vcc, exec, s[42:43]
	v_mov_b32_e32 v141, 0
	s_cbranch_vccnz .LBB0_826
	global_load_dwordx2 v[140:141], v[230:231], off offset:8

; __device__ __forceinline__ int fresh_tid() { int t = threadIdx.x; asm volatile("" : "+v"(t)); return t; }
; #define PG8_STAGE(bufoff, gbase, voff) do { _Pragma("unroll") for (int _i = 0; _i < 2; ++_i) \
;         __builtin_amdgcn_global_load_lds((const unsigned*)((const char*)(gbase) + (voff)[_i]), (LAS unsigned*)(lds + (bufoff) + ldsw + _i * 8192), 16, 0, 0); } while (0)
; #define PG8_WAIT_V(n) asm volatile("s_waitcnt vmcnt(" #n ")" ::: "memory")
; template <class Epi, class Sched, int NSEG, int KK, int LDA, int LDB>
; __device__ __forceinline__ void gemm_phase(LAS unsigned char* lds, const Gemm g, const Sched& S, const Epi& E) {
;     const int tid = fresh_tid(), wid = __builtin_amdgcn_readfirstlane(tid >> 6), lane = tid & 63, wr = wid >> 2, wc = wid & 3, fr = lane & 15, fq = lane >> 4;
;     constexpr int nt = KK / BK;
;     unsigned voffA[2], voffB[2];
; #pragma unroll
;     for (int i = 0; i < 2; ++i) { int R, C; stage_rc(tid * 16 + i * 8192, R, C); const int Rb = Epi::PERM ? ((R & ~31) + perm32(R & 31)) : R;
;         voffA[i] = (unsigned)(R * LDA + C) * 2u; voffB[i] = (unsigned)(Rb * LDB + C) * 2u; }
;     constexpr size_t kstep = (size_t)(BK * 2);
;     constexpr size_t hstepA = (size_t)HALF * LDA * 2, hstepB = (size_t)HALF * LDB * 2;
;     constexpr size_t tstepA = 2 * hstepA, tstepB = 2 * hstepB;
;     const unsigned ldsw = (unsigned)wid * 1024u;
;     const int aoff = lds_byte(wr * 64 + fr, fq * 8), boff = lds_byte(wc * 32 + fr, fq * 8);
;     ...
;     Unit cur, nxt; int ui = 0;
;     if (!S.next(0, cur)) return;
;     f32x4 acc[2][2][4][2];
; #pragma unroll
;     for (int a = 0; a < 2; ++a)
; #pragma unroll
;         for (int b = 0; b < 2; ++b)
; #pragma unroll
;             for (int m = 0; m < 4; ++m)
; #pragma unroll
;                 for (int n = 0; n < 2; ++n) acc[a][b][m][n] = (f32x4){0.f, 0.f, 0.f, 0.f};
;     bf16x8 At[4][2], B0[2][2], B1[2][2];
;     const char* cA = PG8_APTR(cur); const char* cB = PG8_BPTR(cur);
;     PG8_STAGE(PG8_SB(0, 0), cB, voffB); PG8_STAGE(PG8_SB(0, 1), cB + hstepB, voffB); PG8_STAGE(PG8_SA(0, 0), cA, voffA); PG8_STAGE(PG8_SA(0, 1), cA + hstepA, voffA);
;     if (wr == 1) PG8_BAR;
;     PG8_WAIT_V(2); PG8_BAR;
;     PG8_STAGE(PG8_SB(1, 0), cB + kstep, voffB); PG8_STAGE(PG8_SA(1, 0), cA + kstep, voffA); PG8_STAGE(PG8_SB(1, 1), cB + hstepB + kstep, voffB);
;     PG8_WAIT_V(6); PG8_BAR;
.LBB0_972:
	s_or_b64 exec, exec, s[0:1]
	v_readlane_b32 s0, v254, 26
	v_mov_b32_e32 v8, v246
	v_readlane_b32 s1, v254, 27
	s_waitcnt lgkmcnt(0)
	s_barrier
	s_mov_b32 s101, 0
	s_and_b64 vcc, exec, s[0:1]
	v_readfirstlane_b32 s8, v8
	s_cbranch_vccnz .LBB0_1012
	v_lshlrev_b32_e32 v0, 4, v8
	v_add_u32_e32 v3, 0x2000, v0
	v_ashrrev_i32_e32 v2, 31, v3
	v_lshrrev_b32_e32 v2, 22, v2
	v_add_u32_e32 v2, v3, v2
	v_ashrrev_i32_e32 v2, 10, v2
	v_lshlrev_b32_e32 v4, 5, v2
	v_and_b32_e32 v5, 32, v4
	v_mul_i32_i24_e32 v4, 0x400, v2
	v_sub_u32_e32 v3, v3, v4
	v_lshrrev_b32_e32 v4, 4, v3
	v_bitop3_b32 v4, v4, v3, 32 bitop3:0x6c
	v_ashrrev_i32_e32 v3, 31, v4
	v_lshrrev_b32_e32 v3, 26, v3
	v_add_u32_e32 v6, v4, v3
	v_ashrrev_i32_e32 v3, 6, v6
	v_and_b32_e32 v6, 0xc0, v6
	v_sub_u32_e32 v4, v4, v6
	v_ashrrev_i16_sdwa v4, v248, sext(v4) dst_sel:DWORD dst_unused:UNUSED_PAD src0_sel:DWORD src1_sel:BYTE_0
	v_lshlrev_b32_e32 v6, 3, v2
	v_bfe_i32 v4, v4, 0, 16
	v_and_b32_e32 v6, 0x1ffff0, v6
	v_add_u32_e32 v5, v5, v4
	v_add_lshl_u32 v6, v3, v6, 11
	v_lshl_add_u32 v130, v5, 1, v6
	v_ashrrev_i32_e32 v5, 31, v8
	v_lshrrev_b32_e32 v5, 26, v5
	v_add_u32_e32 v5, v8, v5
	v_ashrrev_i32_e32 v5, 6, v5
	v_lshlrev_b32_e32 v6, 5, v5
	v_and_b32_e32 v9, 32, v6
	v_bfe_i32 v6, v8, 27, 1
	v_lshrrev_b32_e32 v6, 22, v6
	v_add_u32_e32 v6, v0, v6
	v_and_b32_e32 v6, 0xfffffc00, v6
	v_sub_u32_e32 v0, v0, v6
	v_lshrrev_b32_e32 v6, 4, v0
	v_bitop3_b32 v7, v6, v0, 32 bitop3:0x6c
	v_ashrrev_i32_e32 v0, 31, v0
	v_lshrrev_b32_e32 v0, 26, v0
	v_add_u32_e32 v0, v7, v0
	v_ashrrev_i32_e32 v6, 6, v0
	v_mul_i32_i24_e32 v0, 64, v6
	v_readlane_b32 s0, v254, 22
	v_sub_u32_e32 v0, v7, v0
	s_add_u32 s12, s0, 0x1200000
	v_readlane_b32 s0, v254, 23
	v_ashrrev_i16_sdwa v0, v248, sext(v0) dst_sel:DWORD dst_unused:UNUSED_PAD src0_sel:DWORD src1_sel:BYTE_0
	s_addc_u32 s13, s0, 0
	s_ashr_i32 s9, s8, 6
	v_bfe_i32 v7, v0, 0, 16
	s_ashr_i32 s22, s8, 8
	s_lshl_b32 s23, s9, 10
	v_add_u32_e32 v0, v9, v7
	v_lshlrev_b32_e32 v9, 3, v5
	v_readlane_b32 s0, v255, 61
	v_and_b32_e32 v9, 0x1ffff0, v9
	v_readlane_b32 s1, v255, 62
	s_add_u32 s44, s12, s0
	v_add_lshl_u32 v9, v6, v9, 11
	s_addc_u32 s45, s13, s1
	s_add_i32 s26, s23, 0
	v_lshl_add_u32 v0, v0, 1, v9
	s_add_i32 m0, s26, 0x10000
	s_nop 0
	global_load_lds_dwordx4 v0, s[44:45]
	s_add_i32 m0, s26, 0x12000
	s_add_u32 s0, s44, 0x40000
	global_load_lds_dwordx4 v130, s[44:45]
	s_addc_u32 s1, s45, 0
	s_add_i32 m0, s26, 0x14000
	s_add_i32 s33, s26, 0x2000
	global_load_lds_dwordx4 v0, s[0:1]
	s_add_i32 m0, s26, 0x16000
	s_add_i32 s38, s26, 0x4000
	global_load_lds_dwordx4 v130, s[0:1]
	v_readlane_b32 s0, v255, 63
	s_mov_b32 m0, s26
	v_readlane_b32 s1, v254, 0
	s_add_i32 s39, s26, 0x6000
	s_cmp_eq_u32 s22, 1
	s_nop 2
	global_load_lds_dwordx4 v0, s[0:1]
	s_mov_b32 m0, s33
	s_nop 0
	global_load_lds_dwordx4 v130, s[0:1]
	v_readlane_b32 s0, v254, 1
	s_mov_b32 m0, s38
	v_readlane_b32 s1, v254, 2
	s_nop 4
	global_load_lds_dwordx4 v0, s[0:1]
	s_mov_b32 m0, s39
	s_nop 0
	global_load_lds_dwordx4 v130, s[0:1]
	s_cselect_b64 s[0:1], -1, 0
	s_cmp_lg_u32 s22, 1
	s_cbranch_scc1 .LBB0_975
	s_barrier

; #define PG8_STAGE(bufoff, gbase, voff) do { _Pragma("unroll") for (int _i = 0; _i < 2; ++_i) \
;         __builtin_amdgcn_global_load_lds((const unsigned*)((const char*)(gbase) + (voff)[_i]), (LAS unsigned*)(lds + (bufoff) + ldsw + _i * 8192), 16, 0, 0); } while (0)
; #define PG8_LDA(dst, b, h) do { _Pragma("unroll") for (int m = 0; m < 4; ++m) _Pragma("unroll") for (int k = 0; k < 2; ++k) dst[m][k] = *(const LAS bf16x8*)(lds + PG8_SA(b, h) + aoff + m * 2048 + k * 1024); } while (0)
; #define PG8_LDB(dst, b, h) do { _Pragma("unroll") for (int n = 0; n < 2; ++n) _Pragma("unroll") for (int k = 0; k < 2; ++k) dst[n][k] = *(const LAS bf16x8*)(lds + PG8_SB(b, h) + boff + n * 2048 + k * 1024); } while (0)
; #define PG8_MMA(ai, bj, At, Bt) do { __builtin_amdgcn_s_setprio(1); _Pragma("unroll") for (int m = 0; m < 4; ++m) _Pragma("unroll") for (int n = 0; n < 2; ++n) _Pragma("unroll") for (int k = 0; k < 2; ++k) \
;         acc[ai][bj][m][n] = __builtin_amdgcn_mfma_f32_16x16x32_bf16(Bt[n][k], At[m][k], acc[ai][bj][m][n], 0, 0, 0); __builtin_amdgcn_s_setprio(0); } while (0)
; #define PG8_WAIT_V(n) asm volatile("s_waitcnt vmcnt(" #n ")" ::: "memory")
; template <class Epi, class Sched, int NSEG, int KK, int LDA, int LDB>
; __device__ __forceinline__ void gemm_phase(LAS unsigned char* lds, const Gemm g, const Sched& S, const Epi& E) {
;     ...
;         const bool has_next = S.next(ui + 1, nxt);
;         const char* nA = has_next ? PG8_APTR(nxt) : cA; const char* nB = has_next ? PG8_BPTR(nxt) : cB;
;         for (int t = 0; t < nt; t += 2) {
;             const bool last = (t == nt - 2);
;             const char* a1 = cA + (size_t)(t + 1) * kstep;
;             const char* a2 = last ? nA : cA + (size_t)(t + 2) * kstep; const char* b2 = last ? nB : cB + (size_t)(t + 2) * kstep;
;             const char* a3 = a2 + kstep; const char* b3 = b2 + kstep;
;             PG8_LDB(B0, 0, 0); PG8_LDB(B1, 0, 1); PG8_SCHED; PG8_LDA(At, 0, 0); PG8_STAGE(PG8_SA(1, 1), a1 + hstepA, voffA);
;             PG8_WAIT_V(8); PG8_WAIT_L(0); PG8_BAR; PG8_MMA(0, 0, At, B0); PG8_MMA(0, 1, At, B1); PG8_BAR; PG8_SCHED;
;             PG8_LDA(At, 0, 1); PG8_STAGE(PG8_SB(0, 0), b2, voffB); PG8_STAGE(PG8_SB(0, 1), b2 + hstepB, voffB); PG8_STAGE(PG8_SA(0, 0), a2, voffA);
;             PG8_WAIT_V(8); PG8_WAIT_L(0); PG8_BAR; PG8_MMA(1, 0, At, B0); PG8_MMA(1, 1, At, B1); PG8_BAR; PG8_SCHED;
.LBB0_985:
	s_add_u32 s10, s42, 0xfffc0080
	s_addc_u32 s11, s43, -1
	s_add_i32 s63, 0, 0x10000
	s_cmp_eq_u32 s62, 12
	s_cselect_b32 s45, s49, s11
	s_cselect_b32 s44, s54, s10
	s_cselect_b32 s11, s47, s61
	s_cselect_b32 s10, s55, s60
	s_add_i32 s77, 0, 0x14000
	v_add_u32_e32 v148, s63, v164
	v_add_u32_e32 v166, s77, v164
	ds_read_b128 v[136:139], v148
	ds_read_b128 v[140:143], v148 offset:1024
	ds_read_b128 v[144:147], v148 offset:256
	ds_read_b128 v[148:151], v148 offset:1280
	ds_read_b128 v[152:155], v166
	ds_read_b128 v[156:159], v166 offset:1024
	ds_read_b128 v[160:163], v166 offset:256
	ds_read_b128 v[176:179], v166 offset:1280
	v_lshl_add_u64 v[166:167], s[42:43], 0, v[132:133]
	s_add_i32 m0, s26, 0xc000
	ds_read_b128 v[180:183], v165
	ds_read_b128 v[184:187], v165 offset:1024
	ds_read_b128 v[188:191], v165 offset:2048
	ds_read_b128 v[192:195], v165 offset:3072
	ds_read_b128 v[196:199], v165 offset:4096
	ds_read_b128 v[200:203], v165 offset:5120
	ds_read_b128 v[204:207], v165 offset:6144
	ds_read_b128 v[208:211], v165 offset:7168
	global_load_lds_dwordx4 v[166:167], off
	v_lshl_add_u64 v[166:167], s[42:43], 0, v[134:135]
	s_add_i32 m0, s26, 0xe000
	s_nop 0
	global_load_lds_dwordx4 v[166:167], off
	s_cmp_lg_u32 s101, 0
	s_cbranch_scc1 .Lskw_3_1
	s_waitcnt vmcnt(8)
.Lskw_3_1:
	s_waitcnt lgkmcnt(0)
	s_barrier
	s_setprio 1
	s_waitcnt lgkmcnt(0)
	v_mfma_f32_16x16x32_bf16 v[126:129], v[136:139], v[180:183], v[126:129]
	v_mfma_f32_16x16x32_bf16 v[122:125], v[144:147], v[180:183], v[122:125]
	v_mfma_f32_16x16x32_bf16 v[110:113], v[136:139], v[188:191], v[110:113]
	v_mfma_f32_16x16x32_bf16 v[106:109], v[144:147], v[188:191], v[106:109]
	v_mfma_f32_16x16x32_bf16 v[94:97], v[136:139], v[196:199], v[94:97]
	v_mfma_f32_16x16x32_bf16 v[90:93], v[144:147], v[196:199], v[90:93]
	v_mfma_f32_16x16x32_bf16 v[78:81], v[136:139], v[204:207], v[78:81]
	v_mfma_f32_16x16x32_bf16 v[74:77], v[144:147], v[204:207], v[74:77]
	v_mfma_f32_16x16x32_bf16 v[126:129], v[140:143], v[184:187], v[126:129]
	v_mfma_f32_16x16x32_bf16 v[122:125], v[148:151], v[184:187], v[122:125]
	v_mfma_f32_16x16x32_bf16 v[110:113], v[140:143], v[192:195], v[110:113]
	v_mfma_f32_16x16x32_bf16 v[106:109], v[148:151], v[192:195], v[106:109]
	v_mfma_f32_16x16x32_bf16 v[94:97], v[140:143], v[200:203], v[94:97]
	v_mfma_f32_16x16x32_bf16 v[90:93], v[148:151], v[200:203], v[90:93]
	v_mfma_f32_16x16x32_bf16 v[78:81], v[140:143], v[208:211], v[78:81]
	v_mfma_f32_16x16x32_bf16 v[74:77], v[148:151], v[208:211], v[74:77]
	s_setprio 0
	s_setprio 1
	v_mfma_f32_16x16x32_bf16 v[118:121], v[152:155], v[180:183], v[118:121]
	v_mfma_f32_16x16x32_bf16 v[114:117], v[160:163], v[180:183], v[114:117]
	v_mfma_f32_16x16x32_bf16 v[102:105], v[152:155], v[188:191], v[102:105]
	v_mfma_f32_16x16x32_bf16 v[98:101], v[160:163], v[188:191], v[98:101]
	v_mfma_f32_16x16x32_bf16 v[86:89], v[152:155], v[196:199], v[86:89]
	v_mfma_f32_16x16x32_bf16 v[82:85], v[160:163], v[196:199], v[82:85]
	v_mfma_f32_16x16x32_bf16 v[70:73], v[152:155], v[204:207], v[70:73]
	v_mfma_f32_16x16x32_bf16 v[66:69], v[160:163], v[204:207], v[66:69]
	v_mfma_f32_16x16x32_bf16 v[118:121], v[156:159], v[184:187], v[118:121]
	v_mfma_f32_16x16x32_bf16 v[114:117], v[176:179], v[184:187], v[114:117]
	v_mfma_f32_16x16x32_bf16 v[102:105], v[156:159], v[192:195], v[102:105]
	v_mfma_f32_16x16x32_bf16 v[98:101], v[176:179], v[192:195], v[98:101]
	v_mfma_f32_16x16x32_bf16 v[86:89], v[156:159], v[200:203], v[86:89]
	v_mfma_f32_16x16x32_bf16 v[82:85], v[176:179], v[200:203], v[82:85]
	v_mfma_f32_16x16x32_bf16 v[70:73], v[156:159], v[208:211], v[70:73]
	v_mfma_f32_16x16x32_bf16 v[66:69], v[176:179], v[208:211], v[66:69]
	s_setprio 0
	s_barrier
	s_add_i32 s63, s63, s23
	v_lshl_add_u64 v[166:167], s[10:11], 0, v[0:1]
	s_mov_b32 m0, s63
	ds_read_b128 v[180:183], v165 offset:16384
	ds_read_b128 v[184:187], v165 offset:17408
	ds_read_b128 v[188:191], v165 offset:18432
	ds_read_b128 v[192:195], v165 offset:19456
	ds_read_b128 v[196:199], v165 offset:20480
	ds_read_b128 v[200:203], v165 offset:21504
	ds_read_b128 v[204:207], v165 offset:22528
	ds_read_b128 v[208:211], v165 offset:23552
	global_load_lds_dwordx4 v[166:167], off
	s_add_i32 m0, s63, 0x2000
	s_add_u32 s94, s10, 0x40000
	v_lshl_add_u64 v[172:173], s[10:11], 0, v[130:131]
	s_addc_u32 s95, s11, 0
	s_add_i32 s63, s77, s23
	global_load_lds_dwordx4 v[172:173], off
	v_lshl_add_u64 v[212:213], s[94:95], 0, v[0:1]
	s_mov_b32 m0, s63
	v_lshl_add_u64 v[214:215], s[44:45], 0, v[130:131]
	global_load_lds_dwordx4 v[212:213], off
	v_lshl_add_u64 v[212:213], s[94:95], 0, v[130:131]
	s_add_i32 m0, s63, 0x2000
	s_nop 0
	global_load_lds_dwordx4 v[212:213], off
	v_lshl_add_u64 v[212:213], s[44:45], 0, v[0:1]
	s_mov_b32 m0, s26
	s_nop 0
	global_load_lds_dwordx4 v[212:213], off
	s_mov_b32 m0, s33
	s_nop 0
	global_load_lds_dwordx4 v[214:215], off
	s_cmp_lg_u32 s101, 0
	s_cbranch_scc1 .Lskw_3_2
	s_waitcnt vmcnt(8)
; #define PG8_STAGE(bufoff, gbase, voff) do { _Pragma("unroll") for (int _i = 0; _i < 2; ++_i) \
;         __builtin_amdgcn_global_load_lds((const unsigned*)((const char*)(gbase) + (voff)[_i]), (LAS unsigned*)(lds + (bufoff) + ldsw + _i * 8192), 16, 0, 0); } while (0)
; #define PG8_LDA(dst, b, h) do { _Pragma("unroll") for (int m = 0; m < 4; ++m) _Pragma("unroll") for (int k = 0; k < 2; ++k) dst[m][k] = *(const LAS bf16x8*)(lds + PG8_SA(b, h) + aoff + m * 2048 + k * 1024); } while (0)
; #define PG8_LDB(dst, b, h) do { _Pragma("unroll") for (int n = 0; n < 2; ++n) _Pragma("unroll") for (int k = 0; k < 2; ++k) dst[n][k] = *(const LAS bf16x8*)(lds + PG8_SB(b, h) + boff + n * 2048 + k * 1024); } while (0)
; #define PG8_MMA(ai, bj, At, Bt) do { __builtin_amdgcn_s_setprio(1); _Pragma("unroll") for (int m = 0; m < 4; ++m) _Pragma("unroll") for (int n = 0; n < 2; ++n) _Pragma("unroll") for (int k = 0; k < 2; ++k) \
;         acc[ai][bj][m][n] = __builtin_amdgcn_mfma_f32_16x16x32_bf16(Bt[n][k], At[m][k], acc[ai][bj][m][n], 0, 0, 0); __builtin_amdgcn_s_setprio(0); } while (0)
; #define PG8_WAIT_V(n) asm volatile("s_waitcnt vmcnt(" #n ")" ::: "memory")
; #define PG8_WAIT_L(n) asm volatile("s_waitcnt lgkmcnt(" #n ")" ::: "memory")
; #define PG8_BAR __builtin_amdgcn_s_barrier()
; #define PG8_SCHED __builtin_amdgcn_sched_barrier(0)
; template <class Epi, class Sched, int NSEG, int KK, int LDA, int LDB>
; __device__ __forceinline__ void gemm_phase(LAS unsigned char* lds, const Gemm g, const Sched& S, const Epi& E) {
;     ...
;             PG8_WAIT_V(8); PG8_WAIT_L(0); PG8_BAR; PG8_MMA(1, 0, At, B0); PG8_MMA(1, 1, At, B1); PG8_BAR; PG8_SCHED;
;             PG8_LDB(B0, 1, 0); PG8_LDB(B1, 1, 1); PG8_SCHED; PG8_LDA(At, 1, 0); PG8_STAGE(PG8_SA(0, 1), a2 + hstepA, voffA);
;             PG8_WAIT_V(8); PG8_WAIT_L(0); PG8_BAR; PG8_MMA(0, 0, At, B0); PG8_MMA(0, 1, At, B1); PG8_BAR; PG8_SCHED;
.Lskw_3_2:
	s_mov_b32 s101, 0
	s_waitcnt lgkmcnt(0)
	s_barrier
	s_setprio 1
	s_waitcnt lgkmcnt(0)
	v_mfma_f32_16x16x32_bf16 v[62:65], v[136:139], v[180:183], v[62:65]
	v_mfma_f32_16x16x32_bf16 v[58:61], v[144:147], v[180:183], v[58:61]
	v_mfma_f32_16x16x32_bf16 v[46:49], v[136:139], v[188:191], v[46:49]
	v_mfma_f32_16x16x32_bf16 v[42:45], v[144:147], v[188:191], v[42:45]
	v_mfma_f32_16x16x32_bf16 v[30:33], v[136:139], v[196:199], v[30:33]
	v_mfma_f32_16x16x32_bf16 v[26:29], v[144:147], v[196:199], v[26:29]
	v_mfma_f32_16x16x32_bf16 v[14:17], v[136:139], v[204:207], v[14:17]
	v_mfma_f32_16x16x32_bf16 v[10:13], v[144:147], v[204:207], v[10:13]
	v_mfma_f32_16x16x32_bf16 v[62:65], v[140:143], v[184:187], v[62:65]
	v_mfma_f32_16x16x32_bf16 v[58:61], v[148:151], v[184:187], v[58:61]
	v_mfma_f32_16x16x32_bf16 v[46:49], v[140:143], v[192:195], v[46:49]
	v_mfma_f32_16x16x32_bf16 v[42:45], v[148:151], v[192:195], v[42:45]
	v_mfma_f32_16x16x32_bf16 v[30:33], v[140:143], v[200:203], v[30:33]
	v_mfma_f32_16x16x32_bf16 v[26:29], v[148:151], v[200:203], v[26:29]
	v_mfma_f32_16x16x32_bf16 v[14:17], v[140:143], v[208:211], v[14:17]
	v_mfma_f32_16x16x32_bf16 v[10:13], v[148:151], v[208:211], v[10:13]
	s_setprio 0
	s_setprio 1
	v_mfma_f32_16x16x32_bf16 v[54:57], v[152:155], v[180:183], v[54:57]
	v_mfma_f32_16x16x32_bf16 v[50:53], v[160:163], v[180:183], v[50:53]
	v_mfma_f32_16x16x32_bf16 v[38:41], v[152:155], v[188:191], v[38:41]
	v_mfma_f32_16x16x32_bf16 v[34:37], v[160:163], v[188:191], v[34:37]
	v_mfma_f32_16x16x32_bf16 v[22:25], v[152:155], v[196:199], v[22:25]
	v_mfma_f32_16x16x32_bf16 v[18:21], v[160:163], v[196:199], v[18:21]
	v_mfma_f32_16x16x32_bf16 v[6:9], v[152:155], v[204:207], v[6:9]
	v_mfma_f32_16x16x32_bf16 v[2:5], v[160:163], v[204:207], v[2:5]
	v_mfma_f32_16x16x32_bf16 v[54:57], v[156:159], v[184:187], v[54:57]
	v_mfma_f32_16x16x32_bf16 v[50:53], v[176:179], v[184:187], v[50:53]
	v_mfma_f32_16x16x32_bf16 v[38:41], v[156:159], v[192:195], v[38:41]
	v_mfma_f32_16x16x32_bf16 v[34:37], v[176:179], v[192:195], v[34:37]
	v_mfma_f32_16x16x32_bf16 v[22:25], v[156:159], v[200:203], v[22:25]
	v_mfma_f32_16x16x32_bf16 v[18:21], v[176:179], v[200:203], v[18:21]
	v_mfma_f32_16x16x32_bf16 v[6:9], v[156:159], v[208:211], v[6:9]
	v_mfma_f32_16x16x32_bf16 v[2:5], v[176:179], v[208:211], v[2:5]
	s_setprio 0
	s_barrier
	s_add_i32 s63, 0, 0x18000
	s_add_i32 s77, 0, 0x1c000
	v_add_u32_e32 v148, s63, v164
	v_add_u32_e32 v176, s77, v164
	ds_read_b128 v[136:139], v148
	ds_read_b128 v[140:143], v148 offset:1024
	ds_read_b128 v[144:147], v148 offset:256
	ds_read_b128 v[148:151], v148 offset:1280
	ds_read_b128 v[152:155], v176
	ds_read_b128 v[156:159], v176 offset:1024
	ds_read_b128 v[160:163], v176 offset:256
	ds_read_b128 v[176:179], v176 offset:1280
	s_add_u32 s44, s44, 0x40000
	s_addc_u32 s45, s45, 0
	s_mov_b32 m0, s38
	v_lshl_add_u64 v[216:217], s[44:45], 0, v[0:1]
	ds_read_b128 v[180:183], v165 offset:32768
	ds_read_b128 v[184:187], v165 offset:33792
	ds_read_b128 v[188:191], v165 offset:34816
	ds_read_b128 v[192:195], v165 offset:35840
	ds_read_b128 v[196:199], v165 offset:36864
	ds_read_b128 v[200:203], v165 offset:37888
	ds_read_b128 v[204:207], v165 offset:38912
	ds_read_b128 v[208:211], v165 offset:39936
	global_load_lds_dwordx4 v[216:217], off
	v_lshl_add_u64 v[216:217], s[44:45], 0, v[130:131]
	s_mov_b32 m0, s39
	s_nop 0
	global_load_lds_dwordx4 v[216:217], off
	s_waitcnt vmcnt(8)
	s_waitcnt lgkmcnt(0)
	s_barrier
	s_setprio 1
	s_waitcnt lgkmcnt(0)
	v_mfma_f32_16x16x32_bf16 v[126:129], v[136:139], v[180:183], v[126:129]
	v_mfma_f32_16x16x32_bf16 v[122:125], v[144:147], v[180:183], v[122:125]
	v_mfma_f32_16x16x32_bf16 v[110:113], v[136:139], v[188:191], v[110:113]
	v_mfma_f32_16x16x32_bf16 v[106:109], v[144:147], v[188:191], v[106:109]
	v_mfma_f32_16x16x32_bf16 v[94:97], v[136:139], v[196:199], v[94:97]
	v_mfma_f32_16x16x32_bf16 v[90:93], v[144:147], v[196:199], v[90:93]
	v_mfma_f32_16x16x32_bf16 v[78:81], v[136:139], v[204:207], v[78:81]
	v_mfma_f32_16x16x32_bf16 v[74:77], v[144:147], v[204:207], v[74:77]
	v_mfma_f32_16x16x32_bf16 v[126:129], v[140:143], v[184:187], v[126:129]
	v_mfma_f32_16x16x32_bf16 v[122:125], v[148:151], v[184:187], v[122:125]
	v_mfma_f32_16x16x32_bf16 v[110:113], v[140:143], v[192:195], v[110:113]
	v_mfma_f32_16x16x32_bf16 v[106:109], v[148:151], v[192:195], v[106:109]
	v_mfma_f32_16x16x32_bf16 v[94:97], v[140:143], v[200:203], v[94:97]
	v_mfma_f32_16x16x32_bf16 v[90:93], v[148:151], v[200:203], v[90:93]
	v_mfma_f32_16x16x32_bf16 v[78:81], v[140:143], v[208:211], v[78:81]
	v_mfma_f32_16x16x32_bf16 v[74:77], v[148:151], v[208:211], v[74:77]
	s_setprio 0
	s_setprio 1
	v_mfma_f32_16x16x32_bf16 v[118:121], v[152:155], v[180:183], v[118:121]
	v_mfma_f32_16x16x32_bf16 v[114:117], v[160:163], v[180:183], v[114:117]
	v_mfma_f32_16x16x32_bf16 v[102:105], v[152:155], v[188:191], v[102:105]
	v_mfma_f32_16x16x32_bf16 v[98:101], v[160:163], v[188:191], v[98:101]
	v_mfma_f32_16x16x32_bf16 v[86:89], v[152:155], v[196:199], v[86:89]
	v_mfma_f32_16x16x32_bf16 v[82:85], v[160:163], v[196:199], v[82:85]
	v_mfma_f32_16x16x32_bf16 v[70:73], v[152:155], v[204:207], v[70:73]
	v_mfma_f32_16x16x32_bf16 v[66:69], v[160:163], v[204:207], v[66:69]
	v_mfma_f32_16x16x32_bf16 v[118:121], v[156:159], v[184:187], v[118:121]
	v_mfma_f32_16x16x32_bf16 v[114:117], v[176:179], v[184:187], v[114:117]
	v_mfma_f32_16x16x32_bf16 v[102:105], v[156:159], v[192:195], v[102:105]
	v_mfma_f32_16x16x32_bf16 v[98:101], v[176:179], v[192:195], v[98:101]
	v_mfma_f32_16x16x32_bf16 v[86:89], v[156:159], v[200:203], v[86:89]
	v_mfma_f32_16x16x32_bf16 v[82:85], v[176:179], v[200:203], v[82:85]
	v_mfma_f32_16x16x32_bf16 v[70:73], v[156:159], v[208:211], v[70:73]
	v_mfma_f32_16x16x32_bf16 v[66:69], v[176:179], v[208:211], v[66:69]
	s_setprio 0
	s_barrier
; #define PG8_STAGE(bufoff, gbase, voff) do { _Pragma("unroll") for (int _i = 0; _i < 2; ++_i) \
;         __builtin_amdgcn_global_load_lds((const unsigned*)((const char*)(gbase) + (voff)[_i]), (LAS unsigned*)(lds + (bufoff) + ldsw + _i * 8192), 16, 0, 0); } while (0)
; #define PG8_LDA(dst, b, h) do { _Pragma("unroll") for (int m = 0; m < 4; ++m) _Pragma("unroll") for (int k = 0; k < 2; ++k) dst[m][k] = *(const LAS bf16x8*)(lds + PG8_SA(b, h) + aoff + m * 2048 + k * 1024); } while (0)
; #define PG8_MMA(ai, bj, At, Bt) do { __builtin_amdgcn_s_setprio(1); _Pragma("unroll") for (int m = 0; m < 4; ++m) _Pragma("unroll") for (int n = 0; n < 2; ++n) _Pragma("unroll") for (int k = 0; k < 2; ++k) \
;         acc[ai][bj][m][n] = __builtin_amdgcn_mfma_f32_16x16x32_bf16(Bt[n][k], At[m][k], acc[ai][bj][m][n], 0, 0, 0); __builtin_amdgcn_s_setprio(0); } while (0)
; #define PG8_WAIT_V(n) asm volatile("s_waitcnt vmcnt(" #n ")" ::: "memory")
; #define PG8_WAIT_L(n) asm volatile("s_waitcnt lgkmcnt(" #n ")" ::: "memory")
; #define PG8_BAR __builtin_amdgcn_s_barrier()
; #define PG8_SCHED __builtin_amdgcn_sched_barrier(0)
; template <class Epi, class Sched, int NSEG, int KK, int LDA, int LDB>
; __device__ __forceinline__ void gemm_phase(LAS unsigned char* lds, const Gemm g, const Sched& S, const Epi& E) {
;     ...
;             PG8_LDA(At, 1, 1); PG8_STAGE(PG8_SB(1, 0), b3, voffB); PG8_STAGE(PG8_SB(1, 1), b3 + hstepB, voffB); PG8_STAGE(PG8_SA(1, 0), a3, voffA);
;             PG8_WAIT_V(8); PG8_WAIT_L(0); PG8_BAR; PG8_MMA(1, 0, At, B0); PG8_MMA(1, 1, At, B1); PG8_BAR; PG8_SCHED;
;         }
;         if (wr == 0) PG8_BAR;
	s_add_i32 s44, s63, s23
	v_lshl_add_u64 v[166:167], v[166:167], 0, s[28:29]
	s_mov_b32 m0, s44
	ds_read_b128 v[180:183], v165 offset:49152
	ds_read_b128 v[184:187], v165 offset:50176
	ds_read_b128 v[188:191], v165 offset:51200
	ds_read_b128 v[192:195], v165 offset:52224
	ds_read_b128 v[196:199], v165 offset:53248
	ds_read_b128 v[200:203], v165 offset:54272
	ds_read_b128 v[204:207], v165 offset:55296
	ds_read_b128 v[208:211], v165 offset:56320
	global_load_lds_dwordx4 v[166:167], off
	s_add_i32 m0, s44, 0x2000
	s_add_u32 s10, s10, 0x40080
	v_lshl_add_u64 v[166:167], v[172:173], 0, s[28:29]
	s_addc_u32 s11, s11, 0
	s_add_i32 s44, s77, s23
	global_load_lds_dwordx4 v[166:167], off
	v_lshl_add_u64 v[166:167], s[10:11], 0, v[0:1]
	s_mov_b32 m0, s44
	s_nop 0
	global_load_lds_dwordx4 v[166:167], off
	v_lshl_add_u64 v[166:167], s[10:11], 0, v[130:131]
	s_add_i32 m0, s44, 0x2000
	s_nop 0
	global_load_lds_dwordx4 v[166:167], off
	v_lshl_add_u64 v[166:167], v[212:213], 0, s[28:29]
	s_mov_b32 m0, s57
	s_nop 0
	global_load_lds_dwordx4 v[166:167], off
	v_lshl_add_u64 v[166:167], v[214:215], 0, s[28:29]
	s_mov_b32 m0, s58
	s_nop 0
	global_load_lds_dwordx4 v[166:167], off
	s_waitcnt vmcnt(8)
	s_waitcnt lgkmcnt(0)
	s_barrier
	s_setprio 1
	s_waitcnt lgkmcnt(0)
	v_mfma_f32_16x16x32_bf16 v[62:65], v[136:139], v[180:183], v[62:65]
	v_mfma_f32_16x16x32_bf16 v[58:61], v[144:147], v[180:183], v[58:61]
	v_mfma_f32_16x16x32_bf16 v[46:49], v[136:139], v[188:191], v[46:49]
	v_mfma_f32_16x16x32_bf16 v[42:45], v[144:147], v[188:191], v[42:45]
	v_mfma_f32_16x16x32_bf16 v[30:33], v[136:139], v[196:199], v[30:33]
	v_mfma_f32_16x16x32_bf16 v[26:29], v[144:147], v[196:199], v[26:29]
	v_mfma_f32_16x16x32_bf16 v[14:17], v[136:139], v[204:207], v[14:17]
	v_mfma_f32_16x16x32_bf16 v[10:13], v[144:147], v[204:207], v[10:13]
	v_mfma_f32_16x16x32_bf16 v[62:65], v[140:143], v[184:187], v[62:65]
	v_mfma_f32_16x16x32_bf16 v[58:61], v[148:151], v[184:187], v[58:61]
	v_mfma_f32_16x16x32_bf16 v[46:49], v[140:143], v[192:195], v[46:49]
	v_mfma_f32_16x16x32_bf16 v[42:45], v[148:151], v[192:195], v[42:45]
	v_mfma_f32_16x16x32_bf16 v[30:33], v[140:143], v[200:203], v[30:33]
	v_mfma_f32_16x16x32_bf16 v[26:29], v[148:151], v[200:203], v[26:29]
	v_mfma_f32_16x16x32_bf16 v[14:17], v[140:143], v[208:211], v[14:17]
	v_mfma_f32_16x16x32_bf16 v[10:13], v[148:151], v[208:211], v[10:13]
	s_setprio 0
	s_setprio 1
	v_mfma_f32_16x16x32_bf16 v[54:57], v[152:155], v[180:183], v[54:57]
	v_mfma_f32_16x16x32_bf16 v[50:53], v[160:163], v[180:183], v[50:53]
	v_mfma_f32_16x16x32_bf16 v[38:41], v[152:155], v[188:191], v[38:41]
	v_mfma_f32_16x16x32_bf16 v[34:37], v[160:163], v[188:191], v[34:37]
	v_mfma_f32_16x16x32_bf16 v[22:25], v[152:155], v[196:199], v[22:25]
	v_mfma_f32_16x16x32_bf16 v[18:21], v[160:163], v[196:199], v[18:21]
	v_mfma_f32_16x16x32_bf16 v[6:9], v[152:155], v[204:207], v[6:9]
	v_mfma_f32_16x16x32_bf16 v[2:5], v[160:163], v[204:207], v[2:5]
	v_mfma_f32_16x16x32_bf16 v[54:57], v[156:159], v[184:187], v[54:57]
	v_mfma_f32_16x16x32_bf16 v[50:53], v[176:179], v[184:187], v[50:53]
	v_mfma_f32_16x16x32_bf16 v[38:41], v[156:159], v[192:195], v[38:41]
	v_mfma_f32_16x16x32_bf16 v[34:37], v[176:179], v[192:195], v[34:37]
	v_mfma_f32_16x16x32_bf16 v[22:25], v[156:159], v[200:203], v[22:25]
	v_mfma_f32_16x16x32_bf16 v[18:21], v[176:179], v[200:203], v[18:21]
	v_mfma_f32_16x16x32_bf16 v[6:9], v[156:159], v[208:211], v[6:9]
	v_mfma_f32_16x16x32_bf16 v[2:5], v[176:179], v[208:211], v[2:5]
	s_setprio 0
	s_barrier
	s_add_i32 s62, s62, 2
	s_add_u32 s42, s42, 0x100
	s_addc_u32 s43, s43, 0
	s_add_u32 s60, s60, 0x100
	s_addc_u32 s61, s61, 0
	s_cmp_gt_u32 s62, 13
	s_cbranch_scc0 .LBB0_985
	s_mov_b32 s101, 1
	s_and_b64 vcc, exec, s[8:9]
	s_cbranch_vccz .LBB0_988
	s_barrier

; __device__ __forceinline__ int fresh_tid() { int t = threadIdx.x; asm volatile("" : "+v"(t)); return t; }
; #define PG8_STAGE(bufoff, gbase, voff) do { _Pragma("unroll") for (int _i = 0; _i < 2; ++_i) \
;         __builtin_amdgcn_global_load_lds((const unsigned*)((const char*)(gbase) + (voff)[_i]), (LAS unsigned*)(lds + (bufoff) + ldsw + _i * 8192), 16, 0, 0); } while (0)
; #define PG8_WAIT_V(n) asm volatile("s_waitcnt vmcnt(" #n ")" ::: "memory")
; template <class Epi, class Sched, int NSEG, int KK, int LDA, int LDB>
; __device__ __forceinline__ void gemm_phase(LAS unsigned char* lds, const Gemm g, const Sched& S, const Epi& E) {
;     const int tid = fresh_tid(), wid = __builtin_amdgcn_readfirstlane(tid >> 6), lane = tid & 63, wr = wid >> 2, wc = wid & 3, fr = lane & 15, fq = lane >> 4;
;     constexpr int nt = KK / BK;
;     unsigned voffA[2], voffB[2];
; #pragma unroll
;     for (int i = 0; i < 2; ++i) { int R, C; stage_rc(tid * 16 + i * 8192, R, C); const int Rb = Epi::PERM ? ((R & ~31) + perm32(R & 31)) : R;
;         voffA[i] = (unsigned)(R * LDA + C) * 2u; voffB[i] = (unsigned)(Rb * LDB + C) * 2u; }
;     constexpr size_t kstep = (size_t)(BK * 2);
;     constexpr size_t hstepA = (size_t)HALF * LDA * 2, hstepB = (size_t)HALF * LDB * 2;
;     constexpr size_t tstepA = 2 * hstepA, tstepB = 2 * hstepB;
;     const unsigned ldsw = (unsigned)wid * 1024u;
;     const int aoff = lds_byte(wr * 64 + fr, fq * 8), boff = lds_byte(wc * 32 + fr, fq * 8);
;     ...
;     Unit cur, nxt; int ui = 0;
;     if (!S.next(0, cur)) return;
;     f32x4 acc[2][2][4][2];
; #pragma unroll
;     for (int a = 0; a < 2; ++a)
; #pragma unroll
;         for (int b = 0; b < 2; ++b)
; #pragma unroll
;             for (int m = 0; m < 4; ++m)
; #pragma unroll
;                 for (int n = 0; n < 2; ++n) acc[a][b][m][n] = (f32x4){0.f, 0.f, 0.f, 0.f};
;     bf16x8 At[4][2], B0[2][2], B1[2][2];
;     const char* cA = PG8_APTR(cur); const char* cB = PG8_BPTR(cur);
;     PG8_STAGE(PG8_SB(0, 0), cB, voffB); PG8_STAGE(PG8_SB(0, 1), cB + hstepB, voffB); PG8_STAGE(PG8_SA(0, 0), cA, voffA); PG8_STAGE(PG8_SA(0, 1), cA + hstepA, voffA);
;     if (wr == 1) PG8_BAR;
;     PG8_WAIT_V(2); PG8_BAR;
;     PG8_STAGE(PG8_SB(1, 0), cB + kstep, voffB); PG8_STAGE(PG8_SA(1, 0), cA + kstep, voffA); PG8_STAGE(PG8_SB(1, 1), cB + hstepB + kstep, voffB);
;     PG8_WAIT_V(6); PG8_BAR;
.LBB0_1056:
	s_or_b64 exec, exec, s[0:1]
	v_readlane_b32 s40, v253, 20
	v_readlane_b32 s52, v253, 32
	v_readlane_b32 s53, v253, 33
	s_mul_i32 s0, s94, 0x10800
	s_mov_b64 s[12:13], s[52:53]
	v_readlane_b32 s8, v255, 33
	s_add_u32 s0, s12, s0
	v_mov_b32_e32 v7, v246
	v_readlane_b32 s9, v255, 34
	s_waitcnt lgkmcnt(0)
	s_barrier
	s_mov_b32 s101, 0
	s_addc_u32 s1, s13, 0
	s_andn2_b64 vcc, exec, s[8:9]
	v_readfirstlane_b32 s8, v7
	v_readlane_b32 s41, v253, 21
	v_readlane_b32 s42, v253, 22
	v_readlane_b32 s43, v253, 23
	v_readlane_b32 s44, v253, 24
	v_readlane_b32 s45, v253, 25
	v_readlane_b32 s46, v253, 26
	v_readlane_b32 s47, v253, 27
	v_readlane_b32 s48, v253, 28
	v_readlane_b32 s49, v253, 29
	v_readlane_b32 s50, v253, 30
	v_readlane_b32 s51, v253, 31
	v_readlane_b32 s54, v253, 34
	v_readlane_b32 s55, v253, 35
	s_cbranch_vccnz .LBB0_1149
	v_lshlrev_b32_e32 v4, 4, v7
	v_add_u32_e32 v2, 0x2000, v4
	v_ashrrev_i32_e32 v0, 31, v2
	v_lshrrev_b32_e32 v0, 22, v0
	v_add_u32_e32 v0, v2, v0
	v_ashrrev_i32_e32 v0, 10, v0
	v_mul_i32_i24_e32 v3, 0x400, v0
	v_sub_u32_e32 v2, v2, v3
	v_lshrrev_b32_e32 v3, 4, v2
	v_bitop3_b32 v3, v3, v2, 32 bitop3:0x6c
	v_ashrrev_i32_e32 v2, 31, v3
	v_lshrrev_b32_e32 v2, 26, v2
	v_add_u32_e32 v5, v3, v2
	v_lshlrev_b32_e32 v6, 3, v0
	v_ashrrev_i32_e32 v2, 6, v5
	v_and_b32_e32 v6, -16, v6
	v_add_u32_e32 v6, v2, v6
	v_and_b32_e32 v8, 3, v2
	s_mov_b32 s10, 0x1fffe0
	v_lshrrev_b32_e32 v9, 2, v6
	v_lshlrev_b32_e32 v10, 1, v6
	v_and_b32_e32 v5, 0xc0, v5
	v_and_or_b32 v8, v6, s10, v8
	v_and_b32_e32 v9, 4, v9
	v_and_b32_e32 v10, 24, v10
	v_sub_u32_e32 v3, v3, v5
	v_or3_b32 v8, v8, v9, v10
	v_lshlrev_b32_e32 v9, 5, v0
	v_ashrrev_i16_sdwa v3, v248, sext(v3) dst_sel:DWORD dst_unused:UNUSED_PAD src0_sel:DWORD src1_sel:BYTE_0
	v_and_b32_e32 v9, 32, v9
	v_bfe_i32 v3, v3, 0, 16
	v_add_lshl_u32 v5, v9, v3, 1
	v_lshl_add_u32 v176, v8, 11, v5
	v_lshl_add_u32 v178, v6, 11, v5
	v_bfe_i32 v5, v7, 27, 1
	v_lshrrev_b32_e32 v5, 22, v5
	v_add_u32_e32 v5, v4, v5
	v_and_b32_e32 v5, 0xfffffc00, v5
	v_sub_u32_e32 v4, v4, v5
	v_lshrrev_b32_e32 v5, 4, v4
	v_bitop3_b32 v6, v5, v4, 32 bitop3:0x6c
	v_ashrrev_i32_e32 v5, 31, v7
	v_lshrrev_b32_e32 v5, 26, v5
	v_ashrrev_i32_e32 v4, 31, v4
	v_add_u32_e32 v5, v7, v5
	v_lshrrev_b32_e32 v4, 26, v4
	v_ashrrev_i32_e32 v5, 6, v5
	v_add_u32_e32 v4, v6, v4
	v_lshlrev_b32_e32 v8, 3, v5
	v_ashrrev_i32_e32 v4, 6, v4
	v_and_b32_e32 v8, -16, v8
	v_add_u32_e32 v8, v4, v8
	v_and_b32_e32 v9, 3, v4
	v_lshrrev_b32_e32 v10, 2, v8
	v_lshlrev_b32_e32 v11, 1, v8
	v_readlane_b32 s9, v254, 22
	v_and_or_b32 v9, v8, s10, v9
	v_and_b32_e32 v10, 4, v10
	v_and_b32_e32 v11, 24, v11
	s_add_u32 s12, s9, 0x1400000
	v_readlane_b32 s9, v254, 23
	v_or3_b32 v9, v9, v10, v11
	v_mul_i32_i24_e32 v11, 64, v4
	s_addc_u32 s13, s9, 0
	s_ashr_i32 s9, s8, 6
	v_sub_u32_e32 v6, v6, v11
	s_ashr_i32 s26, s8, 8
	s_lshl_b32 s38, s9, 10
	v_lshlrev_b32_e32 v10, 5, v5
	v_ashrrev_i16_sdwa v6, v248, sext(v6) dst_sel:DWORD dst_unused:UNUSED_PAD src0_sel:DWORD src1_sel:BYTE_0
	v_readlane_b32 s10, v255, 44
	v_and_b32_e32 v10, 32, v10
	v_bfe_i32 v6, v6, 0, 16
	v_readlane_b32 s11, v255, 45
	s_add_u32 s10, s12, s10
	v_add_lshl_u32 v10, v10, v6, 1
	s_addc_u32 s11, s13, s11
	s_add_i32 s39, s38, 0
	v_lshl_add_u32 v180, v9, 11, v10
	s_add_i32 m0, s39, 0x10000
	v_lshl_add_u32 v182, v8, 11, v10
	global_load_lds_dwordx4 v180, s[10:11]
	s_add_i32 m0, s39, 0x12000
	s_add_u32 s22, s10, 0x40000
	global_load_lds_dwordx4 v176, s[10:11]
	s_addc_u32 s23, s11, 0
	s_add_i32 m0, s39, 0x14000
	s_add_i32 s83, s39, 0x2000
	global_load_lds_dwordx4 v180, s[22:23]
	s_add_i32 m0, s39, 0x16000
	s_add_i32 s77, s39, 0x4000
	global_load_lds_dwordx4 v176, s[22:23]
	v_readlane_b32 s22, v255, 49
	s_mov_b32 m0, s39
	v_readlane_b32 s23, v255, 50
	s_add_i32 s33, s39, 0x6000
	s_cmp_eq_u32 s26, 1
	s_nop 2
	global_load_lds_dwordx4 v182, s[22:23]
	s_mov_b32 m0, s83
	s_nop 0
	global_load_lds_dwordx4 v178, s[22:23]
	v_readlane_b32 s22, v255, 51
	s_mov_b32 m0, s77
	v_readlane_b32 s23, v255, 52
	s_nop 4
	global_load_lds_dwordx4 v182, s[22:23]
	s_mov_b32 m0, s33
	s_nop 0
	global_load_lds_dwordx4 v178, s[22:23]
	s_cselect_b64 s[22:23], -1, 0
	s_cmp_lg_u32 s26, 1
	s_cbranch_scc1 .LBB0_1059
	s_barrier

; #define PG8_STAGE(bufoff, gbase, voff) do { _Pragma("unroll") for (int _i = 0; _i < 2; ++_i) \
;         __builtin_amdgcn_global_load_lds((const unsigned*)((const char*)(gbase) + (voff)[_i]), (LAS unsigned*)(lds + (bufoff) + ldsw + _i * 8192), 16, 0, 0); } while (0)
; #define PG8_LDA(dst, b, h) do { _Pragma("unroll") for (int m = 0; m < 4; ++m) _Pragma("unroll") for (int k = 0; k < 2; ++k) dst[m][k] = *(const LAS bf16x8*)(lds + PG8_SA(b, h) + aoff + m * 2048 + k * 1024); } while (0)
; #define PG8_LDB(dst, b, h) do { _Pragma("unroll") for (int n = 0; n < 2; ++n) _Pragma("unroll") for (int k = 0; k < 2; ++k) dst[n][k] = *(const LAS bf16x8*)(lds + PG8_SB(b, h) + boff + n * 2048 + k * 1024); } while (0)
; #define PG8_MMA(ai, bj, At, Bt) do { __builtin_amdgcn_s_setprio(1); _Pragma("unroll") for (int m = 0; m < 4; ++m) _Pragma("unroll") for (int n = 0; n < 2; ++n) _Pragma("unroll") for (int k = 0; k < 2; ++k) \
;         acc[ai][bj][m][n] = __builtin_amdgcn_mfma_f32_16x16x32_bf16(Bt[n][k], At[m][k], acc[ai][bj][m][n], 0, 0, 0); __builtin_amdgcn_s_setprio(0); } while (0)
; #define PG8_WAIT_V(n) asm volatile("s_waitcnt vmcnt(" #n ")" ::: "memory")
; template <class Epi, class Sched, int NSEG, int KK, int LDA, int LDB>
; __device__ __forceinline__ void gemm_phase(LAS unsigned char* lds, const Gemm g, const Sched& S, const Epi& E) {
;     ...
;         const bool has_next = S.next(ui + 1, nxt);
;         const char* nA = has_next ? PG8_APTR(nxt) : cA; const char* nB = has_next ? PG8_BPTR(nxt) : cB;
;         for (int t = 0; t < nt; t += 2) {
;             const bool last = (t == nt - 2);
;             const char* a1 = cA + (size_t)(t + 1) * kstep;
;             const char* a2 = last ? nA : cA + (size_t)(t + 2) * kstep; const char* b2 = last ? nB : cB + (size_t)(t + 2) * kstep;
;             const char* a3 = a2 + kstep; const char* b3 = b2 + kstep;
;             PG8_LDB(B0, 0, 0); PG8_LDB(B1, 0, 1); PG8_SCHED; PG8_LDA(At, 0, 0); PG8_STAGE(PG8_SA(1, 1), a1 + hstepA, voffA);
;             PG8_WAIT_V(8); PG8_WAIT_L(0); PG8_BAR; PG8_MMA(0, 0, At, B0); PG8_MMA(0, 1, At, B1); PG8_BAR; PG8_SCHED;
;             PG8_LDA(At, 0, 1); PG8_STAGE(PG8_SB(0, 0), b2, voffB); PG8_STAGE(PG8_SB(0, 1), b2 + hstepB, voffB); PG8_STAGE(PG8_SA(0, 0), a2, voffA);
;             PG8_WAIT_V(8); PG8_WAIT_L(0); PG8_BAR; PG8_MMA(1, 0, At, B0); PG8_MMA(1, 1, At, B1); PG8_BAR; PG8_SCHED;
.LBB0_1065:
	s_add_u32 s10, s42, 0xfffc0080
	s_addc_u32 s11, s43, -1
	s_add_i32 s55, 0, 0x10000
	s_cmp_eq_u32 s53, 12
	s_cselect_b32 s45, s46, s11
	s_cselect_b32 s44, s47, s10
	v_add_u32_e32 v0, s55, v252
	s_cselect_b32 s11, s48, s51
	s_cselect_b32 s10, s49, s50
	s_add_i32 s62, 0, 0x14000
	ds_read_b128 v[118:121], v0
	ds_read_b128 v[134:137], v0 offset:1024
	ds_read_b128 v[138:141], v0 offset:2048
	ds_read_b128 v[142:145], v0 offset:3072
	v_add_u32_e32 v0, s62, v252
	ds_read_b128 v[146:149], v0
	ds_read_b128 v[150:153], v0 offset:1024
	ds_read_b128 v[154:157], v0 offset:2048
	ds_read_b128 v[158:161], v0 offset:3072
	v_lshl_add_u64 v[172:173], s[42:43], 0, v[184:185]
	s_add_i32 m0, s39, 0xc000
	ds_read_b128 v[162:165], v166
	ds_read_b128 v[188:191], v166 offset:1024
	ds_read_b128 v[192:195], v166 offset:2048
	ds_read_b128 v[196:199], v166 offset:3072
	ds_read_b128 v[200:203], v166 offset:4096
	ds_read_b128 v[204:207], v166 offset:5120
	ds_read_b128 v[208:211], v166 offset:6144
	ds_read_b128 v[212:215], v166 offset:7168
	global_load_lds_dwordx4 v[172:173], off
	v_lshl_add_u64 v[172:173], s[42:43], 0, v[186:187]
	s_add_i32 m0, s39, 0xe000
	s_nop 0
	global_load_lds_dwordx4 v[172:173], off
	s_cmp_lg_u32 s101, 0
	s_cbranch_scc1 .Lskw_4_1
	s_waitcnt vmcnt(8)
.Lskw_4_1:
	s_waitcnt lgkmcnt(0)
	s_barrier
	s_setprio 1
	s_waitcnt lgkmcnt(0)
	v_mfma_f32_16x16x32_bf16 v[130:133], v[118:121], v[162:165], v[130:133]
	v_mfma_f32_16x16x32_bf16 v[126:129], v[138:141], v[162:165], v[126:129]
	v_mfma_f32_16x16x32_bf16 v[110:113], v[118:121], v[192:195], v[110:113]
	v_mfma_f32_16x16x32_bf16 v[46:49], v[138:141], v[192:195], v[46:49]
	v_mfma_f32_16x16x32_bf16 v[106:109], v[118:121], v[200:203], v[106:109]
	v_mfma_f32_16x16x32_bf16 v[42:45], v[138:141], v[200:203], v[42:45]
	v_mfma_f32_16x16x32_bf16 v[114:117], v[118:121], v[208:211], v[114:117]
	v_mfma_f32_16x16x32_bf16 v[50:53], v[138:141], v[208:211], v[50:53]
	v_mfma_f32_16x16x32_bf16 v[130:133], v[134:137], v[188:191], v[130:133]
	v_mfma_f32_16x16x32_bf16 v[126:129], v[142:145], v[188:191], v[126:129]
	v_mfma_f32_16x16x32_bf16 v[110:113], v[134:137], v[196:199], v[110:113]
	v_mfma_f32_16x16x32_bf16 v[46:49], v[142:145], v[196:199], v[46:49]
	v_mfma_f32_16x16x32_bf16 v[106:109], v[134:137], v[204:207], v[106:109]
	v_mfma_f32_16x16x32_bf16 v[42:45], v[142:145], v[204:207], v[42:45]
	v_mfma_f32_16x16x32_bf16 v[114:117], v[134:137], v[212:215], v[114:117]
	v_mfma_f32_16x16x32_bf16 v[50:53], v[142:145], v[212:215], v[50:53]
	s_setprio 0
	s_setprio 1
	v_mfma_f32_16x16x32_bf16 v[122:125], v[146:149], v[162:165], v[122:125]
	v_mfma_f32_16x16x32_bf16 v[62:65], v[154:157], v[162:165], v[62:65]
	v_mfma_f32_16x16x32_bf16 v[102:105], v[146:149], v[192:195], v[102:105]
	v_mfma_f32_16x16x32_bf16 v[38:41], v[154:157], v[192:195], v[38:41]
	v_mfma_f32_16x16x32_bf16 v[98:101], v[146:149], v[200:203], v[98:101]
	v_mfma_f32_16x16x32_bf16 v[34:37], v[154:157], v[200:203], v[34:37]
	v_mfma_f32_16x16x32_bf16 v[90:93], v[146:149], v[208:211], v[90:93]
	v_mfma_f32_16x16x32_bf16 v[54:57], v[154:157], v[208:211], v[54:57]
	v_mfma_f32_16x16x32_bf16 v[122:125], v[150:153], v[188:191], v[122:125]
	v_mfma_f32_16x16x32_bf16 v[62:65], v[158:161], v[188:191], v[62:65]
	v_mfma_f32_16x16x32_bf16 v[102:105], v[150:153], v[196:199], v[102:105]
	v_mfma_f32_16x16x32_bf16 v[38:41], v[158:161], v[196:199], v[38:41]
	v_mfma_f32_16x16x32_bf16 v[98:101], v[150:153], v[204:207], v[98:101]
	v_mfma_f32_16x16x32_bf16 v[34:37], v[158:161], v[204:207], v[34:37]
	v_mfma_f32_16x16x32_bf16 v[90:93], v[150:153], v[212:215], v[90:93]
	v_mfma_f32_16x16x32_bf16 v[54:57], v[158:161], v[212:215], v[54:57]
	s_setprio 0
	s_barrier
	s_add_i32 s55, s55, s38
	v_lshl_add_u64 v[172:173], s[10:11], 0, v[180:181]
	s_mov_b32 m0, s55
	ds_read_b128 v[162:165], v166 offset:16384
	ds_read_b128 v[188:191], v166 offset:17408
	ds_read_b128 v[192:195], v166 offset:18432
	ds_read_b128 v[196:199], v166 offset:19456
	ds_read_b128 v[200:203], v166 offset:20480
	ds_read_b128 v[204:207], v166 offset:21504
	ds_read_b128 v[208:211], v166 offset:22528
	ds_read_b128 v[212:215], v166 offset:23552
	global_load_lds_dwordx4 v[172:173], off
	s_add_i32 m0, s55, 0x2000
	s_add_u32 s60, s10, 0x40000
	v_lshl_add_u64 v[216:217], s[10:11], 0, v[176:177]
	s_addc_u32 s61, s11, 0
	s_add_i32 s55, s62, s38
	global_load_lds_dwordx4 v[216:217], off
	v_lshl_add_u64 v[218:219], s[60:61], 0, v[180:181]
	s_mov_b32 m0, s55
	v_lshl_add_u64 v[220:221], s[44:45], 0, v[178:179]
	global_load_lds_dwordx4 v[218:219], off
	v_lshl_add_u64 v[218:219], s[60:61], 0, v[176:177]
	s_add_i32 m0, s55, 0x2000
	s_nop 0
	global_load_lds_dwordx4 v[218:219], off
	v_lshl_add_u64 v[218:219], s[44:45], 0, v[182:183]
	s_mov_b32 m0, s39
	s_nop 0
	global_load_lds_dwordx4 v[218:219], off
	s_mov_b32 m0, s83
	s_nop 0
	global_load_lds_dwordx4 v[220:221], off
	s_cmp_lg_u32 s101, 0
	s_cbranch_scc1 .Lskw_4_2
	s_waitcnt vmcnt(8)
; #define PG8_STAGE(bufoff, gbase, voff) do { _Pragma("unroll") for (int _i = 0; _i < 2; ++_i) \
;         __builtin_amdgcn_global_load_lds((const unsigned*)((const char*)(gbase) + (voff)[_i]), (LAS unsigned*)(lds + (bufoff) + ldsw + _i * 8192), 16, 0, 0); } while (0)
; #define PG8_LDA(dst, b, h) do { _Pragma("unroll") for (int m = 0; m < 4; ++m) _Pragma("unroll") for (int k = 0; k < 2; ++k) dst[m][k] = *(const LAS bf16x8*)(lds + PG8_SA(b, h) + aoff + m * 2048 + k * 1024); } while (0)
; #define PG8_LDB(dst, b, h) do { _Pragma("unroll") for (int n = 0; n < 2; ++n) _Pragma("unroll") for (int k = 0; k < 2; ++k) dst[n][k] = *(const LAS bf16x8*)(lds + PG8_SB(b, h) + boff + n * 2048 + k * 1024); } while (0)
; #define PG8_MMA(ai, bj, At, Bt) do { __builtin_amdgcn_s_setprio(1); _Pragma("unroll") for (int m = 0; m < 4; ++m) _Pragma("unroll") for (int n = 0; n < 2; ++n) _Pragma("unroll") for (int k = 0; k < 2; ++k) \
;         acc[ai][bj][m][n] = __builtin_amdgcn_mfma_f32_16x16x32_bf16(Bt[n][k], At[m][k], acc[ai][bj][m][n], 0, 0, 0); __builtin_amdgcn_s_setprio(0); } while (0)
; #define PG8_WAIT_V(n) asm volatile("s_waitcnt vmcnt(" #n ")" ::: "memory")
; #define PG8_WAIT_L(n) asm volatile("s_waitcnt lgkmcnt(" #n ")" ::: "memory")
; #define PG8_BAR __builtin_amdgcn_s_barrier()
; #define PG8_SCHED __builtin_amdgcn_sched_barrier(0)
; template <class Epi, class Sched, int NSEG, int KK, int LDA, int LDB>
; __device__ __forceinline__ void gemm_phase(LAS unsigned char* lds, const Gemm g, const Sched& S, const Epi& E) {
;     ...
;             PG8_WAIT_V(8); PG8_WAIT_L(0); PG8_BAR; PG8_MMA(1, 0, At, B0); PG8_MMA(1, 1, At, B1); PG8_BAR; PG8_SCHED;
;             PG8_LDB(B0, 1, 0); PG8_LDB(B1, 1, 1); PG8_SCHED; PG8_LDA(At, 1, 0); PG8_STAGE(PG8_SA(0, 1), a2 + hstepA, voffA);
;             PG8_WAIT_V(8); PG8_WAIT_L(0); PG8_BAR; PG8_MMA(0, 0, At, B0); PG8_MMA(0, 1, At, B1); PG8_BAR; PG8_SCHED;
.Lskw_4_2:
	s_mov_b32 s101, 0
	s_waitcnt lgkmcnt(0)
	s_barrier
	s_setprio 1
	s_waitcnt lgkmcnt(0)
	v_mfma_f32_16x16x32_bf16 v[94:97], v[118:121], v[162:165], v[94:97]
	v_mfma_f32_16x16x32_bf16 v[22:25], v[138:141], v[162:165], v[22:25]
	v_mfma_f32_16x16x32_bf16 v[86:89], v[118:121], v[192:195], v[86:89]
	v_mfma_f32_16x16x32_bf16 v[18:21], v[138:141], v[192:195], v[18:21]
	v_mfma_f32_16x16x32_bf16 v[74:77], v[118:121], v[200:203], v[74:77]
	v_mfma_f32_16x16x32_bf16 v[10:13], v[138:141], v[200:203], v[10:13]
	v_mfma_f32_16x16x32_bf16 v[82:85], v[118:121], v[208:211], v[82:85]
	v_mfma_f32_16x16x32_bf16 v[26:29], v[138:141], v[208:211], v[26:29]
	v_mfma_f32_16x16x32_bf16 v[94:97], v[134:137], v[188:191], v[94:97]
	v_mfma_f32_16x16x32_bf16 v[22:25], v[142:145], v[188:191], v[22:25]
	v_mfma_f32_16x16x32_bf16 v[86:89], v[134:137], v[196:199], v[86:89]
	v_mfma_f32_16x16x32_bf16 v[18:21], v[142:145], v[196:199], v[18:21]
	v_mfma_f32_16x16x32_bf16 v[74:77], v[134:137], v[204:207], v[74:77]
	v_mfma_f32_16x16x32_bf16 v[10:13], v[142:145], v[204:207], v[10:13]
	v_mfma_f32_16x16x32_bf16 v[82:85], v[134:137], v[212:215], v[82:85]
	v_mfma_f32_16x16x32_bf16 v[26:29], v[142:145], v[212:215], v[26:29]
	s_setprio 0
	s_setprio 1
	v_mfma_f32_16x16x32_bf16 v[78:81], v[146:149], v[162:165], v[78:81]
	v_mfma_f32_16x16x32_bf16 v[14:17], v[154:157], v[162:165], v[14:17]
	v_mfma_f32_16x16x32_bf16 v[70:73], v[146:149], v[192:195], v[70:73]
	v_mfma_f32_16x16x32_bf16 v[6:9], v[154:157], v[192:195], v[6:9]
	v_mfma_f32_16x16x32_bf16 v[66:69], v[146:149], v[200:203], v[66:69]
	v_mfma_f32_16x16x32_bf16 v[2:5], v[154:157], v[200:203], v[2:5]
	v_mfma_f32_16x16x32_bf16 v[58:61], v[146:149], v[208:211], v[58:61]
	v_mfma_f32_16x16x32_bf16 v[30:33], v[154:157], v[208:211], v[30:33]
	v_mfma_f32_16x16x32_bf16 v[78:81], v[150:153], v[188:191], v[78:81]
	v_mfma_f32_16x16x32_bf16 v[14:17], v[158:161], v[188:191], v[14:17]
	v_mfma_f32_16x16x32_bf16 v[70:73], v[150:153], v[196:199], v[70:73]
	v_mfma_f32_16x16x32_bf16 v[6:9], v[158:161], v[196:199], v[6:9]
	v_mfma_f32_16x16x32_bf16 v[66:69], v[150:153], v[204:207], v[66:69]
	v_mfma_f32_16x16x32_bf16 v[2:5], v[158:161], v[204:207], v[2:5]
	v_mfma_f32_16x16x32_bf16 v[58:61], v[150:153], v[212:215], v[58:61]
	v_mfma_f32_16x16x32_bf16 v[30:33], v[158:161], v[212:215], v[30:33]
	s_setprio 0
	s_barrier
	s_add_i32 s55, 0, 0x18000
	v_add_u32_e32 v0, s55, v252
	s_add_i32 s60, 0, 0x1c000
	ds_read_b128 v[118:121], v0
	ds_read_b128 v[134:137], v0 offset:1024
	ds_read_b128 v[138:141], v0 offset:2048
	ds_read_b128 v[142:145], v0 offset:3072
	v_add_u32_e32 v0, s60, v252
	ds_read_b128 v[146:149], v0
	ds_read_b128 v[150:153], v0 offset:1024
	ds_read_b128 v[154:157], v0 offset:2048
	ds_read_b128 v[158:161], v0 offset:3072
	s_add_u32 s44, s44, 0x40000
	s_addc_u32 s45, s45, 0
	s_mov_b32 m0, s77
	v_lshl_add_u64 v[222:223], s[44:45], 0, v[182:183]
	ds_read_b128 v[162:165], v166 offset:32768
	ds_read_b128 v[188:191], v166 offset:33792
	ds_read_b128 v[192:195], v166 offset:34816
	ds_read_b128 v[196:199], v166 offset:35840
	ds_read_b128 v[200:203], v166 offset:36864
	ds_read_b128 v[204:207], v166 offset:37888
	ds_read_b128 v[208:211], v166 offset:38912
	ds_read_b128 v[212:215], v166 offset:39936
	global_load_lds_dwordx4 v[222:223], off
	v_lshl_add_u64 v[222:223], s[44:45], 0, v[178:179]
	s_mov_b32 m0, s33
	s_nop 0
	global_load_lds_dwordx4 v[222:223], off
	s_waitcnt vmcnt(8)
	s_waitcnt lgkmcnt(0)
	s_barrier
	s_setprio 1
	s_waitcnt lgkmcnt(0)
	v_mfma_f32_16x16x32_bf16 v[130:133], v[118:121], v[162:165], v[130:133]
	v_mfma_f32_16x16x32_bf16 v[126:129], v[138:141], v[162:165], v[126:129]
	v_mfma_f32_16x16x32_bf16 v[110:113], v[118:121], v[192:195], v[110:113]
	v_mfma_f32_16x16x32_bf16 v[46:49], v[138:141], v[192:195], v[46:49]
	v_mfma_f32_16x16x32_bf16 v[106:109], v[118:121], v[200:203], v[106:109]
	v_mfma_f32_16x16x32_bf16 v[42:45], v[138:141], v[200:203], v[42:45]
	v_mfma_f32_16x16x32_bf16 v[114:117], v[118:121], v[208:211], v[114:117]
	v_mfma_f32_16x16x32_bf16 v[50:53], v[138:141], v[208:211], v[50:53]
	v_mfma_f32_16x16x32_bf16 v[130:133], v[134:137], v[188:191], v[130:133]
	v_mfma_f32_16x16x32_bf16 v[126:129], v[142:145], v[188:191], v[126:129]
	v_mfma_f32_16x16x32_bf16 v[110:113], v[134:137], v[196:199], v[110:113]
	v_mfma_f32_16x16x32_bf16 v[46:49], v[142:145], v[196:199], v[46:49]
	v_mfma_f32_16x16x32_bf16 v[106:109], v[134:137], v[204:207], v[106:109]
	v_mfma_f32_16x16x32_bf16 v[42:45], v[142:145], v[204:207], v[42:45]
	v_mfma_f32_16x16x32_bf16 v[114:117], v[134:137], v[212:215], v[114:117]
	v_mfma_f32_16x16x32_bf16 v[50:53], v[142:145], v[212:215], v[50:53]
	s_setprio 0
	s_setprio 1
	v_mfma_f32_16x16x32_bf16 v[122:125], v[146:149], v[162:165], v[122:125]
	v_mfma_f32_16x16x32_bf16 v[62:65], v[154:157], v[162:165], v[62:65]
	v_mfma_f32_16x16x32_bf16 v[102:105], v[146:149], v[192:195], v[102:105]
	v_mfma_f32_16x16x32_bf16 v[38:41], v[154:157], v[192:195], v[38:41]
	v_mfma_f32_16x16x32_bf16 v[98:101], v[146:149], v[200:203], v[98:101]
	v_mfma_f32_16x16x32_bf16 v[34:37], v[154:157], v[200:203], v[34:37]
	v_mfma_f32_16x16x32_bf16 v[90:93], v[146:149], v[208:211], v[90:93]
	v_mfma_f32_16x16x32_bf16 v[54:57], v[154:157], v[208:211], v[54:57]
	v_mfma_f32_16x16x32_bf16 v[122:125], v[150:153], v[188:191], v[122:125]
	v_mfma_f32_16x16x32_bf16 v[62:65], v[158:161], v[188:191], v[62:65]
	v_mfma_f32_16x16x32_bf16 v[102:105], v[150:153], v[196:199], v[102:105]
	v_mfma_f32_16x16x32_bf16 v[38:41], v[158:161], v[196:199], v[38:41]
	v_mfma_f32_16x16x32_bf16 v[98:101], v[150:153], v[204:207], v[98:101]
	v_mfma_f32_16x16x32_bf16 v[34:37], v[158:161], v[204:207], v[34:37]
	v_mfma_f32_16x16x32_bf16 v[90:93], v[150:153], v[212:215], v[90:93]
	v_mfma_f32_16x16x32_bf16 v[54:57], v[158:161], v[212:215], v[54:57]
	s_setprio 0
	s_barrier
; #define PG8_STAGE(bufoff, gbase, voff) do { _Pragma("unroll") for (int _i = 0; _i < 2; ++_i) \
;         __builtin_amdgcn_global_load_lds((const unsigned*)((const char*)(gbase) + (voff)[_i]), (LAS unsigned*)(lds + (bufoff) + ldsw + _i * 8192), 16, 0, 0); } while (0)
; #define PG8_LDA(dst, b, h) do { _Pragma("unroll") for (int m = 0; m < 4; ++m) _Pragma("unroll") for (int k = 0; k < 2; ++k) dst[m][k] = *(const LAS bf16x8*)(lds + PG8_SA(b, h) + aoff + m * 2048 + k * 1024); } while (0)
; #define PG8_MMA(ai, bj, At, Bt) do { __builtin_amdgcn_s_setprio(1); _Pragma("unroll") for (int m = 0; m < 4; ++m) _Pragma("unroll") for (int n = 0; n < 2; ++n) _Pragma("unroll") for (int k = 0; k < 2; ++k) \
;         acc[ai][bj][m][n] = __builtin_amdgcn_mfma_f32_16x16x32_bf16(Bt[n][k], At[m][k], acc[ai][bj][m][n], 0, 0, 0); __builtin_amdgcn_s_setprio(0); } while (0)
; #define PG8_WAIT_V(n) asm volatile("s_waitcnt vmcnt(" #n ")" ::: "memory")
; #define PG8_WAIT_L(n) asm volatile("s_waitcnt lgkmcnt(" #n ")" ::: "memory")
; #define PG8_BAR __builtin_amdgcn_s_barrier()
; #define PG8_SCHED __builtin_amdgcn_sched_barrier(0)
; template <class Epi, class Sched, int NSEG, int KK, int LDA, int LDB>
; __device__ __forceinline__ void gemm_phase(LAS unsigned char* lds, const Gemm g, const Sched& S, const Epi& E) {
;     ...
;             PG8_LDA(At, 1, 1); PG8_STAGE(PG8_SB(1, 0), b3, voffB); PG8_STAGE(PG8_SB(1, 1), b3 + hstepB, voffB); PG8_STAGE(PG8_SA(1, 0), a3, voffA);
;             PG8_WAIT_V(8); PG8_WAIT_L(0); PG8_BAR; PG8_MMA(1, 0, At, B0); PG8_MMA(1, 1, At, B1); PG8_BAR; PG8_SCHED;
;         }
;         if (wr == 0) PG8_BAR;
	s_add_i32 s44, s55, s38
	v_lshl_add_u64 v[172:173], v[172:173], 0, s[28:29]
	s_mov_b32 m0, s44
	ds_read_b128 v[162:165], v166 offset:49152
	ds_read_b128 v[188:191], v166 offset:50176
	ds_read_b128 v[192:195], v166 offset:51200
	ds_read_b128 v[196:199], v166 offset:52224
	ds_read_b128 v[200:203], v166 offset:53248
	ds_read_b128 v[204:207], v166 offset:54272
	ds_read_b128 v[208:211], v166 offset:55296
	ds_read_b128 v[212:215], v166 offset:56320
	global_load_lds_dwordx4 v[172:173], off
	s_add_i32 m0, s44, 0x2000
	s_add_u32 s10, s10, 0x40080
	v_lshl_add_u64 v[172:173], v[216:217], 0, s[28:29]
	s_addc_u32 s11, s11, 0
	s_add_i32 s44, s60, s38
	global_load_lds_dwordx4 v[172:173], off
	v_lshl_add_u64 v[172:173], s[10:11], 0, v[180:181]
	s_mov_b32 m0, s44
	s_nop 0
	global_load_lds_dwordx4 v[172:173], off
	v_lshl_add_u64 v[172:173], s[10:11], 0, v[176:177]
	s_add_i32 m0, s44, 0x2000
	s_nop 0
	global_load_lds_dwordx4 v[172:173], off
	v_lshl_add_u64 v[172:173], v[218:219], 0, s[28:29]
	s_mov_b32 m0, s91
	s_nop 0
	global_load_lds_dwordx4 v[172:173], off
	v_lshl_add_u64 v[172:173], v[220:221], 0, s[28:29]
	s_mov_b32 m0, s94
	s_nop 0
	global_load_lds_dwordx4 v[172:173], off
	s_waitcnt vmcnt(8)
	s_waitcnt lgkmcnt(0)
	s_barrier
	s_setprio 1
	s_waitcnt lgkmcnt(0)
	v_mfma_f32_16x16x32_bf16 v[94:97], v[118:121], v[162:165], v[94:97]
	v_mfma_f32_16x16x32_bf16 v[22:25], v[138:141], v[162:165], v[22:25]
	v_mfma_f32_16x16x32_bf16 v[86:89], v[118:121], v[192:195], v[86:89]
	v_mfma_f32_16x16x32_bf16 v[18:21], v[138:141], v[192:195], v[18:21]
	v_mfma_f32_16x16x32_bf16 v[74:77], v[118:121], v[200:203], v[74:77]
	v_mfma_f32_16x16x32_bf16 v[10:13], v[138:141], v[200:203], v[10:13]
	v_mfma_f32_16x16x32_bf16 v[82:85], v[118:121], v[208:211], v[82:85]
	v_mfma_f32_16x16x32_bf16 v[26:29], v[138:141], v[208:211], v[26:29]
	v_mfma_f32_16x16x32_bf16 v[94:97], v[134:137], v[188:191], v[94:97]
	v_mfma_f32_16x16x32_bf16 v[22:25], v[142:145], v[188:191], v[22:25]
	v_mfma_f32_16x16x32_bf16 v[86:89], v[134:137], v[196:199], v[86:89]
	v_mfma_f32_16x16x32_bf16 v[18:21], v[142:145], v[196:199], v[18:21]
	v_mfma_f32_16x16x32_bf16 v[74:77], v[134:137], v[204:207], v[74:77]
	v_mfma_f32_16x16x32_bf16 v[10:13], v[142:145], v[204:207], v[10:13]
	v_mfma_f32_16x16x32_bf16 v[82:85], v[134:137], v[212:215], v[82:85]
	v_mfma_f32_16x16x32_bf16 v[26:29], v[142:145], v[212:215], v[26:29]
	s_setprio 0
	s_setprio 1
	v_mfma_f32_16x16x32_bf16 v[78:81], v[146:149], v[162:165], v[78:81]
	v_mfma_f32_16x16x32_bf16 v[14:17], v[154:157], v[162:165], v[14:17]
	v_mfma_f32_16x16x32_bf16 v[70:73], v[146:149], v[192:195], v[70:73]
	v_mfma_f32_16x16x32_bf16 v[6:9], v[154:157], v[192:195], v[6:9]
	v_mfma_f32_16x16x32_bf16 v[66:69], v[146:149], v[200:203], v[66:69]
	v_mfma_f32_16x16x32_bf16 v[2:5], v[154:157], v[200:203], v[2:5]
	v_mfma_f32_16x16x32_bf16 v[58:61], v[146:149], v[208:211], v[58:61]
	v_mfma_f32_16x16x32_bf16 v[30:33], v[154:157], v[208:211], v[30:33]
	v_mfma_f32_16x16x32_bf16 v[78:81], v[150:153], v[188:191], v[78:81]
	v_mfma_f32_16x16x32_bf16 v[14:17], v[158:161], v[188:191], v[14:17]
	v_mfma_f32_16x16x32_bf16 v[70:73], v[150:153], v[196:199], v[70:73]
	v_mfma_f32_16x16x32_bf16 v[6:9], v[158:161], v[196:199], v[6:9]
	v_mfma_f32_16x16x32_bf16 v[66:69], v[150:153], v[204:207], v[66:69]
	v_mfma_f32_16x16x32_bf16 v[2:5], v[158:161], v[204:207], v[2:5]
	v_mfma_f32_16x16x32_bf16 v[58:61], v[150:153], v[212:215], v[58:61]
	v_mfma_f32_16x16x32_bf16 v[30:33], v[158:161], v[212:215], v[30:33]
	s_setprio 0
	s_barrier
	s_add_i32 s53, s53, 2
	s_add_u32 s42, s42, 0x100
	s_addc_u32 s43, s43, 0
	s_add_u32 s50, s50, 0x100
	s_addc_u32 s51, s51, 0
	s_cmp_gt_u32 s53, 13
	s_cbranch_scc0 .LBB0_1065
	s_mov_b32 s101, 1
	s_and_b64 vcc, exec, s[24:25]
	s_cbranch_vccz .LBB0_1068
	s_barrier

; #define FRESH_IDS() const int tid = fresh_tid(), lane = tid & 63, wave = __builtin_amdgcn_readfirstlane(tid >> 6), gw = blk * 8 + wave; (void)lane; (void)gw
; __global__ void __launch_bounds__(NTHREADS, 2) mega_fwd(Args args) {
;     ...
;             {
;                 FRESH_IDS();
;                 const float* fw = args.in[14] + (size_t)l * 3 * DFF2;
;                 pg8::Unit fu;
;                 for (int i = 0; S.next(i, fu); ++i) {
;                     const int pm = fu.pm; const bool first = (pm & 15) == 0;
;                     const float* P0 = PRE + (size_t)pm * 4 * DFF2; const float* Pp = PRE + (size_t)(pm - 1) * 4 * DFF2;
;                     float fx0[6][2], fx1[6][2], fm2[6][2], fm1[6][2], fw0[6][2], fw1[6][2], fw2[6][2];
; #pragma unroll
;                     for (int k = 0; k < 6; ++k) { const int c = tid + k * NTHREADS;
; #pragma unroll
;                         for (int hbj = 0; hbj < 2; ++hbj) { const int cc = (c < DFF ? c : tid) + hbj * DFF;
;                             fx0[k][hbj] = P0[cc]; fx1[k][hbj] = P0[DFF2 + cc]; fm2[k][hbj] = first ? 0.f : Pp[2 * DFF2 + cc]; fm1[k][hbj] = first ? 0.f : Pp[3 * DFF2 + cc];
;                             fw0[k][hbj] = fw[cc]; fw1[k][hbj] = fw[DFF2 + cc]; fw2[k][hbj] = fw[2 * DFF2 + cc]; } }
.LBB0_1193:
	s_or_b64 exec, exec, s[8:9]
	v_mov_b32_e32 v2, v246
	s_movk_i32 s8, 0x900
	s_waitcnt lgkmcnt(0)
	s_barrier
	s_mov_b32 s101, 0
	s_mov_b64 s[10:11], 0x5800
	v_cmp_gt_i32_e64 s[40:41], s8, v2
	s_movk_i32 s8, 0x700
	v_cmp_gt_i32_e64 s[42:43], s8, v2
	s_movk_i32 s8, 0x500
	v_add_u32_e32 v0, 0x200, v2
	v_cmp_gt_i32_e64 s[44:45], s8, v2
	s_movk_i32 s8, 0x300
	v_cndmask_b32_e64 v18, v2, v0, s[40:41]
	v_add_u32_e32 v0, 0x400, v2
	v_cmp_gt_i32_e64 s[46:47], s8, v2
	s_movk_i32 s8, 0x100
	v_cndmask_b32_e64 v34, v2, v0, s[42:43]
	v_add_u32_e32 v0, 0x600, v2
	v_add_u32_e32 v98, 0x800, v2
	v_add_u32_e32 v100, 0xa00, v2
	v_cmp_gt_i32_e64 s[48:49], s8, v2
	v_cndmask_b32_e64 v50, v2, v0, s[44:45]
	v_cndmask_b32_e64 v66, v2, v98, s[46:47]
	v_cndmask_b32_e64 v82, v2, v100, s[48:49]
	v_ashrrev_i32_e32 v3, 31, v2
	v_ashrrev_i32_e32 v19, 31, v18
	v_ashrrev_i32_e32 v35, 31, v34
	v_ashrrev_i32_e32 v51, 31, v50
	v_ashrrev_i32_e32 v67, 31, v66
	v_ashrrev_i32_e32 v83, 31, v82
	v_lshl_add_u64 v[4:5], v[2:3], 2, s[0:1]
	s_mov_b64 s[12:13], 0xb000
	v_add_u32_e32 v10, 0xb00, v2
	s_mov_b64 s[22:23], 0x2c00
	s_mov_b64 s[24:25], 0x8400
	s_mov_b64 s[38:39], 0xdc00
	v_lshl_add_u64 v[20:21], v[18:19], 2, s[0:1]
	v_add_u32_e32 v26, 0xb00, v18
	v_lshl_add_u64 v[36:37], v[34:35], 2, s[0:1]
	v_add_u32_e32 v42, 0xb00, v34
	v_lshl_add_u64 v[52:53], v[50:51], 2, s[0:1]
	v_add_u32_e32 v58, 0xb00, v50
	v_lshl_add_u64 v[68:69], v[66:67], 2, s[0:1]
	v_add_u32_e32 v74, 0xb00, v66
	v_lshl_add_u64 v[84:85], v[82:83], 2, s[0:1]
	v_add_u32_e32 v90, 0xb00, v82
	s_movk_i32 s0, 0xb00
	v_ashrrev_i32_e32 v99, 31, v98
	v_ashrrev_i32_e32 v101, 31, v100
	v_lshl_add_u64 v[6:7], v[4:5], 0, s[10:11]
	v_lshl_add_u64 v[8:9], v[4:5], 0, s[12:13]
	v_ashrrev_i32_e32 v11, 31, v10
	v_lshl_add_u64 v[12:13], v[4:5], 0, s[22:23]
	v_lshl_add_u64 v[14:15], v[4:5], 0, s[24:25]
	v_lshl_add_u64 v[16:17], v[4:5], 0, s[38:39]
	v_lshl_add_u64 v[22:23], v[20:21], 0, s[10:11]
	v_lshl_add_u64 v[24:25], v[20:21], 0, s[12:13]
	v_ashrrev_i32_e32 v27, 31, v26
	v_lshl_add_u64 v[28:29], v[20:21], 0, s[22:23]
	v_lshl_add_u64 v[30:31], v[20:21], 0, s[24:25]
	v_lshl_add_u64 v[32:33], v[20:21], 0, s[38:39]
	v_lshl_add_u64 v[38:39], v[36:37], 0, s[10:11]
	v_lshl_add_u64 v[40:41], v[36:37], 0, s[12:13]
	v_ashrrev_i32_e32 v43, 31, v42
	v_lshl_add_u64 v[44:45], v[36:37], 0, s[22:23]
	v_lshl_add_u64 v[46:47], v[36:37], 0, s[24:25]
	v_lshl_add_u64 v[48:49], v[36:37], 0, s[38:39]
	v_lshl_add_u64 v[54:55], v[52:53], 0, s[10:11]
	v_lshl_add_u64 v[56:57], v[52:53], 0, s[12:13]
	v_ashrrev_i32_e32 v59, 31, v58
	v_lshl_add_u64 v[60:61], v[52:53], 0, s[22:23]
	v_lshl_add_u64 v[62:63], v[52:53], 0, s[24:25]
	v_lshl_add_u64 v[64:65], v[52:53], 0, s[38:39]
	v_lshl_add_u64 v[70:71], v[68:69], 0, s[10:11]
	v_lshl_add_u64 v[72:73], v[68:69], 0, s[12:13]
	v_ashrrev_i32_e32 v75, 31, v74
	v_lshl_add_u64 v[76:77], v[68:69], 0, s[22:23]
	v_lshl_add_u64 v[78:79], v[68:69], 0, s[24:25]
	v_lshl_add_u64 v[80:81], v[68:69], 0, s[38:39]
	v_lshl_add_u64 v[86:87], v[84:85], 0, s[10:11]
	v_lshl_add_u64 v[88:89], v[84:85], 0, s[12:13]
	v_ashrrev_i32_e32 v91, 31, v90
	v_lshl_add_u64 v[92:93], v[84:85], 0, s[22:23]
	v_lshl_add_u64 v[94:95], v[84:85], 0, s[24:25]
	v_lshl_add_u64 v[96:97], v[84:85], 0, s[38:39]
	v_cmp_gt_i32_e64 s[50:51], s0, v2
	v_lshlrev_b64 v[98:99], 1, v[98:99]
	v_lshlrev_b64 v[100:101], 1, v[100:101]
	s_mov_b64 s[0:1], s[2:3]
	s_branch .LBB0_1196

; #define PG8_STAGE(bufoff, gbase, voff) do { _Pragma("unroll") for (int _i = 0; _i < 2; ++_i) \
;         __builtin_amdgcn_global_load_lds((const unsigned*)((const char*)(gbase) + (voff)[_i]), (LAS unsigned*)(lds + (bufoff) + ldsw + _i * 8192), 16, 0, 0); } while (0)
; #define PG8_LDA(dst, b, h) do { _Pragma("unroll") for (int m = 0; m < 4; ++m) _Pragma("unroll") for (int k = 0; k < 2; ++k) dst[m][k] = *(const LAS bf16x8*)(lds + PG8_SA(b, h) + aoff + m * 2048 + k * 1024); } while (0)
; #define PG8_LDB(dst, b, h) do { _Pragma("unroll") for (int n = 0; n < 2; ++n) _Pragma("unroll") for (int k = 0; k < 2; ++k) dst[n][k] = *(const LAS bf16x8*)(lds + PG8_SB(b, h) + boff + n * 2048 + k * 1024); } while (0)
; #define PG8_MMA(ai, bj, At, Bt) do { __builtin_amdgcn_s_setprio(1); _Pragma("unroll") for (int m = 0; m < 4; ++m) _Pragma("unroll") for (int n = 0; n < 2; ++n) _Pragma("unroll") for (int k = 0; k < 2; ++k) \
;         acc[ai][bj][m][n] = __builtin_amdgcn_mfma_f32_16x16x32_bf16(Bt[n][k], At[m][k], acc[ai][bj][m][n], 0, 0, 0); __builtin_amdgcn_s_setprio(0); } while (0)
; #define PG8_WAIT_V(n) asm volatile("s_waitcnt vmcnt(" #n ")" ::: "memory")
; template <class Epi, class Sched, int NSEG, int KK, int LDA, int LDB>
; __device__ __forceinline__ void gemm_phase(LAS unsigned char* lds, const Gemm g, const Sched& S, const Epi& E) {
;     ...
;         const bool has_next = S.next(ui + 1, nxt);
;         const char* nA = has_next ? PG8_APTR(nxt) : cA; const char* nB = has_next ? PG8_BPTR(nxt) : cB;
;         for (int t = 0; t < nt; t += 2) {
;             const bool last = (t == nt - 2);
;             const char* a1 = cA + (size_t)(t + 1) * kstep;
;             const char* a2 = last ? nA : cA + (size_t)(t + 2) * kstep; const char* b2 = last ? nB : cB + (size_t)(t + 2) * kstep;
;             const char* a3 = a2 + kstep; const char* b3 = b2 + kstep;
;             PG8_LDB(B0, 0, 0); PG8_LDB(B1, 0, 1); PG8_SCHED; PG8_LDA(At, 0, 0); PG8_STAGE(PG8_SA(1, 1), a1 + hstepA, voffA);
;             PG8_WAIT_V(8); PG8_WAIT_L(0); PG8_BAR; PG8_MMA(0, 0, At, B0); PG8_MMA(0, 1, At, B1); PG8_BAR; PG8_SCHED;
;             PG8_LDA(At, 0, 1); PG8_STAGE(PG8_SB(0, 0), b2, voffB); PG8_STAGE(PG8_SB(0, 1), b2 + hstepB, voffB); PG8_STAGE(PG8_SA(0, 0), a2, voffA);
;             PG8_WAIT_V(8); PG8_WAIT_L(0); PG8_BAR; PG8_MMA(1, 0, At, B0); PG8_MMA(1, 1, At, B1); PG8_BAR; PG8_SCHED;
.LBB0_1258:
	s_add_u32 s40, s42, 0x100
	s_addc_u32 s41, s43, 0
	s_add_i32 s61, 0, 0x10000
	s_cmp_eq_u32 s60, 40
	s_cselect_b32 s47, s25, s41
	s_cselect_b32 s46, s24, s40
	s_cselect_b32 s11, s45, s59
	s_cselect_b32 s10, s44, s58
	s_add_i32 s62, 0, 0x14000
	v_add_u32_e32 v148, s61, v164
	v_add_u32_e32 v166, s62, v164
	ds_read_b128 v[136:139], v148
	ds_read_b128 v[140:143], v148 offset:1024
	ds_read_b128 v[144:147], v148 offset:256
	ds_read_b128 v[148:151], v148 offset:1280
	ds_read_b128 v[152:155], v166
	ds_read_b128 v[156:159], v166 offset:1024
	ds_read_b128 v[160:163], v166 offset:256
	ds_read_b128 v[176:179], v166 offset:1280
	v_lshl_add_u64 v[166:167], s[42:43], 0, v[132:133]
	s_add_i32 m0, s48, 0xc000
	ds_read_b128 v[180:183], v165
	ds_read_b128 v[184:187], v165 offset:1024
	ds_read_b128 v[188:191], v165 offset:2048
	ds_read_b128 v[192:195], v165 offset:3072
	ds_read_b128 v[196:199], v165 offset:4096
	ds_read_b128 v[200:203], v165 offset:5120
	ds_read_b128 v[204:207], v165 offset:6144
	ds_read_b128 v[208:211], v165 offset:7168
	global_load_lds_dwordx4 v[166:167], off
	v_lshl_add_u64 v[166:167], s[42:43], 0, v[134:135]
	s_add_i32 m0, s48, 0xe000
	s_nop 0
	global_load_lds_dwordx4 v[166:167], off
	s_cmp_lg_u32 s101, 0
	s_cbranch_scc1 .Lskw_5_1
	s_waitcnt vmcnt(8)
.Lskw_5_1:
	s_waitcnt lgkmcnt(0)
	s_barrier
	s_setprio 1
	s_waitcnt lgkmcnt(0)
	v_mfma_f32_16x16x32_bf16 v[126:129], v[136:139], v[180:183], v[126:129]
	v_mfma_f32_16x16x32_bf16 v[122:125], v[144:147], v[180:183], v[122:125]
	v_mfma_f32_16x16x32_bf16 v[110:113], v[136:139], v[188:191], v[110:113]
	v_mfma_f32_16x16x32_bf16 v[106:109], v[144:147], v[188:191], v[106:109]
	v_mfma_f32_16x16x32_bf16 v[94:97], v[136:139], v[196:199], v[94:97]
	v_mfma_f32_16x16x32_bf16 v[90:93], v[144:147], v[196:199], v[90:93]
	v_mfma_f32_16x16x32_bf16 v[78:81], v[136:139], v[204:207], v[78:81]
	v_mfma_f32_16x16x32_bf16 v[74:77], v[144:147], v[204:207], v[74:77]
	v_mfma_f32_16x16x32_bf16 v[126:129], v[140:143], v[184:187], v[126:129]
	v_mfma_f32_16x16x32_bf16 v[122:125], v[148:151], v[184:187], v[122:125]
	v_mfma_f32_16x16x32_bf16 v[110:113], v[140:143], v[192:195], v[110:113]
	v_mfma_f32_16x16x32_bf16 v[106:109], v[148:151], v[192:195], v[106:109]
	v_mfma_f32_16x16x32_bf16 v[94:97], v[140:143], v[200:203], v[94:97]
	v_mfma_f32_16x16x32_bf16 v[90:93], v[148:151], v[200:203], v[90:93]
	v_mfma_f32_16x16x32_bf16 v[78:81], v[140:143], v[208:211], v[78:81]
	v_mfma_f32_16x16x32_bf16 v[74:77], v[148:151], v[208:211], v[74:77]
	s_setprio 0
	s_setprio 1
	v_mfma_f32_16x16x32_bf16 v[118:121], v[152:155], v[180:183], v[118:121]
	v_mfma_f32_16x16x32_bf16 v[114:117], v[160:163], v[180:183], v[114:117]
	v_mfma_f32_16x16x32_bf16 v[102:105], v[152:155], v[188:191], v[102:105]
	v_mfma_f32_16x16x32_bf16 v[98:101], v[160:163], v[188:191], v[98:101]
	v_mfma_f32_16x16x32_bf16 v[86:89], v[152:155], v[196:199], v[86:89]
	v_mfma_f32_16x16x32_bf16 v[82:85], v[160:163], v[196:199], v[82:85]
	v_mfma_f32_16x16x32_bf16 v[70:73], v[152:155], v[204:207], v[70:73]
	v_mfma_f32_16x16x32_bf16 v[66:69], v[160:163], v[204:207], v[66:69]
	v_mfma_f32_16x16x32_bf16 v[118:121], v[156:159], v[184:187], v[118:121]
	v_mfma_f32_16x16x32_bf16 v[114:117], v[176:179], v[184:187], v[114:117]
	v_mfma_f32_16x16x32_bf16 v[102:105], v[156:159], v[192:195], v[102:105]
	v_mfma_f32_16x16x32_bf16 v[98:101], v[176:179], v[192:195], v[98:101]
	v_mfma_f32_16x16x32_bf16 v[86:89], v[156:159], v[200:203], v[86:89]
	v_mfma_f32_16x16x32_bf16 v[82:85], v[176:179], v[200:203], v[82:85]
	v_mfma_f32_16x16x32_bf16 v[70:73], v[156:159], v[208:211], v[70:73]
	v_mfma_f32_16x16x32_bf16 v[66:69], v[176:179], v[208:211], v[66:69]
	s_setprio 0
	s_barrier
	s_add_i32 s42, s61, s13
	v_lshl_add_u64 v[166:167], s[10:11], 0, v[0:1]
	s_mov_b32 m0, s42
	ds_read_b128 v[180:183], v165 offset:16384
	ds_read_b128 v[184:187], v165 offset:17408
	ds_read_b128 v[188:191], v165 offset:18432
	ds_read_b128 v[192:195], v165 offset:19456
	ds_read_b128 v[196:199], v165 offset:20480
	ds_read_b128 v[200:203], v165 offset:21504
	ds_read_b128 v[204:207], v165 offset:22528
	ds_read_b128 v[208:211], v165 offset:23552
	global_load_lds_dwordx4 v[166:167], off
	s_add_i32 m0, s42, 0x2000
	s_add_u32 s42, s10, 0xb0000
	v_lshl_add_u64 v[172:173], s[10:11], 0, v[130:131]
	s_addc_u32 s43, s11, 0
	s_add_i32 s61, s62, s13
	global_load_lds_dwordx4 v[172:173], off
	v_lshl_add_u64 v[212:213], s[42:43], 0, v[0:1]
	s_mov_b32 m0, s61
	v_lshl_add_u64 v[214:215], s[46:47], 0, v[130:131]
	global_load_lds_dwordx4 v[212:213], off
	v_lshl_add_u64 v[212:213], s[42:43], 0, v[130:131]
	s_add_i32 m0, s61, 0x2000
	s_nop 0
	global_load_lds_dwordx4 v[212:213], off
	v_lshl_add_u64 v[212:213], s[46:47], 0, v[0:1]
	s_mov_b32 m0, s48
	s_nop 0
	global_load_lds_dwordx4 v[212:213], off
	s_mov_b32 m0, s49
	s_nop 0
	global_load_lds_dwordx4 v[214:215], off
	s_cmp_lg_u32 s101, 0
	s_cbranch_scc1 .Lskw_5_2
	s_waitcnt vmcnt(8)
; #define PG8_STAGE(bufoff, gbase, voff) do { _Pragma("unroll") for (int _i = 0; _i < 2; ++_i) \
;         __builtin_amdgcn_global_load_lds((const unsigned*)((const char*)(gbase) + (voff)[_i]), (LAS unsigned*)(lds + (bufoff) + ldsw + _i * 8192), 16, 0, 0); } while (0)
; #define PG8_LDA(dst, b, h) do { _Pragma("unroll") for (int m = 0; m < 4; ++m) _Pragma("unroll") for (int k = 0; k < 2; ++k) dst[m][k] = *(const LAS bf16x8*)(lds + PG8_SA(b, h) + aoff + m * 2048 + k * 1024); } while (0)
; #define PG8_LDB(dst, b, h) do { _Pragma("unroll") for (int n = 0; n < 2; ++n) _Pragma("unroll") for (int k = 0; k < 2; ++k) dst[n][k] = *(const LAS bf16x8*)(lds + PG8_SB(b, h) + boff + n * 2048 + k * 1024); } while (0)
; #define PG8_MMA(ai, bj, At, Bt) do { __builtin_amdgcn_s_setprio(1); _Pragma("unroll") for (int m = 0; m < 4; ++m) _Pragma("unroll") for (int n = 0; n < 2; ++n) _Pragma("unroll") for (int k = 0; k < 2; ++k) \
;         acc[ai][bj][m][n] = __builtin_amdgcn_mfma_f32_16x16x32_bf16(Bt[n][k], At[m][k], acc[ai][bj][m][n], 0, 0, 0); __builtin_amdgcn_s_setprio(0); } while (0)
; #define PG8_WAIT_V(n) asm volatile("s_waitcnt vmcnt(" #n ")" ::: "memory")
; #define PG8_WAIT_L(n) asm volatile("s_waitcnt lgkmcnt(" #n ")" ::: "memory")
; #define PG8_BAR __builtin_amdgcn_s_barrier()
; #define PG8_SCHED __builtin_amdgcn_sched_barrier(0)
; template <class Epi, class Sched, int NSEG, int KK, int LDA, int LDB>
; __device__ __forceinline__ void gemm_phase(LAS unsigned char* lds, const Gemm g, const Sched& S, const Epi& E) {
;     ...
;             PG8_WAIT_V(8); PG8_WAIT_L(0); PG8_BAR; PG8_MMA(1, 0, At, B0); PG8_MMA(1, 1, At, B1); PG8_BAR; PG8_SCHED;
;             PG8_LDB(B0, 1, 0); PG8_LDB(B1, 1, 1); PG8_SCHED; PG8_LDA(At, 1, 0); PG8_STAGE(PG8_SA(0, 1), a2 + hstepA, voffA);
;             PG8_WAIT_V(8); PG8_WAIT_L(0); PG8_BAR; PG8_MMA(0, 0, At, B0); PG8_MMA(0, 1, At, B1); PG8_BAR; PG8_SCHED;
.Lskw_5_2:
	s_mov_b32 s101, 0
	s_waitcnt lgkmcnt(0)
	s_barrier
	s_setprio 1
	s_waitcnt lgkmcnt(0)
	v_mfma_f32_16x16x32_bf16 v[62:65], v[136:139], v[180:183], v[62:65]
	v_mfma_f32_16x16x32_bf16 v[58:61], v[144:147], v[180:183], v[58:61]
	v_mfma_f32_16x16x32_bf16 v[46:49], v[136:139], v[188:191], v[46:49]
	v_mfma_f32_16x16x32_bf16 v[42:45], v[144:147], v[188:191], v[42:45]
	v_mfma_f32_16x16x32_bf16 v[30:33], v[136:139], v[196:199], v[30:33]
	v_mfma_f32_16x16x32_bf16 v[26:29], v[144:147], v[196:199], v[26:29]
	v_mfma_f32_16x16x32_bf16 v[14:17], v[136:139], v[204:207], v[14:17]
	v_mfma_f32_16x16x32_bf16 v[10:13], v[144:147], v[204:207], v[10:13]
	v_mfma_f32_16x16x32_bf16 v[62:65], v[140:143], v[184:187], v[62:65]
	v_mfma_f32_16x16x32_bf16 v[58:61], v[148:151], v[184:187], v[58:61]
	v_mfma_f32_16x16x32_bf16 v[46:49], v[140:143], v[192:195], v[46:49]
	v_mfma_f32_16x16x32_bf16 v[42:45], v[148:151], v[192:195], v[42:45]
	v_mfma_f32_16x16x32_bf16 v[30:33], v[140:143], v[200:203], v[30:33]
	v_mfma_f32_16x16x32_bf16 v[26:29], v[148:151], v[200:203], v[26:29]
	v_mfma_f32_16x16x32_bf16 v[14:17], v[140:143], v[208:211], v[14:17]
	v_mfma_f32_16x16x32_bf16 v[10:13], v[148:151], v[208:211], v[10:13]
	s_setprio 0
	s_setprio 1
	v_mfma_f32_16x16x32_bf16 v[54:57], v[152:155], v[180:183], v[54:57]
	v_mfma_f32_16x16x32_bf16 v[50:53], v[160:163], v[180:183], v[50:53]
	v_mfma_f32_16x16x32_bf16 v[38:41], v[152:155], v[188:191], v[38:41]
	v_mfma_f32_16x16x32_bf16 v[34:37], v[160:163], v[188:191], v[34:37]
	v_mfma_f32_16x16x32_bf16 v[22:25], v[152:155], v[196:199], v[22:25]
	v_mfma_f32_16x16x32_bf16 v[18:21], v[160:163], v[196:199], v[18:21]
	v_mfma_f32_16x16x32_bf16 v[6:9], v[152:155], v[204:207], v[6:9]
	v_mfma_f32_16x16x32_bf16 v[2:5], v[160:163], v[204:207], v[2:5]
	v_mfma_f32_16x16x32_bf16 v[54:57], v[156:159], v[184:187], v[54:57]
	v_mfma_f32_16x16x32_bf16 v[50:53], v[176:179], v[184:187], v[50:53]
	v_mfma_f32_16x16x32_bf16 v[38:41], v[156:159], v[192:195], v[38:41]
	v_mfma_f32_16x16x32_bf16 v[34:37], v[176:179], v[192:195], v[34:37]
	v_mfma_f32_16x16x32_bf16 v[22:25], v[156:159], v[200:203], v[22:25]
	v_mfma_f32_16x16x32_bf16 v[18:21], v[176:179], v[200:203], v[18:21]
	v_mfma_f32_16x16x32_bf16 v[6:9], v[156:159], v[208:211], v[6:9]
	v_mfma_f32_16x16x32_bf16 v[2:5], v[176:179], v[208:211], v[2:5]
	s_setprio 0
	s_barrier
	s_add_i32 s61, 0, 0x18000
	s_add_i32 s62, 0, 0x1c000
	v_add_u32_e32 v148, s61, v164
	v_add_u32_e32 v176, s62, v164
	ds_read_b128 v[136:139], v148
	ds_read_b128 v[140:143], v148 offset:1024
	ds_read_b128 v[144:147], v148 offset:256
	ds_read_b128 v[148:151], v148 offset:1280
	ds_read_b128 v[152:155], v176
	ds_read_b128 v[156:159], v176 offset:1024
	ds_read_b128 v[160:163], v176 offset:256
	ds_read_b128 v[176:179], v176 offset:1280
	s_add_u32 s42, s46, 0xb0000
	s_addc_u32 s43, s47, 0
	s_mov_b32 m0, s50
	v_lshl_add_u64 v[216:217], s[42:43], 0, v[0:1]
	ds_read_b128 v[180:183], v165 offset:32768
	ds_read_b128 v[184:187], v165 offset:33792
	ds_read_b128 v[188:191], v165 offset:34816
	ds_read_b128 v[192:195], v165 offset:35840
	ds_read_b128 v[196:199], v165 offset:36864
	ds_read_b128 v[200:203], v165 offset:37888
	ds_read_b128 v[204:207], v165 offset:38912
	ds_read_b128 v[208:211], v165 offset:39936
	global_load_lds_dwordx4 v[216:217], off
	v_lshl_add_u64 v[216:217], s[42:43], 0, v[130:131]
	s_mov_b32 m0, s51
	s_nop 0
	global_load_lds_dwordx4 v[216:217], off
	s_waitcnt vmcnt(8)
	s_waitcnt lgkmcnt(0)
	s_barrier
	s_setprio 1
	s_waitcnt lgkmcnt(0)
	v_mfma_f32_16x16x32_bf16 v[126:129], v[136:139], v[180:183], v[126:129]
	v_mfma_f32_16x16x32_bf16 v[122:125], v[144:147], v[180:183], v[122:125]
	v_mfma_f32_16x16x32_bf16 v[110:113], v[136:139], v[188:191], v[110:113]
	v_mfma_f32_16x16x32_bf16 v[106:109], v[144:147], v[188:191], v[106:109]
	v_mfma_f32_16x16x32_bf16 v[94:97], v[136:139], v[196:199], v[94:97]
	v_mfma_f32_16x16x32_bf16 v[90:93], v[144:147], v[196:199], v[90:93]
	v_mfma_f32_16x16x32_bf16 v[78:81], v[136:139], v[204:207], v[78:81]
	v_mfma_f32_16x16x32_bf16 v[74:77], v[144:147], v[204:207], v[74:77]
	v_mfma_f32_16x16x32_bf16 v[126:129], v[140:143], v[184:187], v[126:129]
	v_mfma_f32_16x16x32_bf16 v[122:125], v[148:151], v[184:187], v[122:125]
	v_mfma_f32_16x16x32_bf16 v[110:113], v[140:143], v[192:195], v[110:113]
	v_mfma_f32_16x16x32_bf16 v[106:109], v[148:151], v[192:195], v[106:109]
	v_mfma_f32_16x16x32_bf16 v[94:97], v[140:143], v[200:203], v[94:97]
	v_mfma_f32_16x16x32_bf16 v[90:93], v[148:151], v[200:203], v[90:93]
	v_mfma_f32_16x16x32_bf16 v[78:81], v[140:143], v[208:211], v[78:81]
	v_mfma_f32_16x16x32_bf16 v[74:77], v[148:151], v[208:211], v[74:77]
	s_setprio 0
	s_setprio 1
	v_mfma_f32_16x16x32_bf16 v[118:121], v[152:155], v[180:183], v[118:121]
	v_mfma_f32_16x16x32_bf16 v[114:117], v[160:163], v[180:183], v[114:117]
	v_mfma_f32_16x16x32_bf16 v[102:105], v[152:155], v[188:191], v[102:105]
	v_mfma_f32_16x16x32_bf16 v[98:101], v[160:163], v[188:191], v[98:101]
	v_mfma_f32_16x16x32_bf16 v[86:89], v[152:155], v[196:199], v[86:89]
	v_mfma_f32_16x16x32_bf16 v[82:85], v[160:163], v[196:199], v[82:85]
	v_mfma_f32_16x16x32_bf16 v[70:73], v[152:155], v[204:207], v[70:73]
	v_mfma_f32_16x16x32_bf16 v[66:69], v[160:163], v[204:207], v[66:69]
	v_mfma_f32_16x16x32_bf16 v[118:121], v[156:159], v[184:187], v[118:121]
	v_mfma_f32_16x16x32_bf16 v[114:117], v[176:179], v[184:187], v[114:117]
	v_mfma_f32_16x16x32_bf16 v[102:105], v[156:159], v[192:195], v[102:105]
	v_mfma_f32_16x16x32_bf16 v[98:101], v[176:179], v[192:195], v[98:101]
	v_mfma_f32_16x16x32_bf16 v[86:89], v[156:159], v[200:203], v[86:89]
	v_mfma_f32_16x16x32_bf16 v[82:85], v[176:179], v[200:203], v[82:85]
	v_mfma_f32_16x16x32_bf16 v[70:73], v[156:159], v[208:211], v[70:73]
	v_mfma_f32_16x16x32_bf16 v[66:69], v[176:179], v[208:211], v[66:69]
	s_setprio 0
	s_barrier
; #define PG8_STAGE(bufoff, gbase, voff) do { _Pragma("unroll") for (int _i = 0; _i < 2; ++_i) \
;         __builtin_amdgcn_global_load_lds((const unsigned*)((const char*)(gbase) + (voff)[_i]), (LAS unsigned*)(lds + (bufoff) + ldsw + _i * 8192), 16, 0, 0); } while (0)
; #define PG8_LDA(dst, b, h) do { _Pragma("unroll") for (int m = 0; m < 4; ++m) _Pragma("unroll") for (int k = 0; k < 2; ++k) dst[m][k] = *(const LAS bf16x8*)(lds + PG8_SA(b, h) + aoff + m * 2048 + k * 1024); } while (0)
; #define PG8_MMA(ai, bj, At, Bt) do { __builtin_amdgcn_s_setprio(1); _Pragma("unroll") for (int m = 0; m < 4; ++m) _Pragma("unroll") for (int n = 0; n < 2; ++n) _Pragma("unroll") for (int k = 0; k < 2; ++k) \
;         acc[ai][bj][m][n] = __builtin_amdgcn_mfma_f32_16x16x32_bf16(Bt[n][k], At[m][k], acc[ai][bj][m][n], 0, 0, 0); __builtin_amdgcn_s_setprio(0); } while (0)
; #define PG8_WAIT_V(n) asm volatile("s_waitcnt vmcnt(" #n ")" ::: "memory")
; #define PG8_WAIT_L(n) asm volatile("s_waitcnt lgkmcnt(" #n ")" ::: "memory")
; #define PG8_BAR __builtin_amdgcn_s_barrier()
; #define PG8_SCHED __builtin_amdgcn_sched_barrier(0)
; template <class Epi, class Sched, int NSEG, int KK, int LDA, int LDB>
; __device__ __forceinline__ void gemm_phase(LAS unsigned char* lds, const Gemm g, const Sched& S, const Epi& E) {
;     ...
;             PG8_LDA(At, 1, 1); PG8_STAGE(PG8_SB(1, 0), b3, voffB); PG8_STAGE(PG8_SB(1, 1), b3 + hstepB, voffB); PG8_STAGE(PG8_SA(1, 0), a3, voffA);
;             PG8_WAIT_V(8); PG8_WAIT_L(0); PG8_BAR; PG8_MMA(1, 0, At, B0); PG8_MMA(1, 1, At, B1); PG8_BAR; PG8_SCHED;
;         }
;         if (wr == 0) PG8_BAR;
	s_add_i32 s42, s61, s13
	v_lshl_add_u64 v[166:167], v[166:167], 0, s[28:29]
	s_mov_b32 m0, s42
	ds_read_b128 v[180:183], v165 offset:49152
	ds_read_b128 v[184:187], v165 offset:50176
	ds_read_b128 v[188:191], v165 offset:51200
	ds_read_b128 v[192:195], v165 offset:52224
	ds_read_b128 v[196:199], v165 offset:53248
	ds_read_b128 v[200:203], v165 offset:54272
	ds_read_b128 v[204:207], v165 offset:55296
	ds_read_b128 v[208:211], v165 offset:56320
	global_load_lds_dwordx4 v[166:167], off
	s_add_i32 m0, s42, 0x2000
	s_add_u32 s10, s10, 0xb0080
	v_lshl_add_u64 v[166:167], v[172:173], 0, s[28:29]
	s_addc_u32 s11, s11, 0
	s_add_i32 s42, s62, s13
	global_load_lds_dwordx4 v[166:167], off
	v_lshl_add_u64 v[166:167], s[10:11], 0, v[0:1]
	s_mov_b32 m0, s42
	s_nop 0
	global_load_lds_dwordx4 v[166:167], off
	v_lshl_add_u64 v[166:167], s[10:11], 0, v[130:131]
	s_add_i32 m0, s42, 0x2000
	s_nop 0
	global_load_lds_dwordx4 v[166:167], off
	v_lshl_add_u64 v[166:167], v[212:213], 0, s[28:29]
	s_mov_b32 m0, s53
	s_nop 0
	global_load_lds_dwordx4 v[166:167], off
	v_lshl_add_u64 v[166:167], v[214:215], 0, s[28:29]
	s_mov_b32 m0, s54
	s_nop 0
	global_load_lds_dwordx4 v[166:167], off
	s_waitcnt vmcnt(8)
	s_waitcnt lgkmcnt(0)
	s_barrier
	s_setprio 1
	s_waitcnt lgkmcnt(0)
	v_mfma_f32_16x16x32_bf16 v[62:65], v[136:139], v[180:183], v[62:65]
	v_mfma_f32_16x16x32_bf16 v[58:61], v[144:147], v[180:183], v[58:61]
	v_mfma_f32_16x16x32_bf16 v[46:49], v[136:139], v[188:191], v[46:49]
	v_mfma_f32_16x16x32_bf16 v[42:45], v[144:147], v[188:191], v[42:45]
	v_mfma_f32_16x16x32_bf16 v[30:33], v[136:139], v[196:199], v[30:33]
	v_mfma_f32_16x16x32_bf16 v[26:29], v[144:147], v[196:199], v[26:29]
	v_mfma_f32_16x16x32_bf16 v[14:17], v[136:139], v[204:207], v[14:17]
	v_mfma_f32_16x16x32_bf16 v[10:13], v[144:147], v[204:207], v[10:13]
	v_mfma_f32_16x16x32_bf16 v[62:65], v[140:143], v[184:187], v[62:65]
	v_mfma_f32_16x16x32_bf16 v[58:61], v[148:151], v[184:187], v[58:61]
	v_mfma_f32_16x16x32_bf16 v[46:49], v[140:143], v[192:195], v[46:49]
	v_mfma_f32_16x16x32_bf16 v[42:45], v[148:151], v[192:195], v[42:45]
	v_mfma_f32_16x16x32_bf16 v[30:33], v[140:143], v[200:203], v[30:33]
	v_mfma_f32_16x16x32_bf16 v[26:29], v[148:151], v[200:203], v[26:29]
	v_mfma_f32_16x16x32_bf16 v[14:17], v[140:143], v[208:211], v[14:17]
	v_mfma_f32_16x16x32_bf16 v[10:13], v[148:151], v[208:211], v[10:13]
	s_setprio 0
	s_setprio 1
	v_mfma_f32_16x16x32_bf16 v[54:57], v[152:155], v[180:183], v[54:57]
	v_mfma_f32_16x16x32_bf16 v[50:53], v[160:163], v[180:183], v[50:53]
	v_mfma_f32_16x16x32_bf16 v[38:41], v[152:155], v[188:191], v[38:41]
	v_mfma_f32_16x16x32_bf16 v[34:37], v[160:163], v[188:191], v[34:37]
	v_mfma_f32_16x16x32_bf16 v[22:25], v[152:155], v[196:199], v[22:25]
	v_mfma_f32_16x16x32_bf16 v[18:21], v[160:163], v[196:199], v[18:21]
	v_mfma_f32_16x16x32_bf16 v[6:9], v[152:155], v[204:207], v[6:9]
	v_mfma_f32_16x16x32_bf16 v[2:5], v[160:163], v[204:207], v[2:5]
	v_mfma_f32_16x16x32_bf16 v[54:57], v[156:159], v[184:187], v[54:57]
	v_mfma_f32_16x16x32_bf16 v[50:53], v[176:179], v[184:187], v[50:53]
	v_mfma_f32_16x16x32_bf16 v[38:41], v[156:159], v[192:195], v[38:41]
	v_mfma_f32_16x16x32_bf16 v[34:37], v[176:179], v[192:195], v[34:37]
	v_mfma_f32_16x16x32_bf16 v[22:25], v[156:159], v[200:203], v[22:25]
	v_mfma_f32_16x16x32_bf16 v[18:21], v[176:179], v[200:203], v[18:21]
	v_mfma_f32_16x16x32_bf16 v[6:9], v[156:159], v[208:211], v[6:9]
	v_mfma_f32_16x16x32_bf16 v[2:5], v[176:179], v[208:211], v[2:5]
	s_setprio 0
	s_barrier
	s_add_i32 s60, s60, 2
	s_add_u32 s58, s58, 0x100
	s_addc_u32 s59, s59, 0
	s_cmp_gt_u32 s60, 41
	s_mov_b64 s[42:43], s[40:41]
	s_cbranch_scc0 .LBB0_1258
	s_mov_b32 s101, 1
	s_and_b64 vcc, exec, s[8:9]
	s_cbranch_vccz .LBB0_1261
	s_barrier

; __global__ void __launch_bounds__(NTHREADS, 2) mega_fwd(Args args) {
;     extern __shared__ __attribute__((aligned(16))) unsigned char lds_raw[];
	.amdhsa_kernel _Z8mega_fwd4Args
		.amdhsa_group_segment_fixed_size 0
		.amdhsa_private_segment_fixed_size 0
		.amdhsa_kernarg_size 408
		.amdhsa_user_sgpr_count 2
		.amdhsa_user_sgpr_dispatch_ptr 0
		.amdhsa_user_sgpr_queue_ptr 0
		.amdhsa_user_sgpr_kernarg_segment_ptr 1
		.amdhsa_user_sgpr_dispatch_id 0
		.amdhsa_user_sgpr_kernarg_preload_length 0
		.amdhsa_user_sgpr_kernarg_preload_offset 0
		.amdhsa_user_sgpr_private_segment_size 0
		.amdhsa_uses_dynamic_stack 0
		.amdhsa_enable_private_segment 0
		.amdhsa_system_sgpr_workgroup_id_x 1
		.amdhsa_system_sgpr_workgroup_id_y 0
		.amdhsa_system_sgpr_workgroup_id_z 0
		.amdhsa_system_sgpr_workgroup_info 0
		.amdhsa_system_vgpr_workitem_id 2
		.amdhsa_next_free_vgpr 256
		.amdhsa_next_free_sgpr 102
		.amdhsa_accum_offset 256
		.amdhsa_reserve_vcc 1
		.amdhsa_float_round_mode_32 0
		.amdhsa_float_round_mode_16_64 0
		.amdhsa_float_denorm_mode_32 3
		.amdhsa_float_denorm_mode_16_64 3
		.amdhsa_dx10_clamp 1
		.amdhsa_ieee_mode 1
		.amdhsa_fp16_overflow 0
		.amdhsa_tg_split 0
		.amdhsa_exception_fp_ieee_invalid_op 0
		.amdhsa_exception_fp_denorm_src 0
		.amdhsa_exception_fp_ieee_div_zero 0
		.amdhsa_exception_fp_ieee_overflow 0
		.amdhsa_exception_fp_ieee_underflow 0
		.amdhsa_exception_fp_ieee_inexact 0
		.amdhsa_exception_int_div_zero 0
	.end_amdhsa_kernel

; __global__ void __launch_bounds__(NTHREADS, 2) mega_fwd(Args args) {
amdhsa.kernels:
  - .agpr_count:     0
    .args:
      - .offset:         0
        .size:           152
        .value_kind:     by_value
      - .offset:         152
        .size:           4
        .value_kind:     hidden_block_count_x
      - .offset:         156
        .size:           4
        .value_kind:     hidden_block_count_y
      - .offset:         160
        .size:           4
        .value_kind:     hidden_block_count_z
      - .offset:         164
        .size:           2
        .value_kind:     hidden_group_size_x
      - .offset:         166
        .size:           2
        .value_kind:     hidden_group_size_y
      - .offset:         168
        .size:           2
        .value_kind:     hidden_group_size_z
      - .offset:         170
        .size:           2
        .value_kind:     hidden_remainder_x
      - .offset:         172
        .size:           2
        .value_kind:     hidden_remainder_y
      - .offset:         174
        .size:           2
        .value_kind:     hidden_remainder_z
      - .offset:         192
        .size:           8
        .value_kind:     hidden_global_offset_x
      - .offset:         200
        .size:           8
        .value_kind:     hidden_global_offset_y
      - .offset:         208
        .size:           8
        .value_kind:     hidden_global_offset_z
      - .offset:         216
        .size:           2
        .value_kind:     hidden_grid_dims
      - .offset:         240
        .size:           8
        .value_kind:     hidden_multigrid_sync_arg
      - .offset:         272
        .size:           4
        .value_kind:     hidden_dynamic_lds_size
    .group_segment_fixed_size: 0
    .kernarg_segment_align: 8
    .kernarg_segment_size: 408
    .language:       OpenCL C
    .language_version:
      - 2
      - 0
    .max_flat_workgroup_size: 512
    .name:           _Z8mega_fwd4Args
    .private_segment_fixed_size: 0
    .sgpr_count:     108
    .sgpr_spill_count: 156
    .symbol:         _Z8mega_fwd4Args.kd
    .uniform_work_group_size: 1
    .uses_dynamic_stack: false
    .vgpr_count:     256
    .vgpr_spill_count: 0
    .wavefront_size: 64
